# GEMM K-loops: LDS-DMA addresses as SGPR base + 32-bit VGPR offset (16 v_lshl_add_u64 per iteration removed, 2 SALU snapshots added); diff loop DMA pieces without m0 save/restore
# baseline (speedup 1.0000x reference)
; #define PG8_STAGE(bufoff, gbase, voff) do { _Pragma("unroll") for (int _i = 0; _i < 2; ++_i) \
;         __builtin_amdgcn_global_load_lds((const unsigned*)((const char*)(gbase) + (voff)[_i]), (PG8_LAS unsigned*)(lds + (bufoff) + ldsw + _i * 8192), 16, 0, 0); } while (0)
; #define PG8_LDA(dst, b, h) do { _Pragma("unroll") for (int m = 0; m < 4; ++m) _Pragma("unroll") for (int k = 0; k < 2; ++k) dst[m][k] = *(const PG8_LAS bf16x8*)(lds + PG8_SA(b, h) + aoff + m * 2048 + k * 1024); } while (0)
; #define PG8_LDB(dst, b, h) do { _Pragma("unroll") for (int n = 0; n < 2; ++n) _Pragma("unroll") for (int k = 0; k < 2; ++k) dst[n][k] = *(const PG8_LAS bf16x8*)(lds + PG8_SB(b, h) + boff + n * 2048 + k * 1024); } while (0)
; #define PG8_MMA(ai, bj, At, Bt) do { __builtin_amdgcn_s_setprio(1); _Pragma("unroll") for (int m = 0; m < 4; ++m) _Pragma("unroll") for (int n = 0; n < 2; ++n) _Pragma("unroll") for (int k = 0; k < 2; ++k) \
;         acc[ai][bj][m][n] = __builtin_amdgcn_mfma_f32_16x16x32_bf16(Bt[n][k], At[m][k], acc[ai][bj][m][n], 0, 0, 0); __builtin_amdgcn_s_setprio(0); } while (0)
; #define PG8_WAIT_V(n) asm volatile("s_waitcnt vmcnt(" #n ")" ::: "memory")
; #define PG8_WAIT_L(n) asm volatile("s_waitcnt lgkmcnt(" #n ")" ::: "memory")
; #define PG8_BAR __builtin_amdgcn_s_barrier()
; #define PG8_SCHED __builtin_amdgcn_sched_barrier(0)
; template <class Epi, class Sched, bool ALIGN_EPI = false, bool SP2 = false>
; __device__ __forceinline__ void gemm_phase(PG8_LAS unsigned char* lds, const Gemm g, const Sched& S, const Epi& E) {
;     ...
;             PG8_LDB(B0, 0, 0); PG8_LDB(B1, 0, 1); PG8_SCHED; PG8_LDA(At, 0, 0); PG8_STAGE(PG8_SA(1, 1), a1 + hstep, voffA);
;             PG8_WAIT_V(8); PG8_WAIT_L(0); PG8_BAR; PG8_MMA(0, 0, At, B0); PG8_MMA(0, 1, At, B1); PG8_BAR; PG8_SCHED;
;             PG8_LDA(At, 0, 1); PG8_STAGE(PG8_SB(0, 0), b2, voffB); PG8_STAGE(PG8_SB(0, 1), b2 + hstep, voffB); PG8_STAGE(PG8_SA(0, 0), a2, voffA);
;             PG8_WAIT_V(8); PG8_WAIT_L(0); PG8_BAR; PG8_MMA(1, 0, At, B0); PG8_MMA(1, 1, At, B1); PG8_BAR; PG8_SCHED;
.LBB0_163:
	ds_read_b128 v[128:131], v188
	ds_read_b128 v[132:135], v189
	ds_read_b128 v[136:139], v190
	ds_read_b128 v[140:143], v191
	ds_read_b128 v[144:147], v192
	ds_read_b128 v[148:151], v193
	ds_read_b128 v[172:175], v194
	ds_read_b128 v[176:179], v195
	s_add_u32 s44, s42, 0xfffc0080
	s_addc_u32 s45, s43, -1
	s_cmp_eq_u32 s74, 12
	s_cselect_b32 s47, s9, s45
	s_cselect_b32 s46, s11, s44
	s_cselect_b32 s45, s29, s73
	s_cselect_b32 s44, s31, s72
	s_mov_b32 m0, s68
	ds_read_b128 v[180:183], v186
	ds_read_b128 v[208:211], v186 offset:1024
	ds_read_b128 v[212:215], v186 offset:2048
	ds_read_b128 v[216:219], v186 offset:3072
	ds_read_b128 v[220:223], v186 offset:4096
	ds_read_b128 v[224:227], v186 offset:5120
	ds_read_b128 v[228:231], v186 offset:6144
	ds_read_b128 v[232:235], v186 offset:7168
	global_load_lds_dwordx4 v166, s[42:43]
	s_mov_b32 m0, s69
	s_nop 0
	global_load_lds_dwordx4 v164, s[42:43]
	s_waitcnt vmcnt(8)
	s_waitcnt lgkmcnt(0)
	s_barrier
	s_setprio 1
	s_waitcnt lgkmcnt(0)
	v_mfma_f32_16x16x32_bf16 v[124:127], v[128:131], v[180:183], v[124:127]
	v_mfma_f32_16x16x32_bf16 v[120:123], v[136:139], v[180:183], v[120:123]
	v_mfma_f32_16x16x32_bf16 v[108:111], v[128:131], v[212:215], v[108:111]
	v_mfma_f32_16x16x32_bf16 v[104:107], v[136:139], v[212:215], v[104:107]
	v_mfma_f32_16x16x32_bf16 v[92:95], v[128:131], v[220:223], v[92:95]
	v_mfma_f32_16x16x32_bf16 v[88:91], v[136:139], v[220:223], v[88:91]
	v_mfma_f32_16x16x32_bf16 v[76:79], v[128:131], v[228:231], v[76:79]
	v_mfma_f32_16x16x32_bf16 v[72:75], v[136:139], v[228:231], v[72:75]
	v_mfma_f32_16x16x32_bf16 v[124:127], v[132:135], v[208:211], v[124:127]
	v_mfma_f32_16x16x32_bf16 v[120:123], v[140:143], v[208:211], v[120:123]
	v_mfma_f32_16x16x32_bf16 v[108:111], v[132:135], v[216:219], v[108:111]
	v_mfma_f32_16x16x32_bf16 v[104:107], v[140:143], v[216:219], v[104:107]
	v_mfma_f32_16x16x32_bf16 v[92:95], v[132:135], v[224:227], v[92:95]
	v_mfma_f32_16x16x32_bf16 v[88:91], v[140:143], v[224:227], v[88:91]
	v_mfma_f32_16x16x32_bf16 v[76:79], v[132:135], v[232:235], v[76:79]
	v_mfma_f32_16x16x32_bf16 v[72:75], v[140:143], v[232:235], v[72:75]
	s_setprio 0
	s_setprio 1
	v_mfma_f32_16x16x32_bf16 v[116:119], v[144:147], v[180:183], v[116:119]
	v_mfma_f32_16x16x32_bf16 v[112:115], v[172:175], v[180:183], v[112:115]
	v_mfma_f32_16x16x32_bf16 v[100:103], v[144:147], v[212:215], v[100:103]
	v_mfma_f32_16x16x32_bf16 v[96:99], v[172:175], v[212:215], v[96:99]
	v_mfma_f32_16x16x32_bf16 v[84:87], v[144:147], v[220:223], v[84:87]
	v_mfma_f32_16x16x32_bf16 v[80:83], v[172:175], v[220:223], v[80:83]
	v_mfma_f32_16x16x32_bf16 v[68:71], v[144:147], v[228:231], v[68:71]
	v_mfma_f32_16x16x32_bf16 v[64:67], v[172:175], v[228:231], v[64:67]
	v_mfma_f32_16x16x32_bf16 v[116:119], v[148:151], v[208:211], v[116:119]
	v_mfma_f32_16x16x32_bf16 v[112:115], v[176:179], v[208:211], v[112:115]
	v_mfma_f32_16x16x32_bf16 v[100:103], v[148:151], v[216:219], v[100:103]
	v_mfma_f32_16x16x32_bf16 v[96:99], v[176:179], v[216:219], v[96:99]
	v_mfma_f32_16x16x32_bf16 v[84:87], v[148:151], v[224:227], v[84:87]
	v_mfma_f32_16x16x32_bf16 v[80:83], v[176:179], v[224:227], v[80:83]
	v_mfma_f32_16x16x32_bf16 v[68:71], v[148:151], v[232:235], v[68:71]
	v_mfma_f32_16x16x32_bf16 v[64:67], v[176:179], v[232:235], v[64:67]
	s_setprio 0
	s_barrier
	s_add_u32 s88, s44, 0x80
	s_addc_u32 s89, s45, 0
	s_add_u32 s90, s46, 0x80
	s_addc_u32 s91, s47, 0
	s_mov_b32 m0, s51
	s_add_u32 s76, s44, 0x40000
	ds_read_b128 v[180:183], v186 offset:16384
	ds_read_b128 v[208:211], v186 offset:17408
	ds_read_b128 v[212:215], v186 offset:18432
	ds_read_b128 v[216:219], v186 offset:19456
	ds_read_b128 v[220:223], v186 offset:20480
	ds_read_b128 v[224:227], v186 offset:21504
	ds_read_b128 v[228:231], v186 offset:22528
	ds_read_b128 v[232:235], v186 offset:23552
	global_load_lds_dwordx4 v154, s[44:45]
	s_mov_b32 m0, s52
	s_addc_u32 s77, s45, 0
	global_load_lds_dwordx4 v158, s[44:45]
	s_mov_b32 m0, s53
	s_nop 0
	global_load_lds_dwordx4 v154, s[76:77]
	s_mov_b32 m0, s54
	s_nop 0
	global_load_lds_dwordx4 v158, s[76:77]
	s_mov_b32 m0, s50
	s_nop 0
	global_load_lds_dwordx4 v152, s[46:47]
	s_mov_b32 m0, s55
	s_nop 0
	global_load_lds_dwordx4 v156, s[46:47]
	s_waitcnt vmcnt(8)
	s_waitcnt lgkmcnt(0)
	s_barrier
	s_setprio 1
	s_waitcnt lgkmcnt(0)
	v_mfma_f32_16x16x32_bf16 v[60:63], v[128:131], v[180:183], v[60:63]
	v_mfma_f32_16x16x32_bf16 v[56:59], v[136:139], v[180:183], v[56:59]
	v_mfma_f32_16x16x32_bf16 v[44:47], v[128:131], v[212:215], v[44:47]
	v_mfma_f32_16x16x32_bf16 v[40:43], v[136:139], v[212:215], v[40:43]
	v_mfma_f32_16x16x32_bf16 v[28:31], v[128:131], v[220:223], v[28:31]
	v_mfma_f32_16x16x32_bf16 v[24:27], v[136:139], v[220:223], v[24:27]
	v_mfma_f32_16x16x32_bf16 v[12:15], v[128:131], v[228:231], v[12:15]
	v_mfma_f32_16x16x32_bf16 v[8:11], v[136:139], v[228:231], v[8:11]
	v_mfma_f32_16x16x32_bf16 v[60:63], v[132:135], v[208:211], v[60:63]
	v_mfma_f32_16x16x32_bf16 v[56:59], v[140:143], v[208:211], v[56:59]
	v_mfma_f32_16x16x32_bf16 v[44:47], v[132:135], v[216:219], v[44:47]
	v_mfma_f32_16x16x32_bf16 v[40:43], v[140:143], v[216:219], v[40:43]
	v_mfma_f32_16x16x32_bf16 v[28:31], v[132:135], v[224:227], v[28:31]
	v_mfma_f32_16x16x32_bf16 v[24:27], v[140:143], v[224:227], v[24:27]
	v_mfma_f32_16x16x32_bf16 v[12:15], v[132:135], v[232:235], v[12:15]
	v_mfma_f32_16x16x32_bf16 v[8:11], v[140:143], v[232:235], v[8:11]
	s_setprio 0
	s_setprio 1
	v_mfma_f32_16x16x32_bf16 v[52:55], v[144:147], v[180:183], v[52:55]
	v_mfma_f32_16x16x32_bf16 v[48:51], v[172:175], v[180:183], v[48:51]
	v_mfma_f32_16x16x32_bf16 v[36:39], v[144:147], v[212:215], v[36:39]
	v_mfma_f32_16x16x32_bf16 v[32:35], v[172:175], v[212:215], v[32:35]
	v_mfma_f32_16x16x32_bf16 v[20:23], v[144:147], v[220:223], v[20:23]
	v_mfma_f32_16x16x32_bf16 v[16:19], v[172:175], v[220:223], v[16:19]
	v_mfma_f32_16x16x32_bf16 v[4:7], v[144:147], v[228:231], v[4:7]
	v_mfma_f32_16x16x32_bf16 v[0:3], v[172:175], v[228:231], v[0:3]
	v_mfma_f32_16x16x32_bf16 v[52:55], v[148:151], v[208:211], v[52:55]
	v_mfma_f32_16x16x32_bf16 v[48:51], v[176:179], v[208:211], v[48:51]
	v_mfma_f32_16x16x32_bf16 v[36:39], v[148:151], v[216:219], v[36:39]
	v_mfma_f32_16x16x32_bf16 v[32:35], v[176:179], v[216:219], v[32:35]
	v_mfma_f32_16x16x32_bf16 v[20:23], v[148:151], v[224:227], v[20:23]
	v_mfma_f32_16x16x32_bf16 v[16:19], v[176:179], v[224:227], v[16:19]
	v_mfma_f32_16x16x32_bf16 v[4:7], v[148:151], v[232:235], v[4:7]
	v_mfma_f32_16x16x32_bf16 v[0:3], v[176:179], v[232:235], v[0:3]
	s_setprio 0
	s_barrier
; #define PG8_STAGE(bufoff, gbase, voff) do { _Pragma("unroll") for (int _i = 0; _i < 2; ++_i) \
;         __builtin_amdgcn_global_load_lds((const unsigned*)((const char*)(gbase) + (voff)[_i]), (PG8_LAS unsigned*)(lds + (bufoff) + ldsw + _i * 8192), 16, 0, 0); } while (0)
; #define PG8_LDA(dst, b, h) do { _Pragma("unroll") for (int m = 0; m < 4; ++m) _Pragma("unroll") for (int k = 0; k < 2; ++k) dst[m][k] = *(const PG8_LAS bf16x8*)(lds + PG8_SA(b, h) + aoff + m * 2048 + k * 1024); } while (0)
; #define PG8_LDB(dst, b, h) do { _Pragma("unroll") for (int n = 0; n < 2; ++n) _Pragma("unroll") for (int k = 0; k < 2; ++k) dst[n][k] = *(const PG8_LAS bf16x8*)(lds + PG8_SB(b, h) + boff + n * 2048 + k * 1024); } while (0)
; #define PG8_MMA(ai, bj, At, Bt) do { __builtin_amdgcn_s_setprio(1); _Pragma("unroll") for (int m = 0; m < 4; ++m) _Pragma("unroll") for (int n = 0; n < 2; ++n) _Pragma("unroll") for (int k = 0; k < 2; ++k) \
;         acc[ai][bj][m][n] = __builtin_amdgcn_mfma_f32_16x16x32_bf16(Bt[n][k], At[m][k], acc[ai][bj][m][n], 0, 0, 0); __builtin_amdgcn_s_setprio(0); } while (0)
; #define PG8_WAIT_V(n) asm volatile("s_waitcnt vmcnt(" #n ")" ::: "memory")
; #define PG8_WAIT_L(n) asm volatile("s_waitcnt lgkmcnt(" #n ")" ::: "memory")
; #define PG8_BAR __builtin_amdgcn_s_barrier()
; #define PG8_SCHED __builtin_amdgcn_sched_barrier(0)
; template <class Epi, class Sched, bool ALIGN_EPI = false, bool SP2 = false>
; __device__ __forceinline__ void gemm_phase(PG8_LAS unsigned char* lds, const Gemm g, const Sched& S, const Epi& E) {
;     ...
;         for (int t = 0; t < nt; t += 2) {
;     ...
;             PG8_LDB(B0, 1, 0); PG8_LDB(B1, 1, 1); PG8_SCHED; PG8_LDA(At, 1, 0); PG8_STAGE(PG8_SA(0, 1), a2 + hstep, voffA);
;             PG8_WAIT_V(8); PG8_WAIT_L(0); PG8_BAR; PG8_MMA(0, 0, At, B0); PG8_MMA(0, 1, At, B1); PG8_BAR; PG8_SCHED;
;             PG8_LDA(At, 1, 1); PG8_STAGE(PG8_SB(1, 0), b3, voffB); PG8_STAGE(PG8_SB(1, 1), b3 + hstep, voffB); PG8_STAGE(PG8_SA(1, 0), a3, voffA);
;             PG8_WAIT_V(8); PG8_WAIT_L(0); PG8_BAR; PG8_MMA(1, 0, At, B0); PG8_MMA(1, 1, At, B1); PG8_BAR; PG8_SCHED;
	ds_read_b128 v[128:131], v196
	ds_read_b128 v[132:135], v197
	ds_read_b128 v[136:139], v198
	ds_read_b128 v[140:143], v199
	ds_read_b128 v[144:147], v200
	ds_read_b128 v[148:151], v201
	ds_read_b128 v[172:175], v202
	ds_read_b128 v[176:179], v203
	s_add_u32 s46, s46, 0x40000
	s_addc_u32 s47, s47, 0
	s_mov_b32 m0, s56
	ds_read_b128 v[180:183], v186 offset:32768
	ds_read_b128 v[208:211], v186 offset:33792
	ds_read_b128 v[212:215], v186 offset:34816
	ds_read_b128 v[216:219], v186 offset:35840
	ds_read_b128 v[220:223], v186 offset:36864
	ds_read_b128 v[224:227], v186 offset:37888
	ds_read_b128 v[228:231], v186 offset:38912
	ds_read_b128 v[232:235], v186 offset:39936
	global_load_lds_dwordx4 v152, s[46:47]
	s_mov_b32 m0, s57
	s_nop 0
	global_load_lds_dwordx4 v156, s[46:47]
	s_waitcnt vmcnt(8)
	s_waitcnt lgkmcnt(0)
	s_barrier
	s_setprio 1
	s_waitcnt lgkmcnt(0)
	v_mfma_f32_16x16x32_bf16 v[124:127], v[128:131], v[180:183], v[124:127]
	v_mfma_f32_16x16x32_bf16 v[120:123], v[136:139], v[180:183], v[120:123]
	v_mfma_f32_16x16x32_bf16 v[108:111], v[128:131], v[212:215], v[108:111]
	v_mfma_f32_16x16x32_bf16 v[104:107], v[136:139], v[212:215], v[104:107]
	v_mfma_f32_16x16x32_bf16 v[92:95], v[128:131], v[220:223], v[92:95]
	v_mfma_f32_16x16x32_bf16 v[88:91], v[136:139], v[220:223], v[88:91]
	v_mfma_f32_16x16x32_bf16 v[76:79], v[128:131], v[228:231], v[76:79]
	v_mfma_f32_16x16x32_bf16 v[72:75], v[136:139], v[228:231], v[72:75]
	v_mfma_f32_16x16x32_bf16 v[124:127], v[132:135], v[208:211], v[124:127]
	v_mfma_f32_16x16x32_bf16 v[120:123], v[140:143], v[208:211], v[120:123]
	v_mfma_f32_16x16x32_bf16 v[108:111], v[132:135], v[216:219], v[108:111]
	v_mfma_f32_16x16x32_bf16 v[104:107], v[140:143], v[216:219], v[104:107]
	v_mfma_f32_16x16x32_bf16 v[92:95], v[132:135], v[224:227], v[92:95]
	v_mfma_f32_16x16x32_bf16 v[88:91], v[140:143], v[224:227], v[88:91]
	v_mfma_f32_16x16x32_bf16 v[76:79], v[132:135], v[232:235], v[76:79]
	v_mfma_f32_16x16x32_bf16 v[72:75], v[140:143], v[232:235], v[72:75]
	s_setprio 0
	s_setprio 1
	v_mfma_f32_16x16x32_bf16 v[116:119], v[144:147], v[180:183], v[116:119]
	v_mfma_f32_16x16x32_bf16 v[112:115], v[172:175], v[180:183], v[112:115]
	v_mfma_f32_16x16x32_bf16 v[100:103], v[144:147], v[212:215], v[100:103]
	v_mfma_f32_16x16x32_bf16 v[96:99], v[172:175], v[212:215], v[96:99]
	v_mfma_f32_16x16x32_bf16 v[84:87], v[144:147], v[220:223], v[84:87]
	v_mfma_f32_16x16x32_bf16 v[80:83], v[172:175], v[220:223], v[80:83]
	v_mfma_f32_16x16x32_bf16 v[68:71], v[144:147], v[228:231], v[68:71]
	v_mfma_f32_16x16x32_bf16 v[64:67], v[172:175], v[228:231], v[64:67]
	v_mfma_f32_16x16x32_bf16 v[116:119], v[148:151], v[208:211], v[116:119]
	v_mfma_f32_16x16x32_bf16 v[112:115], v[176:179], v[208:211], v[112:115]
	v_mfma_f32_16x16x32_bf16 v[100:103], v[148:151], v[216:219], v[100:103]
	v_mfma_f32_16x16x32_bf16 v[96:99], v[176:179], v[216:219], v[96:99]
	v_mfma_f32_16x16x32_bf16 v[84:87], v[148:151], v[224:227], v[84:87]
	v_mfma_f32_16x16x32_bf16 v[80:83], v[176:179], v[224:227], v[80:83]
	v_mfma_f32_16x16x32_bf16 v[68:71], v[148:151], v[232:235], v[68:71]
	v_mfma_f32_16x16x32_bf16 v[64:67], v[176:179], v[232:235], v[64:67]
	s_setprio 0
	s_barrier
	s_mov_b32 m0, s59
	s_add_u32 s44, s44, 0x40080
	ds_read_b128 v[180:183], v186 offset:49152
	ds_read_b128 v[208:211], v186 offset:50176
	ds_read_b128 v[212:215], v186 offset:51200
	ds_read_b128 v[216:219], v186 offset:52224
	ds_read_b128 v[220:223], v186 offset:53248
	ds_read_b128 v[224:227], v186 offset:54272
	ds_read_b128 v[228:231], v186 offset:55296
	ds_read_b128 v[232:235], v186 offset:56320
	global_load_lds_dwordx4 v154, s[88:89]
	s_mov_b32 m0, s60
	s_addc_u32 s45, s45, 0
	global_load_lds_dwordx4 v158, s[88:89]
	s_mov_b32 m0, s63
	s_nop 0
	global_load_lds_dwordx4 v154, s[44:45]
	s_mov_b32 m0, s64
	s_nop 0
	global_load_lds_dwordx4 v158, s[44:45]
	s_mov_b32 m0, s61
	s_nop 0
	global_load_lds_dwordx4 v152, s[90:91]
	s_mov_b32 m0, s62
	s_nop 0
	global_load_lds_dwordx4 v156, s[90:91]
	s_waitcnt vmcnt(8)
	s_waitcnt lgkmcnt(0)
	s_barrier
	s_setprio 1
	s_waitcnt lgkmcnt(0)
	v_mfma_f32_16x16x32_bf16 v[60:63], v[128:131], v[180:183], v[60:63]
	v_mfma_f32_16x16x32_bf16 v[56:59], v[136:139], v[180:183], v[56:59]
	v_mfma_f32_16x16x32_bf16 v[44:47], v[128:131], v[212:215], v[44:47]
	v_mfma_f32_16x16x32_bf16 v[40:43], v[136:139], v[212:215], v[40:43]
	v_mfma_f32_16x16x32_bf16 v[28:31], v[128:131], v[220:223], v[28:31]
	v_mfma_f32_16x16x32_bf16 v[24:27], v[136:139], v[220:223], v[24:27]
	v_mfma_f32_16x16x32_bf16 v[12:15], v[128:131], v[228:231], v[12:15]
	v_mfma_f32_16x16x32_bf16 v[8:11], v[136:139], v[228:231], v[8:11]
	v_mfma_f32_16x16x32_bf16 v[60:63], v[132:135], v[208:211], v[60:63]
	v_mfma_f32_16x16x32_bf16 v[56:59], v[140:143], v[208:211], v[56:59]
	v_mfma_f32_16x16x32_bf16 v[44:47], v[132:135], v[216:219], v[44:47]
	v_mfma_f32_16x16x32_bf16 v[40:43], v[140:143], v[216:219], v[40:43]
	v_mfma_f32_16x16x32_bf16 v[28:31], v[132:135], v[224:227], v[28:31]
	v_mfma_f32_16x16x32_bf16 v[24:27], v[140:143], v[224:227], v[24:27]
	v_mfma_f32_16x16x32_bf16 v[12:15], v[132:135], v[232:235], v[12:15]
	v_mfma_f32_16x16x32_bf16 v[8:11], v[140:143], v[232:235], v[8:11]
	s_setprio 0
	s_setprio 1
	v_mfma_f32_16x16x32_bf16 v[52:55], v[144:147], v[180:183], v[52:55]
	v_mfma_f32_16x16x32_bf16 v[48:51], v[172:175], v[180:183], v[48:51]
	v_mfma_f32_16x16x32_bf16 v[36:39], v[144:147], v[212:215], v[36:39]
	v_mfma_f32_16x16x32_bf16 v[32:35], v[172:175], v[212:215], v[32:35]
	v_mfma_f32_16x16x32_bf16 v[20:23], v[144:147], v[220:223], v[20:23]
	v_mfma_f32_16x16x32_bf16 v[16:19], v[172:175], v[220:223], v[16:19]
	v_mfma_f32_16x16x32_bf16 v[4:7], v[144:147], v[228:231], v[4:7]
	v_mfma_f32_16x16x32_bf16 v[0:3], v[172:175], v[228:231], v[0:3]
	v_mfma_f32_16x16x32_bf16 v[52:55], v[148:151], v[208:211], v[52:55]
	v_mfma_f32_16x16x32_bf16 v[48:51], v[176:179], v[208:211], v[48:51]
	v_mfma_f32_16x16x32_bf16 v[36:39], v[148:151], v[216:219], v[36:39]
	v_mfma_f32_16x16x32_bf16 v[32:35], v[176:179], v[216:219], v[32:35]
	v_mfma_f32_16x16x32_bf16 v[20:23], v[148:151], v[224:227], v[20:23]
	v_mfma_f32_16x16x32_bf16 v[16:19], v[176:179], v[224:227], v[16:19]
	v_mfma_f32_16x16x32_bf16 v[4:7], v[148:151], v[232:235], v[4:7]
	v_mfma_f32_16x16x32_bf16 v[0:3], v[176:179], v[232:235], v[0:3]
	s_setprio 0
	s_barrier
	s_add_i32 s74, s74, 2
	s_add_u32 s72, s72, 0x100
	s_addc_u32 s73, s73, 0
	s_add_u32 s42, s42, 0x100
	s_addc_u32 s43, s43, 0
	s_cmp_gt_u32 s74, 13
	s_cbranch_scc0 .LBB0_163
	s_and_b64 vcc, exec, s[24:25]
	s_cbranch_vccz .LBB0_166
	s_barrier

; #define DF_DMA(t, bufi) do { const bf16_t* sb_ = sbase + (size_t)(64 * (t)) * QKVW; const unsigned base_ = (unsigned)__builtin_amdgcn_readfirstlane(ldsb + (bufi) * DF_STAGE); \
;         glds16s(sb_, oK, base_ + dK); glds16s(sb_, oK + 128u, base_ + DF_K2 + dK); glds16s(sb_, oV0, base_ + dV0); glds16s(sb_, oV1, base_ + dV1); } while (0)
; DI void diff_unit(const Args& A, const bf16_t* QKV, bf16_t* ATT, unsigned char* lds, LAS unsigned char* lds3, int b, int head, int qb, int tid, int wid, int lane) {
;     const int r32 = lane & 31, hi = lane >> 5, comp = wid >> 2, wq = wid & 3;
;     const size_t rowbase = (size_t)b * SEQ;
;     const int q0 = qb * 128 + wq * 32;
;     const int qcol = 1536 + head * 128 + comp * 64;
;     bf16x8 qf[4];
; #pragma unroll
;     for (int c = 0; c < 4; ++c) qf[c] = *(const bf16x8*)(QKV + (rowbase + q0 + r32) * QKVW + qcol + 16 * c + 8 * hi);
;     f32x16 o[4];
; #pragma unroll
;     for (int t = 0; t < 4; ++t)
; #pragma unroll
;         for (int i = 0; i < 16; ++i) o[t][i] = 0.f;
;     float m = -INFINITY, l = 0.f;
;     const int nst = 2 * (qb + 1);
;     const unsigned ldsb = (unsigned)(uintptr_t)lds3;
;     const int kkey = 8 * wid + (lane >> 3), kch = (lane & 7) ^ ((kkey >> 1) & 7);
;     const int vi0 = 2 * wid, vi1 = 2 * wid + 1;
;     const bf16_t* sbase = QKV + rowbase * QKVW + head * 128;
;     const unsigned oK = (unsigned)((kkey * QKVW + 2048 + kch * 8) * 2);
;     const unsigned oV0 = (unsigned)(((16 * (vi0 & 3) + (lane >> 2)) * QKVW + 2560 + ((vi0 >> 2) * 4 + (lane & 3)) * 8) * 2);
;     const unsigned oV1 = (unsigned)(((16 * (vi1 & 3) + (lane >> 2)) * QKVW + 2560 + ((vi1 >> 2) * 4 + (lane & 3)) * 8) * 2);
;     const unsigned dK = (unsigned)__builtin_amdgcn_readfirstlane(wid * 1024);
;     const unsigned dV0 = (unsigned)__builtin_amdgcn_readfirstlane(DF_V + (vi0 >> 2) * 4096 + (vi0 & 3) * 1024), dV1 = (unsigned)__builtin_amdgcn_readfirstlane(DF_V + (vi1 >> 2) * 4096 + (vi1 & 3) * 1024);
;     ...
;     DF_DMA(0, 0); DF_DMA(1, 1);
;     asm volatile("" : "+v"(qf[0]), "+v"(qf[1]), "+v"(qf[2]), "+v"(qf[3]));
;     DF_WAITBAR(4);
;     const int vlane = (4 * hi + ((lane & 15) >> 2)) * 64 + ((lane >> 4) & 1) * 32 + (lane & 3) * 8;
;     const bool skew = false;
;     bf16x8 pp[4]; { const bf16x8 z8 = {0, 0, 0, 0, 0, 0, 0, 0}; pp[0] = z8; pp[1] = z8; pp[2] = z8; pp[3] = z8; } int pvo = vlane; bool have_prev = false;
.LBB0_278:
	s_and_b32 s49, s7, 63
	s_ashr_i32 s6, s7, 8
	s_xor_b32 s24, s49, 0x7f
	s_bfe_u32 s22, s7, 0x20006
	s_ashr_i32 s7, s6, 31
	s_lshl_b32 s25, s24, 7
	s_lshl_b64 s[26:27], s[6:7], 14
	s_or_b32 s7, s25, s34
	v_or_b32_e32 v1, s7, v129
	s_lshl_b32 s48, s22, 7
	v_or_b32_e32 v154, s26, v1
	v_mad_u64_u32 v[2:3], s[8:9], v154, s43, v[140:141]
	s_add_u32 s28, s35, s48
	v_mad_i32_i24 v3, s27, v169, v3
	s_addc_u32 s29, s42, 0
	v_lshl_add_u64 v[2:3], s[28:29], 1, v[2:3]
	v_lshl_add_u64 v[2:3], v[2:3], 0, v[144:145]
	global_load_dwordx4 v[112:115], v[2:3], off offset:3168
	global_load_dwordx4 v[116:119], v[2:3], off offset:3136
	global_load_dwordx4 v[120:123], v[2:3], off offset:3104
	global_load_dwordx4 v[124:127], v[2:3], off offset:3072
	s_mul_hi_i32 s31, s6, 0x6000000
	s_mul_i32 s50, s6, 0x6000000
	s_lshl_b32 s6, s24, 1
	s_add_u32 s24, s12, s50
	v_add_u32_e32 v146, s25, v168
	s_addc_u32 s25, s13, s31
	s_lshl_b32 s22, s22, 8
	v_readfirstlane_b32 s30, v170
	s_add_u32 s24, s24, s22
	s_addc_u32 s25, s25, 0
	s_lshl_b32 s50, s30, 10
	s_mov_b32 s30, m0
	s_mov_b32 m0, s50
	s_nop 0
	global_load_lds_dwordx4 v156, s[24:25]
	s_mov_b32 m0, s30
	s_add_i32 s51, s50, 0x2000
	s_mov_b32 s30, m0
	s_mov_b32 m0, s51
	s_nop 0
	global_load_lds_dwordx4 v159, s[24:25]
	s_mov_b32 m0, s30
	v_readfirstlane_b32 s9, v171
	s_mov_b32 s31, m0
	s_mov_b32 m0, s9
	s_nop 0
	global_load_lds_dwordx4 v157, s[24:25]
	s_mov_b32 m0, s31
	v_readfirstlane_b32 s10, v172
	s_add_u32 s30, s24, 0x60000
	s_mov_b32 s58, m0
	s_mov_b32 m0, s10
	s_nop 0
	global_load_lds_dwordx4 v158, s[24:25]
	s_mov_b32 m0, s58
	s_addc_u32 s31, s25, 0
	s_add_i32 s54, s50, 0x8000
	s_mov_b32 s58, m0
	s_mov_b32 m0, s54
	s_nop 0
	global_load_lds_dwordx4 v156, s[30:31]
	s_mov_b32 m0, s58
	s_add_i32 s55, s50, 0xa000
	s_mov_b32 s54, m0
	s_mov_b32 m0, s55
	s_nop 0
	global_load_lds_dwordx4 v159, s[30:31]
	s_mov_b32 m0, s54
	s_add_i32 s56, s9, 0x8000
	s_mov_b32 s54, m0
	s_mov_b32 m0, s56
	s_nop 0
	global_load_lds_dwordx4 v157, s[30:31]
	s_mov_b32 m0, s54
	v_mov_b32_e32 v14, v0
	v_mov_b32_e32 v15, v0
	s_add_i32 s57, s10, 0x8000
	s_mov_b32 s54, m0
	s_mov_b32 m0, s57
	s_nop 0
	global_load_lds_dwordx4 v158, s[30:31]
	s_mov_b32 m0, s54
	v_mov_b32_e32 v1, v0
	v_mov_b32_e32 v2, v0
	v_mov_b32_e32 v3, v0
	v_mov_b32_e32 v4, v0
	v_mov_b32_e32 v5, v0
	v_mov_b32_e32 v6, v0
	v_mov_b32_e32 v7, v0
	v_mov_b32_e32 v8, v0
	v_mov_b32_e32 v9, v0
	v_mov_b32_e32 v10, v0
	v_mov_b32_e32 v11, v0
	v_mov_b32_e32 v12, v0
	v_mov_b32_e32 v13, v0
	v_mov_b64_e32 v[30:31], v[14:15]
	v_mov_b64_e32 v[46:47], v[14:15]
	v_mov_b64_e32 v[62:63], v[14:15]
	v_mov_b64_e32 v[78:79], v[14:15]
	s_mov_b32 s8, 63
	s_mov_b32 s11, 0
	v_mov_b32_e32 v143, 0
	v_mov_b32_e32 v147, 0xff800000
	v_mov_b64_e32 v[28:29], v[12:13]
	v_mov_b64_e32 v[26:27], v[10:11]
	v_mov_b64_e32 v[24:25], v[8:9]
	v_mov_b64_e32 v[22:23], v[6:7]
	v_mov_b64_e32 v[20:21], v[4:5]
	v_mov_b64_e32 v[18:19], v[2:3]
	v_mov_b64_e32 v[16:17], v[0:1]
	v_mov_b32_e32 v155, s27
	s_or_b32 s52, s6, 1
	s_or_b32 s53, s7, 31
	v_mov_b64_e32 v[44:45], v[12:13]
	v_mov_b64_e32 v[42:43], v[10:11]
	v_mov_b64_e32 v[40:41], v[8:9]
	v_mov_b64_e32 v[38:39], v[6:7]
	v_mov_b64_e32 v[36:37], v[4:5]
	v_mov_b64_e32 v[34:35], v[2:3]
	v_mov_b64_e32 v[32:33], v[0:1]
	v_mov_b64_e32 v[60:61], v[12:13]
	v_mov_b64_e32 v[58:59], v[10:11]
	v_mov_b64_e32 v[56:57], v[8:9]
	s_waitcnt vmcnt(0)
	s_waitcnt vmcnt(4) lgkmcnt(0)
	s_barrier
	v_mov_b64_e32 v[54:55], v[6:7]
	v_mov_b64_e32 v[52:53], v[4:5]
	v_mov_b64_e32 v[50:51], v[2:3]
	v_mov_b64_e32 v[48:49], v[0:1]
	s_mov_b32 s54, 0
	v_mov_b64_e32 v[76:77], v[12:13]
	v_mov_b64_e32 v[74:75], v[10:11]
	v_mov_b64_e32 v[72:73], v[8:9]
	v_mov_b64_e32 v[70:71], v[6:7]
	v_mov_b64_e32 v[68:69], v[4:5]
	v_mov_b64_e32 v[66:67], v[2:3]
	v_mov_b64_e32 v[64:65], v[0:1]
	s_mov_b32 s60, 0
	s_mov_b32 s61, 0
	s_mov_b32 s62, m0
	v_mov_b32_e32 v240, 0
	v_mov_b32_e32 v241, 0
	v_mov_b32_e32 v242, 0
	v_mov_b32_e32 v243, 0
	v_mov_b32_e32 v244, 0
	v_mov_b32_e32 v245, 0
	v_mov_b32_e32 v246, 0
	v_mov_b32_e32 v247, 0
	v_mov_b32_e32 v248, 0
	v_mov_b32_e32 v249, 0
	v_mov_b32_e32 v250, 0
	v_mov_b32_e32 v251, 0
	v_mov_b32_e32 v252, 0
	v_mov_b32_e32 v253, 0
	v_mov_b32_e32 v254, 0
	v_mov_b32_e32 v255, 0
; #define DF_DMA(t, bufi) do { const bf16_t* sb_ = sbase + (size_t)(64 * (t)) * QKVW; const unsigned base_ = (unsigned)__builtin_amdgcn_readfirstlane(ldsb + (bufi) * DF_STAGE); \
;         glds16s(sb_, oK, base_ + dK); glds16s(sb_, oK + 128u, base_ + DF_K2 + dK); glds16s(sb_, oV0, base_ + dV0); glds16s(sb_, oV1, base_ + dV1); } while (0)
; DI void diff_stage(const unsigned char* lds, LAS unsigned char* lds3, int buf, int t, int comp, int q0, int r32, int hi, int vlane, bool skew,
;                    const bf16x8 (&qf)[4], f32x16 (&o)[4], float& m, float& l, bf16x8 (&pp)[4], int& pvo, bool& have_prev) {
;     ...
;     if (k0 > q0 + 31) return;
;     const unsigned char* sb = lds + buf * DF_STAGE + comp * DF_K2 + r32 * 128; const int ke16 = (hi ^ ((r32 >> 1) & 7)) * 16;
;     bf16x8 vf[4];
;     if (skew && have_prev) {
; DI void diff_unit(const Args& A, const bf16_t* QKV, bf16_t* ATT, unsigned char* lds, LAS unsigned char* lds3, int b, int head, int qb, int tid, int wid, int lane) {
;     ...
;     for (int t = 0; t < nst; ++t) {
;         { const int tl = (t + 2 < nst) ? t + 2 : nst - 1; DF_DMA(tl, (t + 2) & 3); }
;         diff_stage(lds, lds3, t & 3, t, comp, q0, r32, hi, vlane, skew, qf, o, m, l, pp, pvo, have_prev);
.Ldf1_loop:
	s_add_i32 s55, s54, 2
	s_cmp_lt_u32 s54, s6
	s_cselect_b32 s56, s55, s52
	s_lshl_b32 s57, s56, 6
	s_mul_i32 s56, s56, 0x60000
	s_mul_hi_u32 s57, s57, 0x1800
	s_add_u32 s56, s24, s56
	s_addc_u32 s57, s25, s57
	s_lshl_b32 s55, s55, 15
	s_and_b32 s55, s55, 0x18000
	s_add_i32 s58, s55, s50
	s_mov_b32 m0, s58
	s_add_i32 s58, s55, s51
	global_load_lds_dwordx4 v156, s[56:57]
	s_mov_b32 m0, s58
	s_add_i32 s58, s55, s9
	global_load_lds_dwordx4 v159, s[56:57]
	s_mov_b32 m0, s58
	s_add_i32 s58, s55, s10
	global_load_lds_dwordx4 v157, s[56:57]
	s_mov_b32 m0, s58
	s_sub_i32 s59, s8, 63
	global_load_lds_dwordx4 v158, s[56:57]
	s_cmp_gt_u32 s59, s53
	s_cbranch_scc1 .Ldf1_skip
	s_and_b32 s55, s11, 0x18000
	v_add_u32_e32 v2, s55, v160
	v_add_u32_e32 v3, v2, v161
	v_add_u32_e32 v4, v2, v162
	v_add_u32_e32 v5, v2, v163
	v_add_u32_e32 v2, v2, v164
	ds_read_b128 v[208:211], v3
	ds_read_b128 v[212:215], v3 offset:4096
	ds_read_b128 v[216:219], v4
	ds_read_b128 v[220:223], v4 offset:4096
	ds_read_b128 v[224:227], v5
	ds_read_b128 v[228:231], v5 offset:4096
	ds_read_b128 v[232:235], v2
	ds_read_b128 v[236:239], v2 offset:4096
	s_add_i32 s56, s11, 0x18000
	s_cmp_eq_u32 s61, 0
	s_cselect_b32 s56, s11, s56
	s_and_b32 s56, s56, 0x18000
	v_add_u32_e32 v6, s56, v165
	s_cmp_eq_u32 s60, 0
	s_cbranch_scc1 .Ldf1s_noresc
	v_pk_mul_f32 v[78:79], v[78:79], v[206:207] op_sel_hi:[1,0]
	v_pk_mul_f32 v[76:77], v[76:77], v[206:207] op_sel_hi:[1,0]
	v_pk_mul_f32 v[74:75], v[74:75], v[206:207] op_sel_hi:[1,0]
	v_pk_mul_f32 v[72:73], v[72:73], v[206:207] op_sel_hi:[1,0]
	v_pk_mul_f32 v[70:71], v[70:71], v[206:207] op_sel_hi:[1,0]
	v_pk_mul_f32 v[68:69], v[68:69], v[206:207] op_sel_hi:[1,0]
	v_pk_mul_f32 v[66:67], v[66:67], v[206:207] op_sel_hi:[1,0]
	v_pk_mul_f32 v[64:65], v[64:65], v[206:207] op_sel_hi:[1,0]
	v_pk_mul_f32 v[62:63], v[62:63], v[206:207] op_sel_hi:[1,0]
	v_pk_mul_f32 v[60:61], v[60:61], v[206:207] op_sel_hi:[1,0]
	v_pk_mul_f32 v[58:59], v[58:59], v[206:207] op_sel_hi:[1,0]
	v_pk_mul_f32 v[56:57], v[56:57], v[206:207] op_sel_hi:[1,0]
	v_pk_mul_f32 v[54:55], v[54:55], v[206:207] op_sel_hi:[1,0]
	v_pk_mul_f32 v[52:53], v[52:53], v[206:207] op_sel_hi:[1,0]
	v_pk_mul_f32 v[50:51], v[50:51], v[206:207] op_sel_hi:[1,0]
	v_pk_mul_f32 v[48:49], v[48:49], v[206:207] op_sel_hi:[1,0]
	v_pk_mul_f32 v[46:47], v[46:47], v[206:207] op_sel_hi:[1,0]
	v_pk_mul_f32 v[44:45], v[44:45], v[206:207] op_sel_hi:[1,0]
	v_pk_mul_f32 v[42:43], v[42:43], v[206:207] op_sel_hi:[1,0]
	v_pk_mul_f32 v[40:41], v[40:41], v[206:207] op_sel_hi:[1,0]
	v_pk_mul_f32 v[38:39], v[38:39], v[206:207] op_sel_hi:[1,0]
	v_pk_mul_f32 v[36:37], v[36:37], v[206:207] op_sel_hi:[1,0]
	v_pk_mul_f32 v[34:35], v[34:35], v[206:207] op_sel_hi:[1,0]
	v_pk_mul_f32 v[32:33], v[32:33], v[206:207] op_sel_hi:[1,0]
	v_pk_mul_f32 v[30:31], v[30:31], v[206:207] op_sel_hi:[1,0]
	v_pk_mul_f32 v[28:29], v[28:29], v[206:207] op_sel_hi:[1,0]
	v_pk_mul_f32 v[26:27], v[26:27], v[206:207] op_sel_hi:[1,0]
	v_pk_mul_f32 v[24:25], v[24:25], v[206:207] op_sel_hi:[1,0]
	v_pk_mul_f32 v[22:23], v[22:23], v[206:207] op_sel_hi:[1,0]
	v_pk_mul_f32 v[20:21], v[20:21], v[206:207] op_sel_hi:[1,0]
	v_pk_mul_f32 v[18:19], v[18:19], v[206:207] op_sel_hi:[1,0]
	v_pk_mul_f32 v[16:17], v[16:17], v[206:207] op_sel_hi:[1,0]
	s_mov_b32 s60, 0

; #define DF_VLD(VF, VOFF, H) do { _Pragma("unroll") for (int d2 = 0; d2 < 2; ++d2) { LAS unsigned char* vb_ = lds3 + (VOFF) + (2 * (H) + d2) * 4096; VF[2 * d2] = vfrag(vb_); VF[2 * d2 + 1] = vfrag(vb_ + 1024); } } while (0)
; #define DF_PVM(VF, P0, P1, H) do { _Pragma("unroll") for (int d2 = 0; d2 < 2; ++d2) { o[2 * (H) + d2] = mfma32(VF[2 * d2], P0, o[2 * (H) + d2]); o[2 * (H) + d2] = mfma32(VF[2 * d2 + 1], P1, o[2 * (H) + d2]); } } while (0)
; DI void diff_unit(const Args& A, const bf16_t* QKV, bf16_t* ATT, unsigned char* lds, LAS unsigned char* lds3, int b, int head, int qb, int tid, int wid, int lane) {
;     ...
;     asm volatile("s_waitcnt vmcnt(0)" ::: "memory");
;     ...
;     if (skew && have_prev) { bf16x8 vf[4];
; #pragma unroll
;         for (int sub = 0; sub < 2; ++sub) { DF_VLD(vf, pvo + sub * 2048, 0); DF_PVM(vf, pp[2 * sub], pp[2 * sub + 1], 0); DF_VLD(vf, pvo + sub * 2048, 1); DF_PVM(vf, pp[2 * sub], pp[2 * sub + 1], 1); } }
.Ldf1_exit:
	s_mov_b32 m0, s62
	s_cmp_eq_u32 s61, 0
	s_cbranch_scc1 .LBB0_287
	s_add_i32 s56, s11, 0x18000
	s_and_b32 s56, s56, 0x18000
	v_add_u32_e32 v6, s56, v165
	s_cmp_eq_u32 s60, 0
	s_cbranch_scc1 .Ldf1x_noresc
	v_pk_mul_f32 v[78:79], v[78:79], v[206:207] op_sel_hi:[1,0]
	v_pk_mul_f32 v[76:77], v[76:77], v[206:207] op_sel_hi:[1,0]
	v_pk_mul_f32 v[74:75], v[74:75], v[206:207] op_sel_hi:[1,0]
	v_pk_mul_f32 v[72:73], v[72:73], v[206:207] op_sel_hi:[1,0]
	v_pk_mul_f32 v[70:71], v[70:71], v[206:207] op_sel_hi:[1,0]
	v_pk_mul_f32 v[68:69], v[68:69], v[206:207] op_sel_hi:[1,0]
	v_pk_mul_f32 v[66:67], v[66:67], v[206:207] op_sel_hi:[1,0]
	v_pk_mul_f32 v[64:65], v[64:65], v[206:207] op_sel_hi:[1,0]
	v_pk_mul_f32 v[62:63], v[62:63], v[206:207] op_sel_hi:[1,0]
	v_pk_mul_f32 v[60:61], v[60:61], v[206:207] op_sel_hi:[1,0]
	v_pk_mul_f32 v[58:59], v[58:59], v[206:207] op_sel_hi:[1,0]
	v_pk_mul_f32 v[56:57], v[56:57], v[206:207] op_sel_hi:[1,0]
	v_pk_mul_f32 v[54:55], v[54:55], v[206:207] op_sel_hi:[1,0]
	v_pk_mul_f32 v[52:53], v[52:53], v[206:207] op_sel_hi:[1,0]
	v_pk_mul_f32 v[50:51], v[50:51], v[206:207] op_sel_hi:[1,0]
	v_pk_mul_f32 v[48:49], v[48:49], v[206:207] op_sel_hi:[1,0]
	v_pk_mul_f32 v[46:47], v[46:47], v[206:207] op_sel_hi:[1,0]
	v_pk_mul_f32 v[44:45], v[44:45], v[206:207] op_sel_hi:[1,0]
	v_pk_mul_f32 v[42:43], v[42:43], v[206:207] op_sel_hi:[1,0]
	v_pk_mul_f32 v[40:41], v[40:41], v[206:207] op_sel_hi:[1,0]
	v_pk_mul_f32 v[38:39], v[38:39], v[206:207] op_sel_hi:[1,0]
	v_pk_mul_f32 v[36:37], v[36:37], v[206:207] op_sel_hi:[1,0]
	v_pk_mul_f32 v[34:35], v[34:35], v[206:207] op_sel_hi:[1,0]
	v_pk_mul_f32 v[32:33], v[32:33], v[206:207] op_sel_hi:[1,0]
	v_pk_mul_f32 v[30:31], v[30:31], v[206:207] op_sel_hi:[1,0]
	v_pk_mul_f32 v[28:29], v[28:29], v[206:207] op_sel_hi:[1,0]
	v_pk_mul_f32 v[26:27], v[26:27], v[206:207] op_sel_hi:[1,0]
	v_pk_mul_f32 v[24:25], v[24:25], v[206:207] op_sel_hi:[1,0]
	v_pk_mul_f32 v[22:23], v[22:23], v[206:207] op_sel_hi:[1,0]
	v_pk_mul_f32 v[20:21], v[20:21], v[206:207] op_sel_hi:[1,0]
	v_pk_mul_f32 v[18:19], v[18:19], v[206:207] op_sel_hi:[1,0]
	v_pk_mul_f32 v[16:17], v[16:17], v[206:207] op_sel_hi:[1,0]
	s_mov_b32 s60, 0

; #define LAS __attribute__((address_space(3)))
; DI void diff_unit(const Args& A, const bf16_t* QKV, bf16_t* ATT, unsigned char* lds, LAS unsigned char* lds3, int b, int head, int qb, int tid, int wid, int lane) {
;     const int r32 = lane & 31, hi = lane >> 5, comp = wid >> 2, wq = wid & 3;
;     const size_t rowbase = (size_t)b * SEQ;
;     const int q0 = qb * 128 + wq * 32;
;     const int qcol = 1536 + head * 128 + comp * 64;
;     bf16x8 qf[4];
; #pragma unroll
;     for (int c = 0; c < 4; ++c) qf[c] = *(const bf16x8*)(QKV + (rowbase + q0 + r32) * QKVW + qcol + 16 * c + 8 * hi);
;     f32x16 o[4];
; #pragma unroll
;     for (int t = 0; t < 4; ++t)
; #pragma unroll
;         for (int i = 0; i < 16; ++i) o[t][i] = 0.f;
;     float m = -INFINITY, l = 0.f;
;     const int nst = 2 * (qb + 1);
;     const unsigned ldsb = (unsigned)(uintptr_t)lds3;
;     const int kkey = 8 * wid + (lane >> 3), kch = (lane & 7) ^ ((kkey >> 1) & 7);
;     const int vi0 = 2 * wid, vi1 = 2 * wid + 1;
;     const bf16_t* sbase = QKV + rowbase * QKVW + head * 128;
;     const unsigned oK = (unsigned)((kkey * QKVW + 2048 + kch * 8) * 2);
;     const unsigned oV0 = (unsigned)(((16 * (vi0 & 3) + (lane >> 2)) * QKVW + 2560 + ((vi0 >> 2) * 4 + (lane & 3)) * 8) * 2);
;     const unsigned oV1 = (unsigned)(((16 * (vi1 & 3) + (lane >> 2)) * QKVW + 2560 + ((vi1 >> 2) * 4 + (lane & 3)) * 8) * 2);
;     const unsigned dK = (unsigned)__builtin_amdgcn_readfirstlane(wid * 1024);
;     const unsigned dV0 = (unsigned)__builtin_amdgcn_readfirstlane(DF_V + (vi0 >> 2) * 4096 + (vi0 & 3) * 1024), dV1 = (unsigned)__builtin_amdgcn_readfirstlane(DF_V + (vi1 >> 2) * 4096 + (vi1 & 3) * 1024);
;     ...
;     DF_DMA(0, 0); DF_DMA(1, 1);
;     asm volatile("" : "+v"(qf[0]), "+v"(qf[1]), "+v"(qf[2]), "+v"(qf[3]));
;     DF_WAITBAR(4);
;     const int vlane = (4 * hi + ((lane & 15) >> 2)) * 64 + ((lane >> 4) & 1) * 32 + (lane & 3) * 8;
;     const bool skew = false;
;     bf16x8 pp[4]; { const bf16x8 z8 = {0, 0, 0, 0, 0, 0, 0, 0}; pp[0] = z8; pp[1] = z8; pp[2] = z8; pp[3] = z8; } int pvo = vlane; bool have_prev = false;
;     for (int t = 0; t < nst; ++t) {
;         { const int tl = (t + 2 < nst) ? t + 2 : nst - 1; DF_DMA(tl, (t + 2) & 3); }
;         diff_stage(lds, lds3, t & 3, t, comp, q0, r32, hi, vlane, skew, qf, o, m, l, pp, pvo, have_prev);
.LBB0_291:
	s_lshl_b32 s52, s49, 7
	s_or_b32 s10, s52, s34
	v_or_b32_e32 v1, s10, v129
	v_or_b32_e32 v154, s26, v1
	v_mov_b64_e32 v[2:3], s[12:13]
	v_mad_u64_u32 v[2:3], s[50:51], v154, s43, v[2:3]
	v_mad_i32_i24 v3, s27, v169, v3
	v_lshl_add_u64 v[2:3], s[28:29], 1, v[2:3]
	v_mov_b32_e32 v143, v0
	v_lshl_add_u64 v[2:3], v[2:3], 0, v[142:143]
	s_barrier
	global_load_dwordx4 v[112:115], v[2:3], off offset:3168
	global_load_dwordx4 v[116:119], v[2:3], off offset:3136
	global_load_dwordx4 v[120:123], v[2:3], off offset:3104
	global_load_dwordx4 v[124:127], v[2:3], off offset:3072
	s_lshl_b32 s22, s33, 10
	v_add_u32_e32 v183, s52, v168
	s_mov_b32 s52, m0
	s_mov_b32 m0, s22
	s_nop 0
	global_load_lds_dwordx4 v156, s[24:25]
	s_mov_b32 m0, s52
	s_add_i32 s28, s22, 0x2000
	s_mov_b32 s52, m0
	s_mov_b32 m0, s28
	s_nop 0
	global_load_lds_dwordx4 v159, s[24:25]
	s_mov_b32 m0, s52
	s_add_i32 s53, s22, 0x8000
	s_mov_b32 s52, m0
	s_mov_b32 m0, s36
	s_nop 0
	global_load_lds_dwordx4 v157, s[24:25]
	s_mov_b32 m0, s52
	s_add_i32 s54, s22, 0xa000
	s_mov_b32 s52, m0
	s_mov_b32 m0, s37
	s_nop 0
	global_load_lds_dwordx4 v158, s[24:25]
	s_mov_b32 m0, s52
	s_add_i32 s50, s36, 0x8000
	s_mov_b32 s52, m0
	s_mov_b32 m0, s53
	s_nop 0
	global_load_lds_dwordx4 v156, s[30:31]
	s_mov_b32 m0, s52
	s_add_i32 s51, s37, 0x8000
	s_mov_b32 s52, m0
	s_mov_b32 m0, s54
	s_nop 0
	global_load_lds_dwordx4 v159, s[30:31]
	s_mov_b32 m0, s52
	v_mov_b32_e32 v14, v0
	s_mov_b32 s52, m0
	s_mov_b32 m0, s50
	s_nop 0
	global_load_lds_dwordx4 v157, s[30:31]
	s_mov_b32 m0, s52
	v_mov_b32_e32 v15, v0
	s_mov_b32 s50, m0
	s_mov_b32 m0, s51
	s_nop 0
	global_load_lds_dwordx4 v158, s[30:31]
	s_mov_b32 m0, s50
	s_lshl_b32 s11, s49, 1
	v_mov_b32_e32 v1, v0
	v_mov_b32_e32 v2, v0
	v_mov_b32_e32 v3, v0
	v_mov_b32_e32 v4, v0
	v_mov_b32_e32 v5, v0
	v_mov_b32_e32 v6, v0
	v_mov_b32_e32 v7, v0
	v_mov_b32_e32 v8, v0
	v_mov_b32_e32 v9, v0
	v_mov_b32_e32 v10, v0
	v_mov_b32_e32 v11, v0
	v_mov_b32_e32 v12, v0
	v_mov_b32_e32 v13, v0
	v_mov_b64_e32 v[30:31], v[14:15]
	v_mov_b64_e32 v[46:47], v[14:15]
	v_mov_b64_e32 v[62:63], v[14:15]
	v_mov_b64_e32 v[78:79], v[14:15]
	v_mov_b32_e32 v155, s27
	s_mov_b32 s26, 0
	v_mov_b32_e32 v143, 0
	v_mov_b32_e32 v185, 0xff800000
	s_mov_b32 s27, 63
	s_or_b32 s29, s11, 1
	v_mov_b64_e32 v[28:29], v[12:13]
	v_mov_b64_e32 v[26:27], v[10:11]
	v_mov_b64_e32 v[24:25], v[8:9]
	v_mov_b64_e32 v[22:23], v[6:7]
	v_mov_b64_e32 v[20:21], v[4:5]
	v_mov_b64_e32 v[18:19], v[2:3]
	v_mov_b64_e32 v[16:17], v[0:1]
	s_or_b32 s49, s10, 31
	v_mov_b64_e32 v[44:45], v[12:13]
	v_mov_b64_e32 v[42:43], v[10:11]
	v_mov_b64_e32 v[40:41], v[8:9]
	v_mov_b64_e32 v[38:39], v[6:7]
	v_mov_b64_e32 v[36:37], v[4:5]
	v_mov_b64_e32 v[34:35], v[2:3]
	v_mov_b64_e32 v[32:33], v[0:1]
	v_mov_b64_e32 v[60:61], v[12:13]
	v_mov_b64_e32 v[58:59], v[10:11]
	v_mov_b64_e32 v[56:57], v[8:9]
	v_mov_b64_e32 v[54:55], v[6:7]
	v_mov_b64_e32 v[52:53], v[4:5]
	v_mov_b64_e32 v[50:51], v[2:3]
	v_mov_b64_e32 v[48:49], v[0:1]
	s_mov_b32 s30, 0
	v_mov_b64_e32 v[76:77], v[12:13]
	v_mov_b64_e32 v[74:75], v[10:11]
	v_mov_b64_e32 v[72:73], v[8:9]
	v_mov_b64_e32 v[70:71], v[6:7]
	v_mov_b64_e32 v[68:69], v[4:5]
	v_mov_b64_e32 v[66:67], v[2:3]
	v_mov_b64_e32 v[64:65], v[0:1]
	s_waitcnt vmcnt(0)
	s_waitcnt vmcnt(4) lgkmcnt(0)
	s_barrier
	s_mov_b32 s60, 0
	s_mov_b32 s61, 0
	s_mov_b32 s62, m0
	v_mov_b32_e32 v240, 0
	v_mov_b32_e32 v241, 0
	v_mov_b32_e32 v242, 0
	v_mov_b32_e32 v243, 0
	v_mov_b32_e32 v244, 0
	v_mov_b32_e32 v245, 0
	v_mov_b32_e32 v246, 0
	v_mov_b32_e32 v247, 0
	v_mov_b32_e32 v248, 0
	v_mov_b32_e32 v249, 0
	v_mov_b32_e32 v250, 0
	v_mov_b32_e32 v251, 0
	v_mov_b32_e32 v252, 0
	v_mov_b32_e32 v253, 0
	v_mov_b32_e32 v254, 0
	v_mov_b32_e32 v255, 0
.Ldf2_loop:
	s_add_i32 s31, s30, 2
	s_cmp_lt_u32 s30, s11
	s_cselect_b32 s50, s31, s29
	s_lshl_b32 s51, s50, 6
	s_mul_i32 s50, s50, 0x60000
	s_mul_hi_u32 s51, s51, 0x1800
	s_add_u32 s50, s24, s50
	s_addc_u32 s51, s25, s51
	s_lshl_b32 s31, s31, 15
	s_and_b32 s31, s31, 0x18000
	s_add_i32 s52, s31, s22
	s_mov_b32 m0, s52
	s_add_i32 s52, s31, s28
	global_load_lds_dwordx4 v156, s[50:51]
	s_mov_b32 m0, s52
	s_add_i32 s52, s31, s36
	global_load_lds_dwordx4 v159, s[50:51]
	s_mov_b32 m0, s52
	s_add_i32 s52, s31, s37
	global_load_lds_dwordx4 v157, s[50:51]
	s_mov_b32 m0, s52
	s_sub_i32 s53, s27, 63
	global_load_lds_dwordx4 v158, s[50:51]
	s_cmp_gt_u32 s53, s49
	s_cbranch_scc1 .Ldf2_skip
	s_and_b32 s31, s26, 0x18000
	v_add_u32_e32 v2, s31, v160
	v_add_u32_e32 v3, v2, v161
	v_add_u32_e32 v4, v2, v162
	v_add_u32_e32 v5, v2, v163
	v_add_u32_e32 v2, v2, v164
	ds_read_b128 v[208:211], v3
	ds_read_b128 v[212:215], v3 offset:4096
	ds_read_b128 v[216:219], v4
	ds_read_b128 v[220:223], v4 offset:4096
	ds_read_b128 v[224:227], v5
	ds_read_b128 v[228:231], v5 offset:4096
	ds_read_b128 v[232:235], v2
	ds_read_b128 v[236:239], v2 offset:4096
	s_add_i32 s50, s26, 0x18000
	s_cmp_eq_u32 s61, 0
	s_cselect_b32 s50, s26, s50
	s_and_b32 s50, s50, 0x18000
	v_add_u32_e32 v6, s50, v165
	s_cmp_eq_u32 s60, 0
	s_cbranch_scc1 .Ldf2s_noresc
	v_pk_mul_f32 v[78:79], v[78:79], v[206:207] op_sel_hi:[1,0]
	v_pk_mul_f32 v[76:77], v[76:77], v[206:207] op_sel_hi:[1,0]
	v_pk_mul_f32 v[74:75], v[74:75], v[206:207] op_sel_hi:[1,0]
	v_pk_mul_f32 v[72:73], v[72:73], v[206:207] op_sel_hi:[1,0]
	v_pk_mul_f32 v[70:71], v[70:71], v[206:207] op_sel_hi:[1,0]
	v_pk_mul_f32 v[68:69], v[68:69], v[206:207] op_sel_hi:[1,0]
	v_pk_mul_f32 v[66:67], v[66:67], v[206:207] op_sel_hi:[1,0]
	v_pk_mul_f32 v[64:65], v[64:65], v[206:207] op_sel_hi:[1,0]
	v_pk_mul_f32 v[62:63], v[62:63], v[206:207] op_sel_hi:[1,0]
	v_pk_mul_f32 v[60:61], v[60:61], v[206:207] op_sel_hi:[1,0]
	v_pk_mul_f32 v[58:59], v[58:59], v[206:207] op_sel_hi:[1,0]
	v_pk_mul_f32 v[56:57], v[56:57], v[206:207] op_sel_hi:[1,0]
	v_pk_mul_f32 v[54:55], v[54:55], v[206:207] op_sel_hi:[1,0]
	v_pk_mul_f32 v[52:53], v[52:53], v[206:207] op_sel_hi:[1,0]
	v_pk_mul_f32 v[50:51], v[50:51], v[206:207] op_sel_hi:[1,0]
	v_pk_mul_f32 v[48:49], v[48:49], v[206:207] op_sel_hi:[1,0]
	v_pk_mul_f32 v[46:47], v[46:47], v[206:207] op_sel_hi:[1,0]
	v_pk_mul_f32 v[44:45], v[44:45], v[206:207] op_sel_hi:[1,0]
	v_pk_mul_f32 v[42:43], v[42:43], v[206:207] op_sel_hi:[1,0]
	v_pk_mul_f32 v[40:41], v[40:41], v[206:207] op_sel_hi:[1,0]
	v_pk_mul_f32 v[38:39], v[38:39], v[206:207] op_sel_hi:[1,0]
	v_pk_mul_f32 v[36:37], v[36:37], v[206:207] op_sel_hi:[1,0]
	v_pk_mul_f32 v[34:35], v[34:35], v[206:207] op_sel_hi:[1,0]
	v_pk_mul_f32 v[32:33], v[32:33], v[206:207] op_sel_hi:[1,0]
	v_pk_mul_f32 v[30:31], v[30:31], v[206:207] op_sel_hi:[1,0]
	v_pk_mul_f32 v[28:29], v[28:29], v[206:207] op_sel_hi:[1,0]
	v_pk_mul_f32 v[26:27], v[26:27], v[206:207] op_sel_hi:[1,0]
	v_pk_mul_f32 v[24:25], v[24:25], v[206:207] op_sel_hi:[1,0]
	v_pk_mul_f32 v[22:23], v[22:23], v[206:207] op_sel_hi:[1,0]
	v_pk_mul_f32 v[20:21], v[20:21], v[206:207] op_sel_hi:[1,0]
	v_pk_mul_f32 v[18:19], v[18:19], v[206:207] op_sel_hi:[1,0]
	v_pk_mul_f32 v[16:17], v[16:17], v[206:207] op_sel_hi:[1,0]
	s_mov_b32 s60, 0

; #define DF_VLD(VF, VOFF, H) do { _Pragma("unroll") for (int d2 = 0; d2 < 2; ++d2) { LAS unsigned char* vb_ = lds3 + (VOFF) + (2 * (H) + d2) * 4096; VF[2 * d2] = vfrag(vb_); VF[2 * d2 + 1] = vfrag(vb_ + 1024); } } while (0)
; #define DF_PVM(VF, P0, P1, H) do { _Pragma("unroll") for (int d2 = 0; d2 < 2; ++d2) { o[2 * (H) + d2] = mfma32(VF[2 * d2], P0, o[2 * (H) + d2]); o[2 * (H) + d2] = mfma32(VF[2 * d2 + 1], P1, o[2 * (H) + d2]); } } while (0)
; DI void diff_unit(const Args& A, const bf16_t* QKV, bf16_t* ATT, unsigned char* lds, LAS unsigned char* lds3, int b, int head, int qb, int tid, int wid, int lane) {
;     ...
;     asm volatile("s_waitcnt vmcnt(0)" ::: "memory");
;     ...
;     if (skew && have_prev) { bf16x8 vf[4];
; #pragma unroll
;         for (int sub = 0; sub < 2; ++sub) { DF_VLD(vf, pvo + sub * 2048, 0); DF_PVM(vf, pp[2 * sub], pp[2 * sub + 1], 0); DF_VLD(vf, pvo + sub * 2048, 1); DF_PVM(vf, pp[2 * sub], pp[2 * sub + 1], 1); } }
.Ldf2_exit:
	s_mov_b32 m0, s62
	s_cmp_eq_u32 s61, 0
	s_cbranch_scc1 .LBB0_300
	s_add_i32 s50, s26, 0x18000
	s_and_b32 s50, s50, 0x18000
	v_add_u32_e32 v6, s50, v165
	s_cmp_eq_u32 s60, 0
	s_cbranch_scc1 .Ldf2x_noresc
	v_pk_mul_f32 v[78:79], v[78:79], v[206:207] op_sel_hi:[1,0]
	v_pk_mul_f32 v[76:77], v[76:77], v[206:207] op_sel_hi:[1,0]
	v_pk_mul_f32 v[74:75], v[74:75], v[206:207] op_sel_hi:[1,0]
	v_pk_mul_f32 v[72:73], v[72:73], v[206:207] op_sel_hi:[1,0]
	v_pk_mul_f32 v[70:71], v[70:71], v[206:207] op_sel_hi:[1,0]
	v_pk_mul_f32 v[68:69], v[68:69], v[206:207] op_sel_hi:[1,0]
	v_pk_mul_f32 v[66:67], v[66:67], v[206:207] op_sel_hi:[1,0]
	v_pk_mul_f32 v[64:65], v[64:65], v[206:207] op_sel_hi:[1,0]
	v_pk_mul_f32 v[62:63], v[62:63], v[206:207] op_sel_hi:[1,0]
	v_pk_mul_f32 v[60:61], v[60:61], v[206:207] op_sel_hi:[1,0]
	v_pk_mul_f32 v[58:59], v[58:59], v[206:207] op_sel_hi:[1,0]
	v_pk_mul_f32 v[56:57], v[56:57], v[206:207] op_sel_hi:[1,0]
	v_pk_mul_f32 v[54:55], v[54:55], v[206:207] op_sel_hi:[1,0]
	v_pk_mul_f32 v[52:53], v[52:53], v[206:207] op_sel_hi:[1,0]
	v_pk_mul_f32 v[50:51], v[50:51], v[206:207] op_sel_hi:[1,0]
	v_pk_mul_f32 v[48:49], v[48:49], v[206:207] op_sel_hi:[1,0]
	v_pk_mul_f32 v[46:47], v[46:47], v[206:207] op_sel_hi:[1,0]
	v_pk_mul_f32 v[44:45], v[44:45], v[206:207] op_sel_hi:[1,0]
	v_pk_mul_f32 v[42:43], v[42:43], v[206:207] op_sel_hi:[1,0]
	v_pk_mul_f32 v[40:41], v[40:41], v[206:207] op_sel_hi:[1,0]
	v_pk_mul_f32 v[38:39], v[38:39], v[206:207] op_sel_hi:[1,0]
	v_pk_mul_f32 v[36:37], v[36:37], v[206:207] op_sel_hi:[1,0]
	v_pk_mul_f32 v[34:35], v[34:35], v[206:207] op_sel_hi:[1,0]
	v_pk_mul_f32 v[32:33], v[32:33], v[206:207] op_sel_hi:[1,0]
	v_pk_mul_f32 v[30:31], v[30:31], v[206:207] op_sel_hi:[1,0]
	v_pk_mul_f32 v[28:29], v[28:29], v[206:207] op_sel_hi:[1,0]
	v_pk_mul_f32 v[26:27], v[26:27], v[206:207] op_sel_hi:[1,0]
	v_pk_mul_f32 v[24:25], v[24:25], v[206:207] op_sel_hi:[1,0]
	v_pk_mul_f32 v[22:23], v[22:23], v[206:207] op_sel_hi:[1,0]
	v_pk_mul_f32 v[20:21], v[20:21], v[206:207] op_sel_hi:[1,0]
	v_pk_mul_f32 v[18:19], v[18:19], v[206:207] op_sel_hi:[1,0]
	v_pk_mul_f32 v[16:17], v[16:17], v[206:207] op_sel_hi:[1,0]
	s_mov_b32 s60, 0

; #define PG8_STAGE(bufoff, gbase, voff) do { _Pragma("unroll") for (int _i = 0; _i < 2; ++_i) \
;         __builtin_amdgcn_global_load_lds((const unsigned*)((const char*)(gbase) + (voff)[_i]), (PG8_LAS unsigned*)(lds + (bufoff) + ldsw + _i * 8192), 16, 0, 0); } while (0)
; #define PG8_LDA(dst, b, h) do { _Pragma("unroll") for (int m = 0; m < 4; ++m) _Pragma("unroll") for (int k = 0; k < 2; ++k) dst[m][k] = *(const PG8_LAS bf16x8*)(lds + PG8_SA(b, h) + aoff + m * 2048 + k * 1024); } while (0)
; #define PG8_LDB(dst, b, h) do { _Pragma("unroll") for (int n = 0; n < 2; ++n) _Pragma("unroll") for (int k = 0; k < 2; ++k) dst[n][k] = *(const PG8_LAS bf16x8*)(lds + PG8_SB(b, h) + boff + n * 2048 + k * 1024); } while (0)
; #define PG8_MMA(ai, bj, At, Bt) do { __builtin_amdgcn_s_setprio(1); _Pragma("unroll") for (int m = 0; m < 4; ++m) _Pragma("unroll") for (int n = 0; n < 2; ++n) _Pragma("unroll") for (int k = 0; k < 2; ++k) \
;         acc[ai][bj][m][n] = __builtin_amdgcn_mfma_f32_16x16x32_bf16(Bt[n][k], At[m][k], acc[ai][bj][m][n], 0, 0, 0); __builtin_amdgcn_s_setprio(0); } while (0)
; #define PG8_WAIT_V(n) asm volatile("s_waitcnt vmcnt(" #n ")" ::: "memory")
; #define PG8_WAIT_L(n) asm volatile("s_waitcnt lgkmcnt(" #n ")" ::: "memory")
; #define PG8_BAR __builtin_amdgcn_s_barrier()
; #define PG8_SCHED __builtin_amdgcn_sched_barrier(0)
; template <class Epi, class Sched, bool ALIGN_EPI = false, bool SP2 = false>
; __device__ __forceinline__ void gemm_phase(PG8_LAS unsigned char* lds, const Gemm g, const Sched& S, const Epi& E) {
;     ...
;             PG8_LDB(B0, 0, 0); PG8_LDB(B1, 0, 1); PG8_SCHED; PG8_LDA(At, 0, 0); PG8_STAGE(PG8_SA(1, 1), a1 + hstep, voffA);
;             PG8_WAIT_V(8); PG8_WAIT_L(0); PG8_BAR; PG8_MMA(0, 0, At, B0); PG8_MMA(0, 1, At, B1); PG8_BAR; PG8_SCHED;
;             PG8_LDA(At, 0, 1); PG8_STAGE(PG8_SB(0, 0), b2, voffB); PG8_STAGE(PG8_SB(0, 1), b2 + hstep, voffB); PG8_STAGE(PG8_SA(0, 0), a2, voffA);
;             PG8_WAIT_V(8); PG8_WAIT_L(0); PG8_BAR; PG8_MMA(1, 0, At, B0); PG8_MMA(1, 1, At, B1); PG8_BAR; PG8_SCHED;
.LBB0_390:
	ds_read_b128 v[144:147], v151
	ds_read_b128 v[168:171], v152
	ds_read_b128 v[172:175], v153
	ds_read_b128 v[176:179], v154
	ds_read_b128 v[180:183], v155
	ds_read_b128 v[186:189], v156
	ds_read_b128 v[190:193], v157
	ds_read_b128 v[194:197], v158
	s_add_u32 s36, s34, 0xfffc0080
	s_addc_u32 s37, s35, -1
	s_cmp_eq_u32 s70, 12
	s_cselect_b32 s43, s25, s37
	s_cselect_b32 s42, s31, s36
	s_cselect_b32 s37, s23, s69
	s_cselect_b32 s36, s67, s68
	s_mov_b32 m0, s64
	ds_read_b128 v[198:201], v149
	ds_read_b128 v[202:205], v149 offset:1024
	ds_read_b128 v[206:209], v149 offset:2048
	ds_read_b128 v[210:213], v149 offset:3072
	ds_read_b128 v[214:217], v149 offset:4096
	ds_read_b128 v[218:221], v149 offset:5120
	ds_read_b128 v[222:225], v149 offset:6144
	ds_read_b128 v[226:229], v149 offset:7168
	global_load_lds_dwordx4 v138, s[34:35]
	s_mov_b32 m0, s65
	s_nop 0
	global_load_lds_dwordx4 v136, s[34:35]
	s_waitcnt vmcnt(8)
	s_waitcnt lgkmcnt(0)
	s_barrier
	s_setprio 1
	s_waitcnt lgkmcnt(0)
	v_mfma_f32_16x16x32_bf16 v[124:127], v[144:147], v[198:201], v[124:127]
	v_mfma_f32_16x16x32_bf16 v[120:123], v[172:175], v[198:201], v[120:123]
	v_mfma_f32_16x16x32_bf16 v[108:111], v[144:147], v[206:209], v[108:111]
	v_mfma_f32_16x16x32_bf16 v[104:107], v[172:175], v[206:209], v[104:107]
	v_mfma_f32_16x16x32_bf16 v[92:95], v[144:147], v[214:217], v[92:95]
	v_mfma_f32_16x16x32_bf16 v[88:91], v[172:175], v[214:217], v[88:91]
	v_mfma_f32_16x16x32_bf16 v[76:79], v[144:147], v[222:225], v[76:79]
	v_mfma_f32_16x16x32_bf16 v[72:75], v[172:175], v[222:225], v[72:75]
	v_mfma_f32_16x16x32_bf16 v[124:127], v[168:171], v[202:205], v[124:127]
	v_mfma_f32_16x16x32_bf16 v[120:123], v[176:179], v[202:205], v[120:123]
	v_mfma_f32_16x16x32_bf16 v[108:111], v[168:171], v[210:213], v[108:111]
	v_mfma_f32_16x16x32_bf16 v[104:107], v[176:179], v[210:213], v[104:107]
	v_mfma_f32_16x16x32_bf16 v[92:95], v[168:171], v[218:221], v[92:95]
	v_mfma_f32_16x16x32_bf16 v[88:91], v[176:179], v[218:221], v[88:91]
	v_mfma_f32_16x16x32_bf16 v[76:79], v[168:171], v[226:229], v[76:79]
	v_mfma_f32_16x16x32_bf16 v[72:75], v[176:179], v[226:229], v[72:75]
	s_setprio 0
	s_setprio 1
	v_mfma_f32_16x16x32_bf16 v[116:119], v[180:183], v[198:201], v[116:119]
	v_mfma_f32_16x16x32_bf16 v[112:115], v[190:193], v[198:201], v[112:115]
	v_mfma_f32_16x16x32_bf16 v[100:103], v[180:183], v[206:209], v[100:103]
	v_mfma_f32_16x16x32_bf16 v[96:99], v[190:193], v[206:209], v[96:99]
	v_mfma_f32_16x16x32_bf16 v[84:87], v[180:183], v[214:217], v[84:87]
	v_mfma_f32_16x16x32_bf16 v[80:83], v[190:193], v[214:217], v[80:83]
	v_mfma_f32_16x16x32_bf16 v[68:71], v[180:183], v[222:225], v[68:71]
	v_mfma_f32_16x16x32_bf16 v[64:67], v[190:193], v[222:225], v[64:67]
	v_mfma_f32_16x16x32_bf16 v[116:119], v[186:189], v[202:205], v[116:119]
	v_mfma_f32_16x16x32_bf16 v[112:115], v[194:197], v[202:205], v[112:115]
	v_mfma_f32_16x16x32_bf16 v[100:103], v[186:189], v[210:213], v[100:103]
	v_mfma_f32_16x16x32_bf16 v[96:99], v[194:197], v[210:213], v[96:99]
	v_mfma_f32_16x16x32_bf16 v[84:87], v[186:189], v[218:221], v[84:87]
	v_mfma_f32_16x16x32_bf16 v[80:83], v[194:197], v[218:221], v[80:83]
	v_mfma_f32_16x16x32_bf16 v[68:71], v[186:189], v[226:229], v[68:71]
	v_mfma_f32_16x16x32_bf16 v[64:67], v[194:197], v[226:229], v[64:67]
	s_setprio 0
	s_barrier
	s_add_u32 s88, s36, 0x80
	s_addc_u32 s89, s37, 0
	s_add_u32 s90, s42, 0x80
	s_addc_u32 s91, s43, 0
	s_mov_b32 m0, s48
	s_add_u32 s72, s36, 0x40000
	ds_read_b128 v[198:201], v149 offset:16384
	ds_read_b128 v[202:205], v149 offset:17408
	ds_read_b128 v[206:209], v149 offset:18432
	ds_read_b128 v[210:213], v149 offset:19456
	ds_read_b128 v[214:217], v149 offset:20480
	ds_read_b128 v[218:221], v149 offset:21504
	ds_read_b128 v[222:225], v149 offset:22528
	ds_read_b128 v[226:229], v149 offset:23552
	global_load_lds_dwordx4 v130, s[36:37]
	s_mov_b32 m0, s49
	s_addc_u32 s73, s37, 0
	global_load_lds_dwordx4 v134, s[36:37]
	s_mov_b32 m0, s50
	s_nop 0
	global_load_lds_dwordx4 v130, s[72:73]
	s_mov_b32 m0, s51
	s_nop 0
	global_load_lds_dwordx4 v134, s[72:73]
	s_mov_b32 m0, s47
	s_nop 0
	global_load_lds_dwordx4 v128, s[42:43]
	s_mov_b32 m0, s52
	s_nop 0
	global_load_lds_dwordx4 v132, s[42:43]
	s_waitcnt vmcnt(8)
	s_waitcnt lgkmcnt(0)
	s_barrier
	s_setprio 1
	s_waitcnt lgkmcnt(0)
	v_mfma_f32_16x16x32_bf16 v[60:63], v[144:147], v[198:201], v[60:63]
	v_mfma_f32_16x16x32_bf16 v[56:59], v[172:175], v[198:201], v[56:59]
	v_mfma_f32_16x16x32_bf16 v[44:47], v[144:147], v[206:209], v[44:47]
	v_mfma_f32_16x16x32_bf16 v[40:43], v[172:175], v[206:209], v[40:43]
	v_mfma_f32_16x16x32_bf16 v[28:31], v[144:147], v[214:217], v[28:31]
	v_mfma_f32_16x16x32_bf16 v[24:27], v[172:175], v[214:217], v[24:27]
	v_mfma_f32_16x16x32_bf16 v[12:15], v[144:147], v[222:225], v[12:15]
	v_mfma_f32_16x16x32_bf16 v[8:11], v[172:175], v[222:225], v[8:11]
	v_mfma_f32_16x16x32_bf16 v[60:63], v[168:171], v[202:205], v[60:63]
	v_mfma_f32_16x16x32_bf16 v[56:59], v[176:179], v[202:205], v[56:59]
	v_mfma_f32_16x16x32_bf16 v[44:47], v[168:171], v[210:213], v[44:47]
	v_mfma_f32_16x16x32_bf16 v[40:43], v[176:179], v[210:213], v[40:43]
	v_mfma_f32_16x16x32_bf16 v[28:31], v[168:171], v[218:221], v[28:31]
	v_mfma_f32_16x16x32_bf16 v[24:27], v[176:179], v[218:221], v[24:27]
	v_mfma_f32_16x16x32_bf16 v[12:15], v[168:171], v[226:229], v[12:15]
	v_mfma_f32_16x16x32_bf16 v[8:11], v[176:179], v[226:229], v[8:11]
	s_setprio 0
	s_setprio 1
	v_mfma_f32_16x16x32_bf16 v[52:55], v[180:183], v[198:201], v[52:55]
	v_mfma_f32_16x16x32_bf16 v[48:51], v[190:193], v[198:201], v[48:51]
	v_mfma_f32_16x16x32_bf16 v[36:39], v[180:183], v[206:209], v[36:39]
	v_mfma_f32_16x16x32_bf16 v[32:35], v[190:193], v[206:209], v[32:35]
	v_mfma_f32_16x16x32_bf16 v[20:23], v[180:183], v[214:217], v[20:23]
	v_mfma_f32_16x16x32_bf16 v[16:19], v[190:193], v[214:217], v[16:19]
	v_mfma_f32_16x16x32_bf16 v[4:7], v[180:183], v[222:225], v[4:7]
	v_mfma_f32_16x16x32_bf16 v[0:3], v[190:193], v[222:225], v[0:3]
	v_mfma_f32_16x16x32_bf16 v[52:55], v[186:189], v[202:205], v[52:55]
	v_mfma_f32_16x16x32_bf16 v[48:51], v[194:197], v[202:205], v[48:51]
	v_mfma_f32_16x16x32_bf16 v[36:39], v[186:189], v[210:213], v[36:39]
	v_mfma_f32_16x16x32_bf16 v[32:35], v[194:197], v[210:213], v[32:35]
	v_mfma_f32_16x16x32_bf16 v[20:23], v[186:189], v[218:221], v[20:23]
	v_mfma_f32_16x16x32_bf16 v[16:19], v[194:197], v[218:221], v[16:19]
	v_mfma_f32_16x16x32_bf16 v[4:7], v[186:189], v[226:229], v[4:7]
	v_mfma_f32_16x16x32_bf16 v[0:3], v[194:197], v[226:229], v[0:3]
	s_setprio 0
	s_barrier
; #define PG8_STAGE(bufoff, gbase, voff) do { _Pragma("unroll") for (int _i = 0; _i < 2; ++_i) \
;         __builtin_amdgcn_global_load_lds((const unsigned*)((const char*)(gbase) + (voff)[_i]), (PG8_LAS unsigned*)(lds + (bufoff) + ldsw + _i * 8192), 16, 0, 0); } while (0)
; #define PG8_LDA(dst, b, h) do { _Pragma("unroll") for (int m = 0; m < 4; ++m) _Pragma("unroll") for (int k = 0; k < 2; ++k) dst[m][k] = *(const PG8_LAS bf16x8*)(lds + PG8_SA(b, h) + aoff + m * 2048 + k * 1024); } while (0)
; #define PG8_LDB(dst, b, h) do { _Pragma("unroll") for (int n = 0; n < 2; ++n) _Pragma("unroll") for (int k = 0; k < 2; ++k) dst[n][k] = *(const PG8_LAS bf16x8*)(lds + PG8_SB(b, h) + boff + n * 2048 + k * 1024); } while (0)
; #define PG8_MMA(ai, bj, At, Bt) do { __builtin_amdgcn_s_setprio(1); _Pragma("unroll") for (int m = 0; m < 4; ++m) _Pragma("unroll") for (int n = 0; n < 2; ++n) _Pragma("unroll") for (int k = 0; k < 2; ++k) \
;         acc[ai][bj][m][n] = __builtin_amdgcn_mfma_f32_16x16x32_bf16(Bt[n][k], At[m][k], acc[ai][bj][m][n], 0, 0, 0); __builtin_amdgcn_s_setprio(0); } while (0)
; #define PG8_WAIT_V(n) asm volatile("s_waitcnt vmcnt(" #n ")" ::: "memory")
; #define PG8_WAIT_L(n) asm volatile("s_waitcnt lgkmcnt(" #n ")" ::: "memory")
; #define PG8_BAR __builtin_amdgcn_s_barrier()
; #define PG8_SCHED __builtin_amdgcn_sched_barrier(0)
; template <class Epi, class Sched, bool ALIGN_EPI = false, bool SP2 = false>
; __device__ __forceinline__ void gemm_phase(PG8_LAS unsigned char* lds, const Gemm g, const Sched& S, const Epi& E) {
;     ...
;         for (int t = 0; t < nt; t += 2) {
;     ...
;             PG8_LDB(B0, 1, 0); PG8_LDB(B1, 1, 1); PG8_SCHED; PG8_LDA(At, 1, 0); PG8_STAGE(PG8_SA(0, 1), a2 + hstep, voffA);
;             PG8_WAIT_V(8); PG8_WAIT_L(0); PG8_BAR; PG8_MMA(0, 0, At, B0); PG8_MMA(0, 1, At, B1); PG8_BAR; PG8_SCHED;
;             PG8_LDA(At, 1, 1); PG8_STAGE(PG8_SB(1, 0), b3, voffB); PG8_STAGE(PG8_SB(1, 1), b3 + hstep, voffB); PG8_STAGE(PG8_SA(1, 0), a3, voffA);
;             PG8_WAIT_V(8); PG8_WAIT_L(0); PG8_BAR; PG8_MMA(1, 0, At, B0); PG8_MMA(1, 1, At, B1); PG8_BAR; PG8_SCHED;
	ds_read_b128 v[144:147], v159
	ds_read_b128 v[168:171], v160
	ds_read_b128 v[172:175], v161
	ds_read_b128 v[176:179], v162
	ds_read_b128 v[180:183], v163
	ds_read_b128 v[186:189], v164
	ds_read_b128 v[190:193], v165
	ds_read_b128 v[194:197], v166
	s_add_u32 s42, s42, 0x40000
	s_addc_u32 s43, s43, 0
	s_mov_b32 m0, s53
	ds_read_b128 v[198:201], v149 offset:32768
	ds_read_b128 v[202:205], v149 offset:33792
	ds_read_b128 v[206:209], v149 offset:34816
	ds_read_b128 v[210:213], v149 offset:35840
	ds_read_b128 v[214:217], v149 offset:36864
	ds_read_b128 v[218:221], v149 offset:37888
	ds_read_b128 v[222:225], v149 offset:38912
	ds_read_b128 v[226:229], v149 offset:39936
	global_load_lds_dwordx4 v128, s[42:43]
	s_mov_b32 m0, s54
	s_nop 0
	global_load_lds_dwordx4 v132, s[42:43]
	s_waitcnt vmcnt(8)
	s_waitcnt lgkmcnt(0)
	s_barrier
	s_setprio 1
	s_waitcnt lgkmcnt(0)
	v_mfma_f32_16x16x32_bf16 v[124:127], v[144:147], v[198:201], v[124:127]
	v_mfma_f32_16x16x32_bf16 v[120:123], v[172:175], v[198:201], v[120:123]
	v_mfma_f32_16x16x32_bf16 v[108:111], v[144:147], v[206:209], v[108:111]
	v_mfma_f32_16x16x32_bf16 v[104:107], v[172:175], v[206:209], v[104:107]
	v_mfma_f32_16x16x32_bf16 v[92:95], v[144:147], v[214:217], v[92:95]
	v_mfma_f32_16x16x32_bf16 v[88:91], v[172:175], v[214:217], v[88:91]
	v_mfma_f32_16x16x32_bf16 v[76:79], v[144:147], v[222:225], v[76:79]
	v_mfma_f32_16x16x32_bf16 v[72:75], v[172:175], v[222:225], v[72:75]
	v_mfma_f32_16x16x32_bf16 v[124:127], v[168:171], v[202:205], v[124:127]
	v_mfma_f32_16x16x32_bf16 v[120:123], v[176:179], v[202:205], v[120:123]
	v_mfma_f32_16x16x32_bf16 v[108:111], v[168:171], v[210:213], v[108:111]
	v_mfma_f32_16x16x32_bf16 v[104:107], v[176:179], v[210:213], v[104:107]
	v_mfma_f32_16x16x32_bf16 v[92:95], v[168:171], v[218:221], v[92:95]
	v_mfma_f32_16x16x32_bf16 v[88:91], v[176:179], v[218:221], v[88:91]
	v_mfma_f32_16x16x32_bf16 v[76:79], v[168:171], v[226:229], v[76:79]
	v_mfma_f32_16x16x32_bf16 v[72:75], v[176:179], v[226:229], v[72:75]
	s_setprio 0
	s_setprio 1
	v_mfma_f32_16x16x32_bf16 v[116:119], v[180:183], v[198:201], v[116:119]
	v_mfma_f32_16x16x32_bf16 v[112:115], v[190:193], v[198:201], v[112:115]
	v_mfma_f32_16x16x32_bf16 v[100:103], v[180:183], v[206:209], v[100:103]
	v_mfma_f32_16x16x32_bf16 v[96:99], v[190:193], v[206:209], v[96:99]
	v_mfma_f32_16x16x32_bf16 v[84:87], v[180:183], v[214:217], v[84:87]
	v_mfma_f32_16x16x32_bf16 v[80:83], v[190:193], v[214:217], v[80:83]
	v_mfma_f32_16x16x32_bf16 v[68:71], v[180:183], v[222:225], v[68:71]
	v_mfma_f32_16x16x32_bf16 v[64:67], v[190:193], v[222:225], v[64:67]
	v_mfma_f32_16x16x32_bf16 v[116:119], v[186:189], v[202:205], v[116:119]
	v_mfma_f32_16x16x32_bf16 v[112:115], v[194:197], v[202:205], v[112:115]
	v_mfma_f32_16x16x32_bf16 v[100:103], v[186:189], v[210:213], v[100:103]
	v_mfma_f32_16x16x32_bf16 v[96:99], v[194:197], v[210:213], v[96:99]
	v_mfma_f32_16x16x32_bf16 v[84:87], v[186:189], v[218:221], v[84:87]
	v_mfma_f32_16x16x32_bf16 v[80:83], v[194:197], v[218:221], v[80:83]
	v_mfma_f32_16x16x32_bf16 v[68:71], v[186:189], v[226:229], v[68:71]
	v_mfma_f32_16x16x32_bf16 v[64:67], v[194:197], v[226:229], v[64:67]
	s_setprio 0
	s_barrier
	s_mov_b32 m0, s56
	s_add_u32 s36, s36, 0x40080
	ds_read_b128 v[198:201], v149 offset:49152
	ds_read_b128 v[202:205], v149 offset:50176
	ds_read_b128 v[206:209], v149 offset:51200
	ds_read_b128 v[210:213], v149 offset:52224
	ds_read_b128 v[214:217], v149 offset:53248
	ds_read_b128 v[218:221], v149 offset:54272
	ds_read_b128 v[222:225], v149 offset:55296
	ds_read_b128 v[226:229], v149 offset:56320
	global_load_lds_dwordx4 v130, s[88:89]
	s_mov_b32 m0, s57
	s_addc_u32 s37, s37, 0
	global_load_lds_dwordx4 v134, s[88:89]
	s_mov_b32 m0, s60
	s_nop 0
	global_load_lds_dwordx4 v130, s[36:37]
	s_mov_b32 m0, s61
	s_nop 0
	global_load_lds_dwordx4 v134, s[36:37]
	s_mov_b32 m0, s58
	s_nop 0
	global_load_lds_dwordx4 v128, s[90:91]
	s_mov_b32 m0, s59
	s_nop 0
	global_load_lds_dwordx4 v132, s[90:91]
	s_waitcnt vmcnt(8)
	s_waitcnt lgkmcnt(0)
	s_barrier
	s_setprio 1
	s_waitcnt lgkmcnt(0)
	v_mfma_f32_16x16x32_bf16 v[60:63], v[144:147], v[198:201], v[60:63]
	v_mfma_f32_16x16x32_bf16 v[56:59], v[172:175], v[198:201], v[56:59]
	v_mfma_f32_16x16x32_bf16 v[44:47], v[144:147], v[206:209], v[44:47]
	v_mfma_f32_16x16x32_bf16 v[40:43], v[172:175], v[206:209], v[40:43]
	v_mfma_f32_16x16x32_bf16 v[28:31], v[144:147], v[214:217], v[28:31]
	v_mfma_f32_16x16x32_bf16 v[24:27], v[172:175], v[214:217], v[24:27]
	v_mfma_f32_16x16x32_bf16 v[12:15], v[144:147], v[222:225], v[12:15]
	v_mfma_f32_16x16x32_bf16 v[8:11], v[172:175], v[222:225], v[8:11]
	v_mfma_f32_16x16x32_bf16 v[60:63], v[168:171], v[202:205], v[60:63]
	v_mfma_f32_16x16x32_bf16 v[56:59], v[176:179], v[202:205], v[56:59]
	v_mfma_f32_16x16x32_bf16 v[44:47], v[168:171], v[210:213], v[44:47]
	v_mfma_f32_16x16x32_bf16 v[40:43], v[176:179], v[210:213], v[40:43]
	v_mfma_f32_16x16x32_bf16 v[28:31], v[168:171], v[218:221], v[28:31]
	v_mfma_f32_16x16x32_bf16 v[24:27], v[176:179], v[218:221], v[24:27]
	v_mfma_f32_16x16x32_bf16 v[12:15], v[168:171], v[226:229], v[12:15]
	v_mfma_f32_16x16x32_bf16 v[8:11], v[176:179], v[226:229], v[8:11]
	s_setprio 0
	s_setprio 1
	v_mfma_f32_16x16x32_bf16 v[52:55], v[180:183], v[198:201], v[52:55]
	v_mfma_f32_16x16x32_bf16 v[48:51], v[190:193], v[198:201], v[48:51]
	v_mfma_f32_16x16x32_bf16 v[36:39], v[180:183], v[206:209], v[36:39]
	v_mfma_f32_16x16x32_bf16 v[32:35], v[190:193], v[206:209], v[32:35]
	v_mfma_f32_16x16x32_bf16 v[20:23], v[180:183], v[214:217], v[20:23]
	v_mfma_f32_16x16x32_bf16 v[16:19], v[190:193], v[214:217], v[16:19]
	v_mfma_f32_16x16x32_bf16 v[4:7], v[180:183], v[222:225], v[4:7]
	v_mfma_f32_16x16x32_bf16 v[0:3], v[190:193], v[222:225], v[0:3]
	v_mfma_f32_16x16x32_bf16 v[52:55], v[186:189], v[202:205], v[52:55]
	v_mfma_f32_16x16x32_bf16 v[48:51], v[194:197], v[202:205], v[48:51]
	v_mfma_f32_16x16x32_bf16 v[36:39], v[186:189], v[210:213], v[36:39]
	v_mfma_f32_16x16x32_bf16 v[32:35], v[194:197], v[210:213], v[32:35]
	v_mfma_f32_16x16x32_bf16 v[20:23], v[186:189], v[218:221], v[20:23]
	v_mfma_f32_16x16x32_bf16 v[16:19], v[194:197], v[218:221], v[16:19]
	v_mfma_f32_16x16x32_bf16 v[4:7], v[186:189], v[226:229], v[4:7]
	v_mfma_f32_16x16x32_bf16 v[0:3], v[194:197], v[226:229], v[0:3]
	s_setprio 0
	s_barrier
	s_add_i32 s70, s70, 2
	s_add_u32 s68, s68, 0x100
	s_addc_u32 s69, s69, 0
	s_add_u32 s34, s34, 0x100
	s_addc_u32 s35, s35, 0
	s_cmp_gt_u32 s70, 13
	s_cbranch_scc0 .LBB0_390
	s_and_b64 vcc, exec, s[18:19]
	s_cbranch_vccz .LBB0_393
	s_barrier

; #define PG8_STAGE(bufoff, gbase, voff) do { _Pragma("unroll") for (int _i = 0; _i < 2; ++_i) \
;         __builtin_amdgcn_global_load_lds((const unsigned*)((const char*)(gbase) + (voff)[_i]), (PG8_LAS unsigned*)(lds + (bufoff) + ldsw + _i * 8192), 16, 0, 0); } while (0)
; #define PG8_LDA(dst, b, h) do { _Pragma("unroll") for (int m = 0; m < 4; ++m) _Pragma("unroll") for (int k = 0; k < 2; ++k) dst[m][k] = *(const PG8_LAS bf16x8*)(lds + PG8_SA(b, h) + aoff + m * 2048 + k * 1024); } while (0)
; #define PG8_LDB(dst, b, h) do { _Pragma("unroll") for (int n = 0; n < 2; ++n) _Pragma("unroll") for (int k = 0; k < 2; ++k) dst[n][k] = *(const PG8_LAS bf16x8*)(lds + PG8_SB(b, h) + boff + n * 2048 + k * 1024); } while (0)
; #define PG8_MMA(ai, bj, At, Bt) do { __builtin_amdgcn_s_setprio(1); _Pragma("unroll") for (int m = 0; m < 4; ++m) _Pragma("unroll") for (int n = 0; n < 2; ++n) _Pragma("unroll") for (int k = 0; k < 2; ++k) \
;         acc[ai][bj][m][n] = __builtin_amdgcn_mfma_f32_16x16x32_bf16(Bt[n][k], At[m][k], acc[ai][bj][m][n], 0, 0, 0); __builtin_amdgcn_s_setprio(0); } while (0)
; #define PG8_WAIT_V(n) asm volatile("s_waitcnt vmcnt(" #n ")" ::: "memory")
; #define PG8_WAIT_L(n) asm volatile("s_waitcnt lgkmcnt(" #n ")" ::: "memory")
; #define PG8_BAR __builtin_amdgcn_s_barrier()
; #define PG8_SCHED __builtin_amdgcn_sched_barrier(0)
; template <class Epi, class Sched, bool ALIGN_EPI = false, bool SP2 = false>
; __device__ __forceinline__ void gemm_phase(PG8_LAS unsigned char* lds, const Gemm g, const Sched& S, const Epi& E) {
;     ...
;             PG8_LDB(B0, 0, 0); PG8_LDB(B1, 0, 1); PG8_SCHED; PG8_LDA(At, 0, 0); PG8_STAGE(PG8_SA(1, 1), a1 + hstep, voffA);
;             PG8_WAIT_V(8); PG8_WAIT_L(0); PG8_BAR; PG8_MMA(0, 0, At, B0); PG8_MMA(0, 1, At, B1); PG8_BAR; PG8_SCHED;
;             PG8_LDA(At, 0, 1); PG8_STAGE(PG8_SB(0, 0), b2, voffB); PG8_STAGE(PG8_SB(0, 1), b2 + hstep, voffB); PG8_STAGE(PG8_SA(0, 0), a2, voffA);
;             PG8_WAIT_V(8); PG8_WAIT_L(0); PG8_BAR; PG8_MMA(1, 0, At, B0); PG8_MMA(1, 1, At, B1); PG8_BAR; PG8_SCHED;
.LBB0_477:
	ds_read_b128 v[144:147], v151
	ds_read_b128 v[170:173], v152
	ds_read_b128 v[174:177], v153
	ds_read_b128 v[178:181], v154
	ds_read_b128 v[186:189], v155
	ds_read_b128 v[190:193], v156
	ds_read_b128 v[194:197], v157
	ds_read_b128 v[198:201], v158
	s_add_u32 s30, s28, 0xfffc0080
	s_addc_u32 s31, s29, -1
	s_cmp_eq_u32 s67, 12
	s_cselect_b32 s35, s23, s31
	s_cselect_b32 s34, s63, s30
	s_cselect_b32 s31, s21, s66
	s_cselect_b32 s30, s64, s65
	s_mov_b32 m0, s60
	ds_read_b128 v[202:205], v149
	ds_read_b128 v[206:209], v149 offset:1024
	ds_read_b128 v[210:213], v149 offset:2048
	ds_read_b128 v[214:217], v149 offset:3072
	ds_read_b128 v[218:221], v149 offset:4096
	ds_read_b128 v[222:225], v149 offset:5120
	ds_read_b128 v[226:229], v149 offset:6144
	ds_read_b128 v[230:233], v149 offset:7168
	global_load_lds_dwordx4 v138, s[28:29]
	s_mov_b32 m0, s61
	s_nop 0
	global_load_lds_dwordx4 v136, s[28:29]
	s_waitcnt vmcnt(8)
	s_waitcnt lgkmcnt(0)
	s_barrier
	s_setprio 1
	s_waitcnt lgkmcnt(0)
	v_mfma_f32_16x16x32_bf16 v[124:127], v[144:147], v[202:205], v[124:127]
	v_mfma_f32_16x16x32_bf16 v[120:123], v[174:177], v[202:205], v[120:123]
	v_mfma_f32_16x16x32_bf16 v[108:111], v[144:147], v[210:213], v[108:111]
	v_mfma_f32_16x16x32_bf16 v[104:107], v[174:177], v[210:213], v[104:107]
	v_mfma_f32_16x16x32_bf16 v[92:95], v[144:147], v[218:221], v[92:95]
	v_mfma_f32_16x16x32_bf16 v[88:91], v[174:177], v[218:221], v[88:91]
	v_mfma_f32_16x16x32_bf16 v[76:79], v[144:147], v[226:229], v[76:79]
	v_mfma_f32_16x16x32_bf16 v[72:75], v[174:177], v[226:229], v[72:75]
	v_mfma_f32_16x16x32_bf16 v[124:127], v[170:173], v[206:209], v[124:127]
	v_mfma_f32_16x16x32_bf16 v[120:123], v[178:181], v[206:209], v[120:123]
	v_mfma_f32_16x16x32_bf16 v[108:111], v[170:173], v[214:217], v[108:111]
	v_mfma_f32_16x16x32_bf16 v[104:107], v[178:181], v[214:217], v[104:107]
	v_mfma_f32_16x16x32_bf16 v[92:95], v[170:173], v[222:225], v[92:95]
	v_mfma_f32_16x16x32_bf16 v[88:91], v[178:181], v[222:225], v[88:91]
	v_mfma_f32_16x16x32_bf16 v[76:79], v[170:173], v[230:233], v[76:79]
	v_mfma_f32_16x16x32_bf16 v[72:75], v[178:181], v[230:233], v[72:75]
	s_setprio 0
	s_setprio 1
	v_mfma_f32_16x16x32_bf16 v[116:119], v[186:189], v[202:205], v[116:119]
	v_mfma_f32_16x16x32_bf16 v[112:115], v[194:197], v[202:205], v[112:115]
	v_mfma_f32_16x16x32_bf16 v[100:103], v[186:189], v[210:213], v[100:103]
	v_mfma_f32_16x16x32_bf16 v[96:99], v[194:197], v[210:213], v[96:99]
	v_mfma_f32_16x16x32_bf16 v[84:87], v[186:189], v[218:221], v[84:87]
	v_mfma_f32_16x16x32_bf16 v[80:83], v[194:197], v[218:221], v[80:83]
	v_mfma_f32_16x16x32_bf16 v[68:71], v[186:189], v[226:229], v[68:71]
	v_mfma_f32_16x16x32_bf16 v[64:67], v[194:197], v[226:229], v[64:67]
	v_mfma_f32_16x16x32_bf16 v[116:119], v[190:193], v[206:209], v[116:119]
	v_mfma_f32_16x16x32_bf16 v[112:115], v[198:201], v[206:209], v[112:115]
	v_mfma_f32_16x16x32_bf16 v[100:103], v[190:193], v[214:217], v[100:103]
	v_mfma_f32_16x16x32_bf16 v[96:99], v[198:201], v[214:217], v[96:99]
	v_mfma_f32_16x16x32_bf16 v[84:87], v[190:193], v[222:225], v[84:87]
	v_mfma_f32_16x16x32_bf16 v[80:83], v[198:201], v[222:225], v[80:83]
	v_mfma_f32_16x16x32_bf16 v[68:71], v[190:193], v[230:233], v[68:71]
	v_mfma_f32_16x16x32_bf16 v[64:67], v[198:201], v[230:233], v[64:67]
	s_setprio 0
	s_barrier
	s_add_u32 s88, s30, 0x80
	s_addc_u32 s89, s31, 0
	s_add_u32 s90, s34, 0x80
	s_addc_u32 s91, s35, 0
	s_mov_b32 m0, s44
	s_add_u32 s68, s30, 0x40000
	ds_read_b128 v[202:205], v149 offset:16384
	ds_read_b128 v[206:209], v149 offset:17408
	ds_read_b128 v[210:213], v149 offset:18432
	ds_read_b128 v[214:217], v149 offset:19456
	ds_read_b128 v[218:221], v149 offset:20480
	ds_read_b128 v[222:225], v149 offset:21504
	ds_read_b128 v[226:229], v149 offset:22528
	ds_read_b128 v[230:233], v149 offset:23552
	global_load_lds_dwordx4 v132, s[30:31]
	s_mov_b32 m0, s45
	s_addc_u32 s69, s31, 0
	global_load_lds_dwordx4 v128, s[30:31]
	s_mov_b32 m0, s46
	s_nop 0
	global_load_lds_dwordx4 v132, s[68:69]
	s_mov_b32 m0, s47
	s_nop 0
	global_load_lds_dwordx4 v128, s[68:69]
	s_mov_b32 m0, s42
	s_nop 0
	global_load_lds_dwordx4 v134, s[34:35]
	s_mov_b32 m0, s48
	s_nop 0
	global_load_lds_dwordx4 v130, s[34:35]
	s_waitcnt vmcnt(8)
	s_waitcnt lgkmcnt(0)
	s_barrier
	s_setprio 1
	s_waitcnt lgkmcnt(0)
	v_mfma_f32_16x16x32_bf16 v[60:63], v[144:147], v[202:205], v[60:63]
	v_mfma_f32_16x16x32_bf16 v[56:59], v[174:177], v[202:205], v[56:59]
	v_mfma_f32_16x16x32_bf16 v[44:47], v[144:147], v[210:213], v[44:47]
	v_mfma_f32_16x16x32_bf16 v[40:43], v[174:177], v[210:213], v[40:43]
	v_mfma_f32_16x16x32_bf16 v[28:31], v[144:147], v[218:221], v[28:31]
	v_mfma_f32_16x16x32_bf16 v[24:27], v[174:177], v[218:221], v[24:27]
	v_mfma_f32_16x16x32_bf16 v[12:15], v[144:147], v[226:229], v[12:15]
	v_mfma_f32_16x16x32_bf16 v[8:11], v[174:177], v[226:229], v[8:11]
	v_mfma_f32_16x16x32_bf16 v[60:63], v[170:173], v[206:209], v[60:63]
	v_mfma_f32_16x16x32_bf16 v[56:59], v[178:181], v[206:209], v[56:59]
	v_mfma_f32_16x16x32_bf16 v[44:47], v[170:173], v[214:217], v[44:47]
	v_mfma_f32_16x16x32_bf16 v[40:43], v[178:181], v[214:217], v[40:43]
	v_mfma_f32_16x16x32_bf16 v[28:31], v[170:173], v[222:225], v[28:31]
	v_mfma_f32_16x16x32_bf16 v[24:27], v[178:181], v[222:225], v[24:27]
	v_mfma_f32_16x16x32_bf16 v[12:15], v[170:173], v[230:233], v[12:15]
	v_mfma_f32_16x16x32_bf16 v[8:11], v[178:181], v[230:233], v[8:11]
	s_setprio 0
	s_setprio 1
	v_mfma_f32_16x16x32_bf16 v[52:55], v[186:189], v[202:205], v[52:55]
	v_mfma_f32_16x16x32_bf16 v[48:51], v[194:197], v[202:205], v[48:51]
	v_mfma_f32_16x16x32_bf16 v[36:39], v[186:189], v[210:213], v[36:39]
	v_mfma_f32_16x16x32_bf16 v[32:35], v[194:197], v[210:213], v[32:35]
	v_mfma_f32_16x16x32_bf16 v[20:23], v[186:189], v[218:221], v[20:23]
	v_mfma_f32_16x16x32_bf16 v[16:19], v[194:197], v[218:221], v[16:19]
	v_mfma_f32_16x16x32_bf16 v[4:7], v[186:189], v[226:229], v[4:7]
	v_mfma_f32_16x16x32_bf16 v[0:3], v[194:197], v[226:229], v[0:3]
	v_mfma_f32_16x16x32_bf16 v[52:55], v[190:193], v[206:209], v[52:55]
	v_mfma_f32_16x16x32_bf16 v[48:51], v[198:201], v[206:209], v[48:51]
	v_mfma_f32_16x16x32_bf16 v[36:39], v[190:193], v[214:217], v[36:39]
	v_mfma_f32_16x16x32_bf16 v[32:35], v[198:201], v[214:217], v[32:35]
	v_mfma_f32_16x16x32_bf16 v[20:23], v[190:193], v[222:225], v[20:23]
	v_mfma_f32_16x16x32_bf16 v[16:19], v[198:201], v[222:225], v[16:19]
	v_mfma_f32_16x16x32_bf16 v[4:7], v[190:193], v[230:233], v[4:7]
	v_mfma_f32_16x16x32_bf16 v[0:3], v[198:201], v[230:233], v[0:3]
	s_setprio 0
	s_barrier
; #define PG8_STAGE(bufoff, gbase, voff) do { _Pragma("unroll") for (int _i = 0; _i < 2; ++_i) \
;         __builtin_amdgcn_global_load_lds((const unsigned*)((const char*)(gbase) + (voff)[_i]), (PG8_LAS unsigned*)(lds + (bufoff) + ldsw + _i * 8192), 16, 0, 0); } while (0)
; #define PG8_LDA(dst, b, h) do { _Pragma("unroll") for (int m = 0; m < 4; ++m) _Pragma("unroll") for (int k = 0; k < 2; ++k) dst[m][k] = *(const PG8_LAS bf16x8*)(lds + PG8_SA(b, h) + aoff + m * 2048 + k * 1024); } while (0)
; #define PG8_LDB(dst, b, h) do { _Pragma("unroll") for (int n = 0; n < 2; ++n) _Pragma("unroll") for (int k = 0; k < 2; ++k) dst[n][k] = *(const PG8_LAS bf16x8*)(lds + PG8_SB(b, h) + boff + n * 2048 + k * 1024); } while (0)
; #define PG8_MMA(ai, bj, At, Bt) do { __builtin_amdgcn_s_setprio(1); _Pragma("unroll") for (int m = 0; m < 4; ++m) _Pragma("unroll") for (int n = 0; n < 2; ++n) _Pragma("unroll") for (int k = 0; k < 2; ++k) \
;         acc[ai][bj][m][n] = __builtin_amdgcn_mfma_f32_16x16x32_bf16(Bt[n][k], At[m][k], acc[ai][bj][m][n], 0, 0, 0); __builtin_amdgcn_s_setprio(0); } while (0)
; #define PG8_WAIT_V(n) asm volatile("s_waitcnt vmcnt(" #n ")" ::: "memory")
; #define PG8_WAIT_L(n) asm volatile("s_waitcnt lgkmcnt(" #n ")" ::: "memory")
; #define PG8_BAR __builtin_amdgcn_s_barrier()
; #define PG8_SCHED __builtin_amdgcn_sched_barrier(0)
; template <class Epi, class Sched, bool ALIGN_EPI = false, bool SP2 = false>
; __device__ __forceinline__ void gemm_phase(PG8_LAS unsigned char* lds, const Gemm g, const Sched& S, const Epi& E) {
;     ...
;         for (int t = 0; t < nt; t += 2) {
;     ...
;             PG8_LDB(B0, 1, 0); PG8_LDB(B1, 1, 1); PG8_SCHED; PG8_LDA(At, 1, 0); PG8_STAGE(PG8_SA(0, 1), a2 + hstep, voffA);
;             PG8_WAIT_V(8); PG8_WAIT_L(0); PG8_BAR; PG8_MMA(0, 0, At, B0); PG8_MMA(0, 1, At, B1); PG8_BAR; PG8_SCHED;
;             PG8_LDA(At, 1, 1); PG8_STAGE(PG8_SB(1, 0), b3, voffB); PG8_STAGE(PG8_SB(1, 1), b3 + hstep, voffB); PG8_STAGE(PG8_SA(1, 0), a3, voffA);
;             PG8_WAIT_V(8); PG8_WAIT_L(0); PG8_BAR; PG8_MMA(1, 0, At, B0); PG8_MMA(1, 1, At, B1); PG8_BAR; PG8_SCHED;
	ds_read_b128 v[144:147], v159
	ds_read_b128 v[170:173], v160
	ds_read_b128 v[174:177], v161
	ds_read_b128 v[178:181], v162
	ds_read_b128 v[186:189], v163
	ds_read_b128 v[190:193], v164
	ds_read_b128 v[194:197], v165
	ds_read_b128 v[198:201], v166
	s_add_u32 s34, s34, 0x40000
	s_addc_u32 s35, s35, 0
	s_mov_b32 m0, s49
	ds_read_b128 v[202:205], v149 offset:32768
	ds_read_b128 v[206:209], v149 offset:33792
	ds_read_b128 v[210:213], v149 offset:34816
	ds_read_b128 v[214:217], v149 offset:35840
	ds_read_b128 v[218:221], v149 offset:36864
	ds_read_b128 v[222:225], v149 offset:37888
	ds_read_b128 v[226:229], v149 offset:38912
	ds_read_b128 v[230:233], v149 offset:39936
	global_load_lds_dwordx4 v134, s[34:35]
	s_mov_b32 m0, s50
	s_nop 0
	global_load_lds_dwordx4 v130, s[34:35]
	s_waitcnt vmcnt(8)
	s_waitcnt lgkmcnt(0)
	s_barrier
	s_setprio 1
	s_waitcnt lgkmcnt(0)
	v_mfma_f32_16x16x32_bf16 v[124:127], v[144:147], v[202:205], v[124:127]
	v_mfma_f32_16x16x32_bf16 v[120:123], v[174:177], v[202:205], v[120:123]
	v_mfma_f32_16x16x32_bf16 v[108:111], v[144:147], v[210:213], v[108:111]
	v_mfma_f32_16x16x32_bf16 v[104:107], v[174:177], v[210:213], v[104:107]
	v_mfma_f32_16x16x32_bf16 v[92:95], v[144:147], v[218:221], v[92:95]
	v_mfma_f32_16x16x32_bf16 v[88:91], v[174:177], v[218:221], v[88:91]
	v_mfma_f32_16x16x32_bf16 v[76:79], v[144:147], v[226:229], v[76:79]
	v_mfma_f32_16x16x32_bf16 v[72:75], v[174:177], v[226:229], v[72:75]
	v_mfma_f32_16x16x32_bf16 v[124:127], v[170:173], v[206:209], v[124:127]
	v_mfma_f32_16x16x32_bf16 v[120:123], v[178:181], v[206:209], v[120:123]
	v_mfma_f32_16x16x32_bf16 v[108:111], v[170:173], v[214:217], v[108:111]
	v_mfma_f32_16x16x32_bf16 v[104:107], v[178:181], v[214:217], v[104:107]
	v_mfma_f32_16x16x32_bf16 v[92:95], v[170:173], v[222:225], v[92:95]
	v_mfma_f32_16x16x32_bf16 v[88:91], v[178:181], v[222:225], v[88:91]
	v_mfma_f32_16x16x32_bf16 v[76:79], v[170:173], v[230:233], v[76:79]
	v_mfma_f32_16x16x32_bf16 v[72:75], v[178:181], v[230:233], v[72:75]
	s_setprio 0
	s_setprio 1
	v_mfma_f32_16x16x32_bf16 v[116:119], v[186:189], v[202:205], v[116:119]
	v_mfma_f32_16x16x32_bf16 v[112:115], v[194:197], v[202:205], v[112:115]
	v_mfma_f32_16x16x32_bf16 v[100:103], v[186:189], v[210:213], v[100:103]
	v_mfma_f32_16x16x32_bf16 v[96:99], v[194:197], v[210:213], v[96:99]
	v_mfma_f32_16x16x32_bf16 v[84:87], v[186:189], v[218:221], v[84:87]
	v_mfma_f32_16x16x32_bf16 v[80:83], v[194:197], v[218:221], v[80:83]
	v_mfma_f32_16x16x32_bf16 v[68:71], v[186:189], v[226:229], v[68:71]
	v_mfma_f32_16x16x32_bf16 v[64:67], v[194:197], v[226:229], v[64:67]
	v_mfma_f32_16x16x32_bf16 v[116:119], v[190:193], v[206:209], v[116:119]
	v_mfma_f32_16x16x32_bf16 v[112:115], v[198:201], v[206:209], v[112:115]
	v_mfma_f32_16x16x32_bf16 v[100:103], v[190:193], v[214:217], v[100:103]
	v_mfma_f32_16x16x32_bf16 v[96:99], v[198:201], v[214:217], v[96:99]
	v_mfma_f32_16x16x32_bf16 v[84:87], v[190:193], v[222:225], v[84:87]
	v_mfma_f32_16x16x32_bf16 v[80:83], v[198:201], v[222:225], v[80:83]
	v_mfma_f32_16x16x32_bf16 v[68:71], v[190:193], v[230:233], v[68:71]
	v_mfma_f32_16x16x32_bf16 v[64:67], v[198:201], v[230:233], v[64:67]
	s_setprio 0
	s_barrier
	s_mov_b32 m0, s53
	s_add_u32 s30, s30, 0x40080
	ds_read_b128 v[202:205], v149 offset:49152
	ds_read_b128 v[206:209], v149 offset:50176
	ds_read_b128 v[210:213], v149 offset:51200
	ds_read_b128 v[214:217], v149 offset:52224
	ds_read_b128 v[218:221], v149 offset:53248
	ds_read_b128 v[222:225], v149 offset:54272
	ds_read_b128 v[226:229], v149 offset:55296
	ds_read_b128 v[230:233], v149 offset:56320
	global_load_lds_dwordx4 v132, s[88:89]
	s_mov_b32 m0, s54
	s_addc_u32 s31, s31, 0
	global_load_lds_dwordx4 v128, s[88:89]
	s_mov_b32 m0, s57
	s_nop 0
	global_load_lds_dwordx4 v132, s[30:31]
	s_mov_b32 m0, s58
	s_nop 0
	global_load_lds_dwordx4 v128, s[30:31]
	s_mov_b32 m0, s55
	s_nop 0
	global_load_lds_dwordx4 v134, s[90:91]
	s_mov_b32 m0, s56
	s_nop 0
	global_load_lds_dwordx4 v130, s[90:91]
	s_waitcnt vmcnt(8)
	s_waitcnt lgkmcnt(0)
	s_barrier
	s_setprio 1
	s_waitcnt lgkmcnt(0)
	v_mfma_f32_16x16x32_bf16 v[60:63], v[144:147], v[202:205], v[60:63]
	v_mfma_f32_16x16x32_bf16 v[56:59], v[174:177], v[202:205], v[56:59]
	v_mfma_f32_16x16x32_bf16 v[44:47], v[144:147], v[210:213], v[44:47]
	v_mfma_f32_16x16x32_bf16 v[40:43], v[174:177], v[210:213], v[40:43]
	v_mfma_f32_16x16x32_bf16 v[28:31], v[144:147], v[218:221], v[28:31]
	v_mfma_f32_16x16x32_bf16 v[24:27], v[174:177], v[218:221], v[24:27]
	v_mfma_f32_16x16x32_bf16 v[12:15], v[144:147], v[226:229], v[12:15]
	v_mfma_f32_16x16x32_bf16 v[8:11], v[174:177], v[226:229], v[8:11]
	v_mfma_f32_16x16x32_bf16 v[60:63], v[170:173], v[206:209], v[60:63]
	v_mfma_f32_16x16x32_bf16 v[56:59], v[178:181], v[206:209], v[56:59]
	v_mfma_f32_16x16x32_bf16 v[44:47], v[170:173], v[214:217], v[44:47]
	v_mfma_f32_16x16x32_bf16 v[40:43], v[178:181], v[214:217], v[40:43]
	v_mfma_f32_16x16x32_bf16 v[28:31], v[170:173], v[222:225], v[28:31]
	v_mfma_f32_16x16x32_bf16 v[24:27], v[178:181], v[222:225], v[24:27]
	v_mfma_f32_16x16x32_bf16 v[12:15], v[170:173], v[230:233], v[12:15]
	v_mfma_f32_16x16x32_bf16 v[8:11], v[178:181], v[230:233], v[8:11]
	s_setprio 0
	s_setprio 1
	v_mfma_f32_16x16x32_bf16 v[52:55], v[186:189], v[202:205], v[52:55]
	v_mfma_f32_16x16x32_bf16 v[48:51], v[194:197], v[202:205], v[48:51]
	v_mfma_f32_16x16x32_bf16 v[36:39], v[186:189], v[210:213], v[36:39]
	v_mfma_f32_16x16x32_bf16 v[32:35], v[194:197], v[210:213], v[32:35]
	v_mfma_f32_16x16x32_bf16 v[20:23], v[186:189], v[218:221], v[20:23]
	v_mfma_f32_16x16x32_bf16 v[16:19], v[194:197], v[218:221], v[16:19]
	v_mfma_f32_16x16x32_bf16 v[4:7], v[186:189], v[226:229], v[4:7]
	v_mfma_f32_16x16x32_bf16 v[0:3], v[194:197], v[226:229], v[0:3]
	v_mfma_f32_16x16x32_bf16 v[52:55], v[190:193], v[206:209], v[52:55]
	v_mfma_f32_16x16x32_bf16 v[48:51], v[198:201], v[206:209], v[48:51]
	v_mfma_f32_16x16x32_bf16 v[36:39], v[190:193], v[214:217], v[36:39]
	v_mfma_f32_16x16x32_bf16 v[32:35], v[198:201], v[214:217], v[32:35]
	v_mfma_f32_16x16x32_bf16 v[20:23], v[190:193], v[222:225], v[20:23]
	v_mfma_f32_16x16x32_bf16 v[16:19], v[198:201], v[222:225], v[16:19]
	v_mfma_f32_16x16x32_bf16 v[4:7], v[190:193], v[230:233], v[4:7]
	v_mfma_f32_16x16x32_bf16 v[0:3], v[198:201], v[230:233], v[0:3]
	s_setprio 0
	s_barrier
	s_add_i32 s67, s67, 2
	s_add_u32 s65, s65, 0x100
	s_addc_u32 s66, s66, 0
	s_add_u32 s28, s28, 0x100
	s_addc_u32 s29, s29, 0
	s_cmp_gt_u32 s67, 13
	s_cbranch_scc0 .LBB0_477
	s_and_b64 vcc, exec, s[18:19]
	s_cbranch_vccz .LBB0_480
	s_barrier

; #define PG8_STAGE(bufoff, gbase, voff) do { _Pragma("unroll") for (int _i = 0; _i < 2; ++_i) \
;         __builtin_amdgcn_global_load_lds((const unsigned*)((const char*)(gbase) + (voff)[_i]), (PG8_LAS unsigned*)(lds + (bufoff) + ldsw + _i * 8192), 16, 0, 0); } while (0)
; #define PG8_LDA(dst, b, h) do { _Pragma("unroll") for (int m = 0; m < 4; ++m) _Pragma("unroll") for (int k = 0; k < 2; ++k) dst[m][k] = *(const PG8_LAS bf16x8*)(lds + PG8_SA(b, h) + aoff + m * 2048 + k * 1024); } while (0)
; #define PG8_LDB(dst, b, h) do { _Pragma("unroll") for (int n = 0; n < 2; ++n) _Pragma("unroll") for (int k = 0; k < 2; ++k) dst[n][k] = *(const PG8_LAS bf16x8*)(lds + PG8_SB(b, h) + boff + n * 2048 + k * 1024); } while (0)
; #define PG8_MMA(ai, bj, At, Bt) do { __builtin_amdgcn_s_setprio(1); _Pragma("unroll") for (int m = 0; m < 4; ++m) _Pragma("unroll") for (int n = 0; n < 2; ++n) _Pragma("unroll") for (int k = 0; k < 2; ++k) \
;         acc[ai][bj][m][n] = __builtin_amdgcn_mfma_f32_16x16x32_bf16(Bt[n][k], At[m][k], acc[ai][bj][m][n], 0, 0, 0); __builtin_amdgcn_s_setprio(0); } while (0)
; #define PG8_WAIT_V(n) asm volatile("s_waitcnt vmcnt(" #n ")" ::: "memory")
; #define PG8_WAIT_L(n) asm volatile("s_waitcnt lgkmcnt(" #n ")" ::: "memory")
; #define PG8_BAR __builtin_amdgcn_s_barrier()
; #define PG8_SCHED __builtin_amdgcn_sched_barrier(0)
; template <class Epi, class Sched, bool ALIGN_EPI = false, bool SP2 = false>
; __device__ __forceinline__ void gemm_phase(PG8_LAS unsigned char* lds, const Gemm g, const Sched& S, const Epi& E) {
;     ...
;             PG8_LDB(B0, 0, 0); PG8_LDB(B1, 0, 1); PG8_SCHED; PG8_LDA(At, 0, 0); PG8_STAGE(PG8_SA(1, 1), a1 + hstep, voffA);
;             PG8_WAIT_V(8); PG8_WAIT_L(0); PG8_BAR; PG8_MMA(0, 0, At, B0); PG8_MMA(0, 1, At, B1); PG8_BAR; PG8_SCHED;
;             PG8_LDA(At, 0, 1); PG8_STAGE(PG8_SB(0, 0), b2, voffB); PG8_STAGE(PG8_SB(0, 1), b2 + hstep, voffB); PG8_STAGE(PG8_SA(0, 0), a2, voffA);
;             PG8_WAIT_V(8); PG8_WAIT_L(0); PG8_BAR; PG8_MMA(1, 0, At, B0); PG8_MMA(1, 1, At, B1); PG8_BAR; PG8_SCHED;
.LBB0_558:
	ds_read_b128 v[144:147], v151
	ds_read_b128 v[168:171], v152
	ds_read_b128 v[172:175], v153
	ds_read_b128 v[176:179], v154
	ds_read_b128 v[180:183], v155
	ds_read_b128 v[186:189], v156
	ds_read_b128 v[190:193], v157
	ds_read_b128 v[194:197], v158
	s_add_u32 s36, s34, 0xfff00080
	s_addc_u32 s37, s35, -1
	s_cmp_eq_u32 s70, 60
	s_cselect_b32 s43, s25, s37
	s_cselect_b32 s42, s31, s36
	s_cselect_b32 s37, s23, s69
	s_cselect_b32 s36, s67, s68
	s_mov_b32 m0, s64
	ds_read_b128 v[198:201], v149
	ds_read_b128 v[202:205], v149 offset:1024
	ds_read_b128 v[206:209], v149 offset:2048
	ds_read_b128 v[210:213], v149 offset:3072
	ds_read_b128 v[214:217], v149 offset:4096
	ds_read_b128 v[218:221], v149 offset:5120
	ds_read_b128 v[222:225], v149 offset:6144
	ds_read_b128 v[226:229], v149 offset:7168
	global_load_lds_dwordx4 v138, s[34:35]
	s_mov_b32 m0, s65
	s_nop 0
	global_load_lds_dwordx4 v136, s[34:35]
	s_waitcnt vmcnt(8)
	s_waitcnt lgkmcnt(0)
	s_barrier
	s_setprio 1
	s_waitcnt lgkmcnt(0)
	v_mfma_f32_16x16x32_bf16 v[124:127], v[144:147], v[198:201], v[124:127]
	v_mfma_f32_16x16x32_bf16 v[120:123], v[172:175], v[198:201], v[120:123]
	v_mfma_f32_16x16x32_bf16 v[108:111], v[144:147], v[206:209], v[108:111]
	v_mfma_f32_16x16x32_bf16 v[104:107], v[172:175], v[206:209], v[104:107]
	v_mfma_f32_16x16x32_bf16 v[92:95], v[144:147], v[214:217], v[92:95]
	v_mfma_f32_16x16x32_bf16 v[88:91], v[172:175], v[214:217], v[88:91]
	v_mfma_f32_16x16x32_bf16 v[76:79], v[144:147], v[222:225], v[76:79]
	v_mfma_f32_16x16x32_bf16 v[72:75], v[172:175], v[222:225], v[72:75]
	v_mfma_f32_16x16x32_bf16 v[124:127], v[168:171], v[202:205], v[124:127]
	v_mfma_f32_16x16x32_bf16 v[120:123], v[176:179], v[202:205], v[120:123]
	v_mfma_f32_16x16x32_bf16 v[108:111], v[168:171], v[210:213], v[108:111]
	v_mfma_f32_16x16x32_bf16 v[104:107], v[176:179], v[210:213], v[104:107]
	v_mfma_f32_16x16x32_bf16 v[92:95], v[168:171], v[218:221], v[92:95]
	v_mfma_f32_16x16x32_bf16 v[88:91], v[176:179], v[218:221], v[88:91]
	v_mfma_f32_16x16x32_bf16 v[76:79], v[168:171], v[226:229], v[76:79]
	v_mfma_f32_16x16x32_bf16 v[72:75], v[176:179], v[226:229], v[72:75]
	s_setprio 0
	s_setprio 1
	v_mfma_f32_16x16x32_bf16 v[116:119], v[180:183], v[198:201], v[116:119]
	v_mfma_f32_16x16x32_bf16 v[112:115], v[190:193], v[198:201], v[112:115]
	v_mfma_f32_16x16x32_bf16 v[100:103], v[180:183], v[206:209], v[100:103]
	v_mfma_f32_16x16x32_bf16 v[96:99], v[190:193], v[206:209], v[96:99]
	v_mfma_f32_16x16x32_bf16 v[84:87], v[180:183], v[214:217], v[84:87]
	v_mfma_f32_16x16x32_bf16 v[80:83], v[190:193], v[214:217], v[80:83]
	v_mfma_f32_16x16x32_bf16 v[68:71], v[180:183], v[222:225], v[68:71]
	v_mfma_f32_16x16x32_bf16 v[64:67], v[190:193], v[222:225], v[64:67]
	v_mfma_f32_16x16x32_bf16 v[116:119], v[186:189], v[202:205], v[116:119]
	v_mfma_f32_16x16x32_bf16 v[112:115], v[194:197], v[202:205], v[112:115]
	v_mfma_f32_16x16x32_bf16 v[100:103], v[186:189], v[210:213], v[100:103]
	v_mfma_f32_16x16x32_bf16 v[96:99], v[194:197], v[210:213], v[96:99]
	v_mfma_f32_16x16x32_bf16 v[84:87], v[186:189], v[218:221], v[84:87]
	v_mfma_f32_16x16x32_bf16 v[80:83], v[194:197], v[218:221], v[80:83]
	v_mfma_f32_16x16x32_bf16 v[68:71], v[186:189], v[226:229], v[68:71]
	v_mfma_f32_16x16x32_bf16 v[64:67], v[194:197], v[226:229], v[64:67]
	s_setprio 0
	s_barrier
	s_add_u32 s88, s36, 0x80
	s_addc_u32 s89, s37, 0
	s_add_u32 s90, s42, 0x80
	s_addc_u32 s91, s43, 0
	s_mov_b32 m0, s48
	s_add_u32 s72, s36, 0x100000
	ds_read_b128 v[198:201], v149 offset:16384
	ds_read_b128 v[202:205], v149 offset:17408
	ds_read_b128 v[206:209], v149 offset:18432
	ds_read_b128 v[210:213], v149 offset:19456
	ds_read_b128 v[214:217], v149 offset:20480
	ds_read_b128 v[218:221], v149 offset:21504
	ds_read_b128 v[222:225], v149 offset:22528
	ds_read_b128 v[226:229], v149 offset:23552
	global_load_lds_dwordx4 v130, s[36:37]
	s_mov_b32 m0, s49
	s_addc_u32 s73, s37, 0
	global_load_lds_dwordx4 v134, s[36:37]
	s_mov_b32 m0, s50
	s_nop 0
	global_load_lds_dwordx4 v130, s[72:73]
	s_mov_b32 m0, s51
	s_nop 0
	global_load_lds_dwordx4 v134, s[72:73]
	s_mov_b32 m0, s47
	s_nop 0
	global_load_lds_dwordx4 v128, s[42:43]
	s_mov_b32 m0, s52
	s_nop 0
	global_load_lds_dwordx4 v132, s[42:43]
	s_waitcnt vmcnt(8)
	s_waitcnt lgkmcnt(0)
	s_barrier
	s_setprio 1
	s_waitcnt lgkmcnt(0)
	v_mfma_f32_16x16x32_bf16 v[60:63], v[144:147], v[198:201], v[60:63]
	v_mfma_f32_16x16x32_bf16 v[56:59], v[172:175], v[198:201], v[56:59]
	v_mfma_f32_16x16x32_bf16 v[44:47], v[144:147], v[206:209], v[44:47]
	v_mfma_f32_16x16x32_bf16 v[40:43], v[172:175], v[206:209], v[40:43]
	v_mfma_f32_16x16x32_bf16 v[28:31], v[144:147], v[214:217], v[28:31]
	v_mfma_f32_16x16x32_bf16 v[24:27], v[172:175], v[214:217], v[24:27]
	v_mfma_f32_16x16x32_bf16 v[12:15], v[144:147], v[222:225], v[12:15]
	v_mfma_f32_16x16x32_bf16 v[8:11], v[172:175], v[222:225], v[8:11]
	v_mfma_f32_16x16x32_bf16 v[60:63], v[168:171], v[202:205], v[60:63]
	v_mfma_f32_16x16x32_bf16 v[56:59], v[176:179], v[202:205], v[56:59]
	v_mfma_f32_16x16x32_bf16 v[44:47], v[168:171], v[210:213], v[44:47]
	v_mfma_f32_16x16x32_bf16 v[40:43], v[176:179], v[210:213], v[40:43]
	v_mfma_f32_16x16x32_bf16 v[28:31], v[168:171], v[218:221], v[28:31]
	v_mfma_f32_16x16x32_bf16 v[24:27], v[176:179], v[218:221], v[24:27]
	v_mfma_f32_16x16x32_bf16 v[12:15], v[168:171], v[226:229], v[12:15]
	v_mfma_f32_16x16x32_bf16 v[8:11], v[176:179], v[226:229], v[8:11]
	s_setprio 0
	s_setprio 1
	v_mfma_f32_16x16x32_bf16 v[52:55], v[180:183], v[198:201], v[52:55]
	v_mfma_f32_16x16x32_bf16 v[48:51], v[190:193], v[198:201], v[48:51]
	v_mfma_f32_16x16x32_bf16 v[36:39], v[180:183], v[206:209], v[36:39]
	v_mfma_f32_16x16x32_bf16 v[32:35], v[190:193], v[206:209], v[32:35]
	v_mfma_f32_16x16x32_bf16 v[20:23], v[180:183], v[214:217], v[20:23]
	v_mfma_f32_16x16x32_bf16 v[16:19], v[190:193], v[214:217], v[16:19]
	v_mfma_f32_16x16x32_bf16 v[4:7], v[180:183], v[222:225], v[4:7]
	v_mfma_f32_16x16x32_bf16 v[0:3], v[190:193], v[222:225], v[0:3]
	v_mfma_f32_16x16x32_bf16 v[52:55], v[186:189], v[202:205], v[52:55]
	v_mfma_f32_16x16x32_bf16 v[48:51], v[194:197], v[202:205], v[48:51]
	v_mfma_f32_16x16x32_bf16 v[36:39], v[186:189], v[210:213], v[36:39]
	v_mfma_f32_16x16x32_bf16 v[32:35], v[194:197], v[210:213], v[32:35]
	v_mfma_f32_16x16x32_bf16 v[20:23], v[186:189], v[218:221], v[20:23]
	v_mfma_f32_16x16x32_bf16 v[16:19], v[194:197], v[218:221], v[16:19]
	v_mfma_f32_16x16x32_bf16 v[4:7], v[186:189], v[226:229], v[4:7]
	v_mfma_f32_16x16x32_bf16 v[0:3], v[194:197], v[226:229], v[0:3]
	s_setprio 0
	s_barrier
; #define PG8_STAGE(bufoff, gbase, voff) do { _Pragma("unroll") for (int _i = 0; _i < 2; ++_i) \
;         __builtin_amdgcn_global_load_lds((const unsigned*)((const char*)(gbase) + (voff)[_i]), (PG8_LAS unsigned*)(lds + (bufoff) + ldsw + _i * 8192), 16, 0, 0); } while (0)
; #define PG8_LDA(dst, b, h) do { _Pragma("unroll") for (int m = 0; m < 4; ++m) _Pragma("unroll") for (int k = 0; k < 2; ++k) dst[m][k] = *(const PG8_LAS bf16x8*)(lds + PG8_SA(b, h) + aoff + m * 2048 + k * 1024); } while (0)
; #define PG8_LDB(dst, b, h) do { _Pragma("unroll") for (int n = 0; n < 2; ++n) _Pragma("unroll") for (int k = 0; k < 2; ++k) dst[n][k] = *(const PG8_LAS bf16x8*)(lds + PG8_SB(b, h) + boff + n * 2048 + k * 1024); } while (0)
; #define PG8_MMA(ai, bj, At, Bt) do { __builtin_amdgcn_s_setprio(1); _Pragma("unroll") for (int m = 0; m < 4; ++m) _Pragma("unroll") for (int n = 0; n < 2; ++n) _Pragma("unroll") for (int k = 0; k < 2; ++k) \
;         acc[ai][bj][m][n] = __builtin_amdgcn_mfma_f32_16x16x32_bf16(Bt[n][k], At[m][k], acc[ai][bj][m][n], 0, 0, 0); __builtin_amdgcn_s_setprio(0); } while (0)
; #define PG8_WAIT_V(n) asm volatile("s_waitcnt vmcnt(" #n ")" ::: "memory")
; #define PG8_WAIT_L(n) asm volatile("s_waitcnt lgkmcnt(" #n ")" ::: "memory")
; #define PG8_BAR __builtin_amdgcn_s_barrier()
; #define PG8_SCHED __builtin_amdgcn_sched_barrier(0)
; template <class Epi, class Sched, bool ALIGN_EPI = false, bool SP2 = false>
; __device__ __forceinline__ void gemm_phase(PG8_LAS unsigned char* lds, const Gemm g, const Sched& S, const Epi& E) {
;     ...
;         for (int t = 0; t < nt; t += 2) {
;     ...
;             PG8_LDB(B0, 1, 0); PG8_LDB(B1, 1, 1); PG8_SCHED; PG8_LDA(At, 1, 0); PG8_STAGE(PG8_SA(0, 1), a2 + hstep, voffA);
;             PG8_WAIT_V(8); PG8_WAIT_L(0); PG8_BAR; PG8_MMA(0, 0, At, B0); PG8_MMA(0, 1, At, B1); PG8_BAR; PG8_SCHED;
;             PG8_LDA(At, 1, 1); PG8_STAGE(PG8_SB(1, 0), b3, voffB); PG8_STAGE(PG8_SB(1, 1), b3 + hstep, voffB); PG8_STAGE(PG8_SA(1, 0), a3, voffA);
;             PG8_WAIT_V(8); PG8_WAIT_L(0); PG8_BAR; PG8_MMA(1, 0, At, B0); PG8_MMA(1, 1, At, B1); PG8_BAR; PG8_SCHED;
	ds_read_b128 v[144:147], v159
	ds_read_b128 v[168:171], v160
	ds_read_b128 v[172:175], v161
	ds_read_b128 v[176:179], v162
	ds_read_b128 v[180:183], v163
	ds_read_b128 v[186:189], v164
	ds_read_b128 v[190:193], v165
	ds_read_b128 v[194:197], v166
	s_add_u32 s42, s42, 0x100000
	s_addc_u32 s43, s43, 0
	s_mov_b32 m0, s53
	ds_read_b128 v[198:201], v149 offset:32768
	ds_read_b128 v[202:205], v149 offset:33792
	ds_read_b128 v[206:209], v149 offset:34816
	ds_read_b128 v[210:213], v149 offset:35840
	ds_read_b128 v[214:217], v149 offset:36864
	ds_read_b128 v[218:221], v149 offset:37888
	ds_read_b128 v[222:225], v149 offset:38912
	ds_read_b128 v[226:229], v149 offset:39936
	global_load_lds_dwordx4 v128, s[42:43]
	s_mov_b32 m0, s54
	s_nop 0
	global_load_lds_dwordx4 v132, s[42:43]
	s_waitcnt vmcnt(8)
	s_waitcnt lgkmcnt(0)
	s_barrier
	s_setprio 1
	s_waitcnt lgkmcnt(0)
	v_mfma_f32_16x16x32_bf16 v[124:127], v[144:147], v[198:201], v[124:127]
	v_mfma_f32_16x16x32_bf16 v[120:123], v[172:175], v[198:201], v[120:123]
	v_mfma_f32_16x16x32_bf16 v[108:111], v[144:147], v[206:209], v[108:111]
	v_mfma_f32_16x16x32_bf16 v[104:107], v[172:175], v[206:209], v[104:107]
	v_mfma_f32_16x16x32_bf16 v[92:95], v[144:147], v[214:217], v[92:95]
	v_mfma_f32_16x16x32_bf16 v[88:91], v[172:175], v[214:217], v[88:91]
	v_mfma_f32_16x16x32_bf16 v[76:79], v[144:147], v[222:225], v[76:79]
	v_mfma_f32_16x16x32_bf16 v[72:75], v[172:175], v[222:225], v[72:75]
	v_mfma_f32_16x16x32_bf16 v[124:127], v[168:171], v[202:205], v[124:127]
	v_mfma_f32_16x16x32_bf16 v[120:123], v[176:179], v[202:205], v[120:123]
	v_mfma_f32_16x16x32_bf16 v[108:111], v[168:171], v[210:213], v[108:111]
	v_mfma_f32_16x16x32_bf16 v[104:107], v[176:179], v[210:213], v[104:107]
	v_mfma_f32_16x16x32_bf16 v[92:95], v[168:171], v[218:221], v[92:95]
	v_mfma_f32_16x16x32_bf16 v[88:91], v[176:179], v[218:221], v[88:91]
	v_mfma_f32_16x16x32_bf16 v[76:79], v[168:171], v[226:229], v[76:79]
	v_mfma_f32_16x16x32_bf16 v[72:75], v[176:179], v[226:229], v[72:75]
	s_setprio 0
	s_setprio 1
	v_mfma_f32_16x16x32_bf16 v[116:119], v[180:183], v[198:201], v[116:119]
	v_mfma_f32_16x16x32_bf16 v[112:115], v[190:193], v[198:201], v[112:115]
	v_mfma_f32_16x16x32_bf16 v[100:103], v[180:183], v[206:209], v[100:103]
	v_mfma_f32_16x16x32_bf16 v[96:99], v[190:193], v[206:209], v[96:99]
	v_mfma_f32_16x16x32_bf16 v[84:87], v[180:183], v[214:217], v[84:87]
	v_mfma_f32_16x16x32_bf16 v[80:83], v[190:193], v[214:217], v[80:83]
	v_mfma_f32_16x16x32_bf16 v[68:71], v[180:183], v[222:225], v[68:71]
	v_mfma_f32_16x16x32_bf16 v[64:67], v[190:193], v[222:225], v[64:67]
	v_mfma_f32_16x16x32_bf16 v[116:119], v[186:189], v[202:205], v[116:119]
	v_mfma_f32_16x16x32_bf16 v[112:115], v[194:197], v[202:205], v[112:115]
	v_mfma_f32_16x16x32_bf16 v[100:103], v[186:189], v[210:213], v[100:103]
	v_mfma_f32_16x16x32_bf16 v[96:99], v[194:197], v[210:213], v[96:99]
	v_mfma_f32_16x16x32_bf16 v[84:87], v[186:189], v[218:221], v[84:87]
	v_mfma_f32_16x16x32_bf16 v[80:83], v[194:197], v[218:221], v[80:83]
	v_mfma_f32_16x16x32_bf16 v[68:71], v[186:189], v[226:229], v[68:71]
	v_mfma_f32_16x16x32_bf16 v[64:67], v[194:197], v[226:229], v[64:67]
	s_setprio 0
	s_barrier
	s_mov_b32 m0, s56
	s_add_u32 s36, s36, 0x100080
	ds_read_b128 v[198:201], v149 offset:49152
	ds_read_b128 v[202:205], v149 offset:50176
	ds_read_b128 v[206:209], v149 offset:51200
	ds_read_b128 v[210:213], v149 offset:52224
	ds_read_b128 v[214:217], v149 offset:53248
	ds_read_b128 v[218:221], v149 offset:54272
	ds_read_b128 v[222:225], v149 offset:55296
	ds_read_b128 v[226:229], v149 offset:56320
	global_load_lds_dwordx4 v130, s[88:89]
	s_mov_b32 m0, s57
	s_addc_u32 s37, s37, 0
	global_load_lds_dwordx4 v134, s[88:89]
	s_mov_b32 m0, s60
	s_nop 0
	global_load_lds_dwordx4 v130, s[36:37]
	s_mov_b32 m0, s61
	s_nop 0
	global_load_lds_dwordx4 v134, s[36:37]
	s_mov_b32 m0, s58
	s_nop 0
	global_load_lds_dwordx4 v128, s[90:91]
	s_mov_b32 m0, s59
	s_nop 0
	global_load_lds_dwordx4 v132, s[90:91]
	s_waitcnt vmcnt(8)
	s_waitcnt lgkmcnt(0)
	s_barrier
	s_setprio 1
	s_waitcnt lgkmcnt(0)
	v_mfma_f32_16x16x32_bf16 v[60:63], v[144:147], v[198:201], v[60:63]
	v_mfma_f32_16x16x32_bf16 v[56:59], v[172:175], v[198:201], v[56:59]
	v_mfma_f32_16x16x32_bf16 v[44:47], v[144:147], v[206:209], v[44:47]
	v_mfma_f32_16x16x32_bf16 v[40:43], v[172:175], v[206:209], v[40:43]
	v_mfma_f32_16x16x32_bf16 v[28:31], v[144:147], v[214:217], v[28:31]
	v_mfma_f32_16x16x32_bf16 v[24:27], v[172:175], v[214:217], v[24:27]
	v_mfma_f32_16x16x32_bf16 v[12:15], v[144:147], v[222:225], v[12:15]
	v_mfma_f32_16x16x32_bf16 v[8:11], v[172:175], v[222:225], v[8:11]
	v_mfma_f32_16x16x32_bf16 v[60:63], v[168:171], v[202:205], v[60:63]
	v_mfma_f32_16x16x32_bf16 v[56:59], v[176:179], v[202:205], v[56:59]
	v_mfma_f32_16x16x32_bf16 v[44:47], v[168:171], v[210:213], v[44:47]
	v_mfma_f32_16x16x32_bf16 v[40:43], v[176:179], v[210:213], v[40:43]
	v_mfma_f32_16x16x32_bf16 v[28:31], v[168:171], v[218:221], v[28:31]
	v_mfma_f32_16x16x32_bf16 v[24:27], v[176:179], v[218:221], v[24:27]
	v_mfma_f32_16x16x32_bf16 v[12:15], v[168:171], v[226:229], v[12:15]
	v_mfma_f32_16x16x32_bf16 v[8:11], v[176:179], v[226:229], v[8:11]
	s_setprio 0
	s_setprio 1
	v_mfma_f32_16x16x32_bf16 v[52:55], v[180:183], v[198:201], v[52:55]
	v_mfma_f32_16x16x32_bf16 v[48:51], v[190:193], v[198:201], v[48:51]
	v_mfma_f32_16x16x32_bf16 v[36:39], v[180:183], v[206:209], v[36:39]
	v_mfma_f32_16x16x32_bf16 v[32:35], v[190:193], v[206:209], v[32:35]
	v_mfma_f32_16x16x32_bf16 v[20:23], v[180:183], v[214:217], v[20:23]
	v_mfma_f32_16x16x32_bf16 v[16:19], v[190:193], v[214:217], v[16:19]
	v_mfma_f32_16x16x32_bf16 v[4:7], v[180:183], v[222:225], v[4:7]
	v_mfma_f32_16x16x32_bf16 v[0:3], v[190:193], v[222:225], v[0:3]
	v_mfma_f32_16x16x32_bf16 v[52:55], v[186:189], v[202:205], v[52:55]
	v_mfma_f32_16x16x32_bf16 v[48:51], v[194:197], v[202:205], v[48:51]
	v_mfma_f32_16x16x32_bf16 v[36:39], v[186:189], v[210:213], v[36:39]
	v_mfma_f32_16x16x32_bf16 v[32:35], v[194:197], v[210:213], v[32:35]
	v_mfma_f32_16x16x32_bf16 v[20:23], v[186:189], v[218:221], v[20:23]
	v_mfma_f32_16x16x32_bf16 v[16:19], v[194:197], v[218:221], v[16:19]
	v_mfma_f32_16x16x32_bf16 v[4:7], v[186:189], v[226:229], v[4:7]
	v_mfma_f32_16x16x32_bf16 v[0:3], v[194:197], v[226:229], v[0:3]
	s_setprio 0
	s_barrier
	s_add_i32 s70, s70, 2
	s_add_u32 s68, s68, 0x100
	s_addc_u32 s69, s69, 0
	s_add_u32 s34, s34, 0x100
	s_addc_u32 s35, s35, 0
	s_cmp_gt_u32 s70, 61
	s_cbranch_scc0 .LBB0_558
	s_and_b64 vcc, exec, s[18:19]
	s_cbranch_vccz .LBB0_561
	s_barrier

; #define PG8_STAGE(bufoff, gbase, voff) do { _Pragma("unroll") for (int _i = 0; _i < 2; ++_i) \
;         __builtin_amdgcn_global_load_lds((const unsigned*)((const char*)(gbase) + (voff)[_i]), (PG8_LAS unsigned*)(lds + (bufoff) + ldsw + _i * 8192), 16, 0, 0); } while (0)
; #define PG8_LDA(dst, b, h) do { _Pragma("unroll") for (int m = 0; m < 4; ++m) _Pragma("unroll") for (int k = 0; k < 2; ++k) dst[m][k] = *(const PG8_LAS bf16x8*)(lds + PG8_SA(b, h) + aoff + m * 2048 + k * 1024); } while (0)
; #define PG8_LDB(dst, b, h) do { _Pragma("unroll") for (int n = 0; n < 2; ++n) _Pragma("unroll") for (int k = 0; k < 2; ++k) dst[n][k] = *(const PG8_LAS bf16x8*)(lds + PG8_SB(b, h) + boff + n * 2048 + k * 1024); } while (0)
; #define PG8_MMA(ai, bj, At, Bt) do { __builtin_amdgcn_s_setprio(1); _Pragma("unroll") for (int m = 0; m < 4; ++m) _Pragma("unroll") for (int n = 0; n < 2; ++n) _Pragma("unroll") for (int k = 0; k < 2; ++k) \
;         acc[ai][bj][m][n] = __builtin_amdgcn_mfma_f32_16x16x32_bf16(Bt[n][k], At[m][k], acc[ai][bj][m][n], 0, 0, 0); __builtin_amdgcn_s_setprio(0); } while (0)
; #define PG8_WAIT_V(n) asm volatile("s_waitcnt vmcnt(" #n ")" ::: "memory")
; #define PG8_WAIT_L(n) asm volatile("s_waitcnt lgkmcnt(" #n ")" ::: "memory")
; #define PG8_BAR __builtin_amdgcn_s_barrier()
; #define PG8_SCHED __builtin_amdgcn_sched_barrier(0)
; template <class Epi, class Sched, bool ALIGN_EPI = false, bool SP2 = false>
; __device__ __forceinline__ void gemm_phase(PG8_LAS unsigned char* lds, const Gemm g, const Sched& S, const Epi& E) {
;     ...
;             const char* a2 = last ? nA : cA + (size_t)(t + 2) * kstep; const char* b2 = last ? nB : cB + (size_t)(t + 2) * kstep;
;     ...
;             PG8_LDB(B0, 0, 0); PG8_LDB(B1, 0, 1); PG8_SCHED; PG8_LDA(At, 0, 0); PG8_STAGE(PG8_SA(1, 1), a1 + hstep, voffA);
;             PG8_WAIT_V(8); PG8_WAIT_L(0); PG8_BAR; PG8_MMA(0, 0, At, B0); PG8_MMA(0, 1, At, B1); PG8_BAR; PG8_SCHED;
;             PG8_LDA(At, 0, 1); PG8_STAGE(PG8_SB(0, 0), b2, voffB); PG8_STAGE(PG8_SB(0, 1), b2 + hstep, voffB); PG8_STAGE(PG8_SA(0, 0), a2, voffA);
;             PG8_WAIT_V(8); PG8_WAIT_L(0); PG8_BAR; PG8_MMA(1, 0, At, B0); PG8_MMA(1, 1, At, B1); PG8_BAR; PG8_SCHED;
.LBB0_645:
	s_add_u32 s54, s36, s52
	s_addc_u32 s55, s37, 0
	s_add_u32 s53, s54, 0x100
	s_addc_u32 s56, s55, 0
	s_and_b64 s[50:51], s[48:49], exec
	s_cselect_b32 s51, s31, s56
	s_cselect_b32 s50, s86, s53
	s_add_u32 s52, s34, s52
	s_addc_u32 s53, s35, 0
	ds_read_b128 v[160:163], v143
	ds_read_b128 v[164:167], v144
	ds_read_b128 v[168:171], v145
	ds_read_b128 v[172:175], v146
	ds_read_b128 v[176:179], v147
	ds_read_b128 v[180:183], v148
	ds_read_b128 v[186:189], v149
	ds_read_b128 v[190:193], v150
	s_add_u32 s52, s52, 0x100
	s_addc_u32 s53, s53, 0
	s_and_b64 s[48:49], s[48:49], exec
	s_cselect_b32 s53, s29, s53
	s_cselect_b32 s52, s87, s52
	s_add_u32 s58, s54, 0x10080
	s_addc_u32 s59, s55, 0
	s_add_u32 s54, s52, 0x10000
	s_addc_u32 s55, s53, 0
	s_add_u32 s48, s50, 0x10000
	s_addc_u32 s49, s51, 0
	s_add_u32 s56, s52, 0x10080
	s_addc_u32 s57, s53, 0
	s_mov_b32 m0, s79
	ds_read_b128 v[194:197], v141
	ds_read_b128 v[198:201], v141 offset:1024
	ds_read_b128 v[202:205], v141 offset:2048
	ds_read_b128 v[206:209], v141 offset:3072
	ds_read_b128 v[210:213], v141 offset:4096
	ds_read_b128 v[214:217], v141 offset:5120
	ds_read_b128 v[218:221], v141 offset:6144
	ds_read_b128 v[222:225], v141 offset:7168
	global_load_lds_dwordx4 v134, s[58:59]
	s_mov_b32 m0, s80
	s_nop 0
	global_load_lds_dwordx4 v130, s[58:59]
	s_waitcnt vmcnt(8)
	s_waitcnt lgkmcnt(0)
	s_barrier
	s_setprio 1
	s_waitcnt lgkmcnt(0)
	v_mfma_f32_16x16x32_bf16 v[124:127], v[160:163], v[194:197], v[124:127]
	v_mfma_f32_16x16x32_bf16 v[120:123], v[168:171], v[194:197], v[120:123]
	v_mfma_f32_16x16x32_bf16 v[116:119], v[160:163], v[202:205], v[116:119]
	v_mfma_f32_16x16x32_bf16 v[112:115], v[168:171], v[202:205], v[112:115]
	v_mfma_f32_16x16x32_bf16 v[100:103], v[160:163], v[210:213], v[100:103]
	v_mfma_f32_16x16x32_bf16 v[96:99], v[168:171], v[210:213], v[96:99]
	v_mfma_f32_16x16x32_bf16 v[84:87], v[160:163], v[218:221], v[84:87]
	v_mfma_f32_16x16x32_bf16 v[80:83], v[168:171], v[218:221], v[80:83]
	v_mfma_f32_16x16x32_bf16 v[124:127], v[164:167], v[198:201], v[124:127]
	v_mfma_f32_16x16x32_bf16 v[120:123], v[172:175], v[198:201], v[120:123]
	v_mfma_f32_16x16x32_bf16 v[116:119], v[164:167], v[206:209], v[116:119]
	v_mfma_f32_16x16x32_bf16 v[112:115], v[172:175], v[206:209], v[112:115]
	v_mfma_f32_16x16x32_bf16 v[100:103], v[164:167], v[214:217], v[100:103]
	v_mfma_f32_16x16x32_bf16 v[96:99], v[172:175], v[214:217], v[96:99]
	v_mfma_f32_16x16x32_bf16 v[84:87], v[164:167], v[222:225], v[84:87]
	v_mfma_f32_16x16x32_bf16 v[80:83], v[172:175], v[222:225], v[80:83]
	s_setprio 0
	s_setprio 1
	v_mfma_f32_16x16x32_bf16 v[108:111], v[176:179], v[194:197], v[108:111]
	v_mfma_f32_16x16x32_bf16 v[104:107], v[186:189], v[194:197], v[104:107]
	v_mfma_f32_16x16x32_bf16 v[92:95], v[176:179], v[202:205], v[92:95]
	v_mfma_f32_16x16x32_bf16 v[88:91], v[186:189], v[202:205], v[88:91]
	v_mfma_f32_16x16x32_bf16 v[76:79], v[176:179], v[210:213], v[76:79]
	v_mfma_f32_16x16x32_bf16 v[72:75], v[186:189], v[210:213], v[72:75]
	v_mfma_f32_16x16x32_bf16 v[68:71], v[176:179], v[218:221], v[68:71]
	v_mfma_f32_16x16x32_bf16 v[64:67], v[186:189], v[218:221], v[64:67]
	v_mfma_f32_16x16x32_bf16 v[108:111], v[180:183], v[198:201], v[108:111]
	v_mfma_f32_16x16x32_bf16 v[104:107], v[190:193], v[198:201], v[104:107]
	v_mfma_f32_16x16x32_bf16 v[92:95], v[180:183], v[206:209], v[92:95]
	v_mfma_f32_16x16x32_bf16 v[88:91], v[190:193], v[206:209], v[88:91]
	v_mfma_f32_16x16x32_bf16 v[76:79], v[180:183], v[214:217], v[76:79]
	v_mfma_f32_16x16x32_bf16 v[72:75], v[190:193], v[214:217], v[72:75]
	v_mfma_f32_16x16x32_bf16 v[68:71], v[180:183], v[222:225], v[68:71]
	v_mfma_f32_16x16x32_bf16 v[64:67], v[190:193], v[222:225], v[64:67]
	s_setprio 0
	s_barrier
	s_add_u32 s88, s52, 0x80
	s_addc_u32 s89, s53, 0
	s_add_u32 s90, s50, 0x80
	s_addc_u32 s91, s51, 0
	s_mov_b32 m0, s27
	ds_read_b128 v[194:197], v141 offset:16384
	ds_read_b128 v[198:201], v141 offset:17408
	ds_read_b128 v[202:205], v141 offset:18432
	ds_read_b128 v[206:209], v141 offset:19456
	ds_read_b128 v[210:213], v141 offset:20480
	ds_read_b128 v[214:217], v141 offset:21504
	ds_read_b128 v[218:221], v141 offset:22528
	ds_read_b128 v[222:225], v141 offset:23552
	global_load_lds_dwordx4 v132, s[52:53]
	s_mov_b32 m0, s65
	s_nop 0
	global_load_lds_dwordx4 v128, s[52:53]
	s_mov_b32 m0, s66
	s_nop 0
	global_load_lds_dwordx4 v132, s[54:55]
	s_mov_b32 m0, s67
	s_nop 0
	global_load_lds_dwordx4 v128, s[54:55]
	s_mov_b32 m0, s63
	s_nop 0
	global_load_lds_dwordx4 v134, s[50:51]
	s_mov_b32 m0, s68
	s_nop 0
	global_load_lds_dwordx4 v130, s[50:51]
	s_waitcnt vmcnt(8)
	s_waitcnt lgkmcnt(0)
	s_barrier
; #define PG8_STAGE(bufoff, gbase, voff) do { _Pragma("unroll") for (int _i = 0; _i < 2; ++_i) \
;         __builtin_amdgcn_global_load_lds((const unsigned*)((const char*)(gbase) + (voff)[_i]), (PG8_LAS unsigned*)(lds + (bufoff) + ldsw + _i * 8192), 16, 0, 0); } while (0)
; #define PG8_LDA(dst, b, h) do { _Pragma("unroll") for (int m = 0; m < 4; ++m) _Pragma("unroll") for (int k = 0; k < 2; ++k) dst[m][k] = *(const PG8_LAS bf16x8*)(lds + PG8_SA(b, h) + aoff + m * 2048 + k * 1024); } while (0)
; #define PG8_LDB(dst, b, h) do { _Pragma("unroll") for (int n = 0; n < 2; ++n) _Pragma("unroll") for (int k = 0; k < 2; ++k) dst[n][k] = *(const PG8_LAS bf16x8*)(lds + PG8_SB(b, h) + boff + n * 2048 + k * 1024); } while (0)
; #define PG8_MMA(ai, bj, At, Bt) do { __builtin_amdgcn_s_setprio(1); _Pragma("unroll") for (int m = 0; m < 4; ++m) _Pragma("unroll") for (int n = 0; n < 2; ++n) _Pragma("unroll") for (int k = 0; k < 2; ++k) \
;         acc[ai][bj][m][n] = __builtin_amdgcn_mfma_f32_16x16x32_bf16(Bt[n][k], At[m][k], acc[ai][bj][m][n], 0, 0, 0); __builtin_amdgcn_s_setprio(0); } while (0)
; #define PG8_WAIT_V(n) asm volatile("s_waitcnt vmcnt(" #n ")" ::: "memory")
; #define PG8_WAIT_L(n) asm volatile("s_waitcnt lgkmcnt(" #n ")" ::: "memory")
; #define PG8_BAR __builtin_amdgcn_s_barrier()
; #define PG8_SCHED __builtin_amdgcn_sched_barrier(0)
; template <class Epi, class Sched, bool ALIGN_EPI = false, bool SP2 = false>
; __device__ __forceinline__ void gemm_phase(PG8_LAS unsigned char* lds, const Gemm g, const Sched& S, const Epi& E) {
;     ...
;             PG8_WAIT_V(8); PG8_WAIT_L(0); PG8_BAR; PG8_MMA(1, 0, At, B0); PG8_MMA(1, 1, At, B1); PG8_BAR; PG8_SCHED;
;             PG8_LDB(B0, 1, 0); PG8_LDB(B1, 1, 1); PG8_SCHED; PG8_LDA(At, 1, 0); PG8_STAGE(PG8_SA(0, 1), a2 + hstep, voffA);
;             PG8_WAIT_V(8); PG8_WAIT_L(0); PG8_BAR; PG8_MMA(0, 0, At, B0); PG8_MMA(0, 1, At, B1); PG8_BAR; PG8_SCHED;
	s_setprio 1
	s_waitcnt lgkmcnt(0)
	v_mfma_f32_16x16x32_bf16 v[60:63], v[160:163], v[194:197], v[60:63]
	v_mfma_f32_16x16x32_bf16 v[56:59], v[168:171], v[194:197], v[56:59]
	v_mfma_f32_16x16x32_bf16 v[52:55], v[160:163], v[202:205], v[52:55]
	v_mfma_f32_16x16x32_bf16 v[48:51], v[168:171], v[202:205], v[48:51]
	v_mfma_f32_16x16x32_bf16 v[36:39], v[160:163], v[210:213], v[36:39]
	v_mfma_f32_16x16x32_bf16 v[32:35], v[168:171], v[210:213], v[32:35]
	v_mfma_f32_16x16x32_bf16 v[20:23], v[160:163], v[218:221], v[20:23]
	v_mfma_f32_16x16x32_bf16 v[16:19], v[168:171], v[218:221], v[16:19]
	v_mfma_f32_16x16x32_bf16 v[60:63], v[164:167], v[198:201], v[60:63]
	v_mfma_f32_16x16x32_bf16 v[56:59], v[172:175], v[198:201], v[56:59]
	v_mfma_f32_16x16x32_bf16 v[52:55], v[164:167], v[206:209], v[52:55]
	v_mfma_f32_16x16x32_bf16 v[48:51], v[172:175], v[206:209], v[48:51]
	v_mfma_f32_16x16x32_bf16 v[36:39], v[164:167], v[214:217], v[36:39]
	v_mfma_f32_16x16x32_bf16 v[32:35], v[172:175], v[214:217], v[32:35]
	v_mfma_f32_16x16x32_bf16 v[20:23], v[164:167], v[222:225], v[20:23]
	v_mfma_f32_16x16x32_bf16 v[16:19], v[172:175], v[222:225], v[16:19]
	s_setprio 0
	s_setprio 1
	v_mfma_f32_16x16x32_bf16 v[44:47], v[176:179], v[194:197], v[44:47]
	v_mfma_f32_16x16x32_bf16 v[40:43], v[186:189], v[194:197], v[40:43]
	v_mfma_f32_16x16x32_bf16 v[28:31], v[176:179], v[202:205], v[28:31]
	v_mfma_f32_16x16x32_bf16 v[24:27], v[186:189], v[202:205], v[24:27]
	v_mfma_f32_16x16x32_bf16 v[12:15], v[176:179], v[210:213], v[12:15]
	v_mfma_f32_16x16x32_bf16 v[8:11], v[186:189], v[210:213], v[8:11]
	v_mfma_f32_16x16x32_bf16 v[4:7], v[176:179], v[218:221], v[4:7]
	v_mfma_f32_16x16x32_bf16 v[0:3], v[186:189], v[218:221], v[0:3]
	v_mfma_f32_16x16x32_bf16 v[44:47], v[180:183], v[198:201], v[44:47]
	v_mfma_f32_16x16x32_bf16 v[40:43], v[190:193], v[198:201], v[40:43]
	v_mfma_f32_16x16x32_bf16 v[28:31], v[180:183], v[206:209], v[28:31]
	v_mfma_f32_16x16x32_bf16 v[24:27], v[190:193], v[206:209], v[24:27]
	v_mfma_f32_16x16x32_bf16 v[12:15], v[180:183], v[214:217], v[12:15]
	v_mfma_f32_16x16x32_bf16 v[8:11], v[190:193], v[214:217], v[8:11]
	v_mfma_f32_16x16x32_bf16 v[4:7], v[180:183], v[222:225], v[4:7]
	v_mfma_f32_16x16x32_bf16 v[0:3], v[190:193], v[222:225], v[0:3]
	s_setprio 0
	s_barrier
	ds_read_b128 v[160:163], v151
	ds_read_b128 v[164:167], v152
	ds_read_b128 v[168:171], v153
	ds_read_b128 v[172:175], v154
	ds_read_b128 v[176:179], v155
	ds_read_b128 v[180:183], v156
	ds_read_b128 v[186:189], v157
	ds_read_b128 v[190:193], v158
	s_mov_b32 m0, s69
	ds_read_b128 v[194:197], v141 offset:32768
	ds_read_b128 v[198:201], v141 offset:33792
	ds_read_b128 v[202:205], v141 offset:34816
	ds_read_b128 v[206:209], v141 offset:35840
	ds_read_b128 v[210:213], v141 offset:36864
	ds_read_b128 v[214:217], v141 offset:37888
	ds_read_b128 v[218:221], v141 offset:38912
	ds_read_b128 v[222:225], v141 offset:39936
	global_load_lds_dwordx4 v134, s[48:49]
	s_mov_b32 m0, s70
	s_nop 0
	global_load_lds_dwordx4 v130, s[48:49]
	s_waitcnt vmcnt(8)
	s_waitcnt lgkmcnt(0)
	s_barrier
	s_setprio 1
	s_waitcnt lgkmcnt(0)
	v_mfma_f32_16x16x32_bf16 v[124:127], v[160:163], v[194:197], v[124:127]
	v_mfma_f32_16x16x32_bf16 v[120:123], v[168:171], v[194:197], v[120:123]
	v_mfma_f32_16x16x32_bf16 v[116:119], v[160:163], v[202:205], v[116:119]
	v_mfma_f32_16x16x32_bf16 v[112:115], v[168:171], v[202:205], v[112:115]
	v_mfma_f32_16x16x32_bf16 v[100:103], v[160:163], v[210:213], v[100:103]
	v_mfma_f32_16x16x32_bf16 v[96:99], v[168:171], v[210:213], v[96:99]
	v_mfma_f32_16x16x32_bf16 v[84:87], v[160:163], v[218:221], v[84:87]
	v_mfma_f32_16x16x32_bf16 v[80:83], v[168:171], v[218:221], v[80:83]
	v_mfma_f32_16x16x32_bf16 v[124:127], v[164:167], v[198:201], v[124:127]
	v_mfma_f32_16x16x32_bf16 v[120:123], v[172:175], v[198:201], v[120:123]
	v_mfma_f32_16x16x32_bf16 v[116:119], v[164:167], v[206:209], v[116:119]
	v_mfma_f32_16x16x32_bf16 v[112:115], v[172:175], v[206:209], v[112:115]
	v_mfma_f32_16x16x32_bf16 v[100:103], v[164:167], v[214:217], v[100:103]
	v_mfma_f32_16x16x32_bf16 v[96:99], v[172:175], v[214:217], v[96:99]
	v_mfma_f32_16x16x32_bf16 v[84:87], v[164:167], v[222:225], v[84:87]
	v_mfma_f32_16x16x32_bf16 v[80:83], v[172:175], v[222:225], v[80:83]
	s_setprio 0
	s_setprio 1
	v_mfma_f32_16x16x32_bf16 v[108:111], v[176:179], v[194:197], v[108:111]
	v_mfma_f32_16x16x32_bf16 v[104:107], v[186:189], v[194:197], v[104:107]
	v_mfma_f32_16x16x32_bf16 v[92:95], v[176:179], v[202:205], v[92:95]
	v_mfma_f32_16x16x32_bf16 v[88:91], v[186:189], v[202:205], v[88:91]
	v_mfma_f32_16x16x32_bf16 v[76:79], v[176:179], v[210:213], v[76:79]
	v_mfma_f32_16x16x32_bf16 v[72:75], v[186:189], v[210:213], v[72:75]
	v_mfma_f32_16x16x32_bf16 v[68:71], v[176:179], v[218:221], v[68:71]
	v_mfma_f32_16x16x32_bf16 v[64:67], v[186:189], v[218:221], v[64:67]
	v_mfma_f32_16x16x32_bf16 v[108:111], v[180:183], v[198:201], v[108:111]
	v_mfma_f32_16x16x32_bf16 v[104:107], v[190:193], v[198:201], v[104:107]
	v_mfma_f32_16x16x32_bf16 v[92:95], v[180:183], v[206:209], v[92:95]
	v_mfma_f32_16x16x32_bf16 v[88:91], v[190:193], v[206:209], v[88:91]
	v_mfma_f32_16x16x32_bf16 v[76:79], v[180:183], v[214:217], v[76:79]
	v_mfma_f32_16x16x32_bf16 v[72:75], v[190:193], v[214:217], v[72:75]
	v_mfma_f32_16x16x32_bf16 v[68:71], v[180:183], v[222:225], v[68:71]
	v_mfma_f32_16x16x32_bf16 v[64:67], v[190:193], v[222:225], v[64:67]
	s_setprio 0
	s_barrier
; #define PG8_STAGE(bufoff, gbase, voff) do { _Pragma("unroll") for (int _i = 0; _i < 2; ++_i) \
;         __builtin_amdgcn_global_load_lds((const unsigned*)((const char*)(gbase) + (voff)[_i]), (PG8_LAS unsigned*)(lds + (bufoff) + ldsw + _i * 8192), 16, 0, 0); } while (0)
; #define PG8_LDA(dst, b, h) do { _Pragma("unroll") for (int m = 0; m < 4; ++m) _Pragma("unroll") for (int k = 0; k < 2; ++k) dst[m][k] = *(const PG8_LAS bf16x8*)(lds + PG8_SA(b, h) + aoff + m * 2048 + k * 1024); } while (0)
; #define PG8_MMA(ai, bj, At, Bt) do { __builtin_amdgcn_s_setprio(1); _Pragma("unroll") for (int m = 0; m < 4; ++m) _Pragma("unroll") for (int n = 0; n < 2; ++n) _Pragma("unroll") for (int k = 0; k < 2; ++k) \
;         acc[ai][bj][m][n] = __builtin_amdgcn_mfma_f32_16x16x32_bf16(Bt[n][k], At[m][k], acc[ai][bj][m][n], 0, 0, 0); __builtin_amdgcn_s_setprio(0); } while (0)
; #define PG8_WAIT_V(n) asm volatile("s_waitcnt vmcnt(" #n ")" ::: "memory")
; #define PG8_WAIT_L(n) asm volatile("s_waitcnt lgkmcnt(" #n ")" ::: "memory")
; #define PG8_BAR __builtin_amdgcn_s_barrier()
; #define PG8_SCHED __builtin_amdgcn_sched_barrier(0)
; template <class Epi, class Sched, bool ALIGN_EPI = false, bool SP2 = false>
; __device__ __forceinline__ void gemm_phase(PG8_LAS unsigned char* lds, const Gemm g, const Sched& S, const Epi& E) {
;     ...
;         for (int t = 0; t < nt; t += 2) {
;     ...
;             PG8_LDA(At, 1, 1); PG8_STAGE(PG8_SB(1, 0), b3, voffB); PG8_STAGE(PG8_SB(1, 1), b3 + hstep, voffB); PG8_STAGE(PG8_SA(1, 0), a3, voffA);
;             PG8_WAIT_V(8); PG8_WAIT_L(0); PG8_BAR; PG8_MMA(1, 0, At, B0); PG8_MMA(1, 1, At, B1); PG8_BAR; PG8_SCHED;
	s_mov_b32 m0, s72
	ds_read_b128 v[194:197], v141 offset:49152
	ds_read_b128 v[198:201], v141 offset:50176
	ds_read_b128 v[202:205], v141 offset:51200
	ds_read_b128 v[206:209], v141 offset:52224
	ds_read_b128 v[210:213], v141 offset:53248
	ds_read_b128 v[214:217], v141 offset:54272
	ds_read_b128 v[218:221], v141 offset:55296
	ds_read_b128 v[222:225], v141 offset:56320
	global_load_lds_dwordx4 v132, s[88:89]
	s_mov_b32 m0, s73
	s_nop 0
	global_load_lds_dwordx4 v128, s[88:89]
	s_mov_b32 m0, s76
	s_nop 0
	global_load_lds_dwordx4 v132, s[56:57]
	s_mov_b32 m0, s77
	s_nop 0
	global_load_lds_dwordx4 v128, s[56:57]
	s_mov_b32 m0, s74
	s_nop 0
	global_load_lds_dwordx4 v134, s[90:91]
	s_mov_b32 m0, s75
	s_nop 0
	global_load_lds_dwordx4 v130, s[90:91]
	s_waitcnt vmcnt(8)
	s_waitcnt lgkmcnt(0)
	s_barrier
	s_setprio 1
	s_waitcnt lgkmcnt(0)
	v_mfma_f32_16x16x32_bf16 v[60:63], v[160:163], v[194:197], v[60:63]
	v_mfma_f32_16x16x32_bf16 v[56:59], v[168:171], v[194:197], v[56:59]
	v_mfma_f32_16x16x32_bf16 v[52:55], v[160:163], v[202:205], v[52:55]
	v_mfma_f32_16x16x32_bf16 v[48:51], v[168:171], v[202:205], v[48:51]
	v_mfma_f32_16x16x32_bf16 v[36:39], v[160:163], v[210:213], v[36:39]
	v_mfma_f32_16x16x32_bf16 v[32:35], v[168:171], v[210:213], v[32:35]
	v_mfma_f32_16x16x32_bf16 v[20:23], v[160:163], v[218:221], v[20:23]
	v_mfma_f32_16x16x32_bf16 v[16:19], v[168:171], v[218:221], v[16:19]
	v_mfma_f32_16x16x32_bf16 v[60:63], v[164:167], v[198:201], v[60:63]
	v_mfma_f32_16x16x32_bf16 v[56:59], v[172:175], v[198:201], v[56:59]
	v_mfma_f32_16x16x32_bf16 v[52:55], v[164:167], v[206:209], v[52:55]
	v_mfma_f32_16x16x32_bf16 v[48:51], v[172:175], v[206:209], v[48:51]
	v_mfma_f32_16x16x32_bf16 v[36:39], v[164:167], v[214:217], v[36:39]
	v_mfma_f32_16x16x32_bf16 v[32:35], v[172:175], v[214:217], v[32:35]
	v_mfma_f32_16x16x32_bf16 v[20:23], v[164:167], v[222:225], v[20:23]
	v_mfma_f32_16x16x32_bf16 v[16:19], v[172:175], v[222:225], v[16:19]
	s_setprio 0
	s_setprio 1
	v_mfma_f32_16x16x32_bf16 v[44:47], v[176:179], v[194:197], v[44:47]
	v_mfma_f32_16x16x32_bf16 v[40:43], v[186:189], v[194:197], v[40:43]
	v_mfma_f32_16x16x32_bf16 v[28:31], v[176:179], v[202:205], v[28:31]
	v_mfma_f32_16x16x32_bf16 v[24:27], v[186:189], v[202:205], v[24:27]
	v_mfma_f32_16x16x32_bf16 v[12:15], v[176:179], v[210:213], v[12:15]
	v_mfma_f32_16x16x32_bf16 v[8:11], v[186:189], v[210:213], v[8:11]
	v_mfma_f32_16x16x32_bf16 v[4:7], v[176:179], v[218:221], v[4:7]
	v_mfma_f32_16x16x32_bf16 v[0:3], v[186:189], v[218:221], v[0:3]
	v_mfma_f32_16x16x32_bf16 v[44:47], v[180:183], v[198:201], v[44:47]
	v_mfma_f32_16x16x32_bf16 v[40:43], v[190:193], v[198:201], v[40:43]
	v_mfma_f32_16x16x32_bf16 v[28:31], v[180:183], v[206:209], v[28:31]
	v_mfma_f32_16x16x32_bf16 v[24:27], v[190:193], v[206:209], v[24:27]
	v_mfma_f32_16x16x32_bf16 v[12:15], v[180:183], v[214:217], v[12:15]
	v_mfma_f32_16x16x32_bf16 v[8:11], v[190:193], v[214:217], v[8:11]
	v_mfma_f32_16x16x32_bf16 v[4:7], v[180:183], v[222:225], v[4:7]
	v_mfma_f32_16x16x32_bf16 v[0:3], v[190:193], v[222:225], v[0:3]
	s_setprio 0
	s_barrier
	s_movk_i32 s52, 0x100
	s_andn2_b64 vcc, exec, s[46:47]
	s_mov_b64 s[48:49], -1
	s_mov_b64 s[46:47], 0
	s_cbranch_vccz .LBB0_645
	s_and_b64 vcc, exec, s[16:17]
	s_cbranch_vccz .LBB0_648
	s_barrier

; #define PG8_STAGE(bufoff, gbase, voff) do { _Pragma("unroll") for (int _i = 0; _i < 2; ++_i) \
;         __builtin_amdgcn_global_load_lds((const unsigned*)((const char*)(gbase) + (voff)[_i]), (PG8_LAS unsigned*)(lds + (bufoff) + ldsw + _i * 8192), 16, 0, 0); } while (0)
; #define PG8_LDA(dst, b, h) do { _Pragma("unroll") for (int m = 0; m < 4; ++m) _Pragma("unroll") for (int k = 0; k < 2; ++k) dst[m][k] = *(const PG8_LAS bf16x8*)(lds + PG8_SA(b, h) + aoff + m * 2048 + k * 1024); } while (0)
; #define PG8_LDB(dst, b, h) do { _Pragma("unroll") for (int n = 0; n < 2; ++n) _Pragma("unroll") for (int k = 0; k < 2; ++k) dst[n][k] = *(const PG8_LAS bf16x8*)(lds + PG8_SB(b, h) + boff + n * 2048 + k * 1024); } while (0)
; #define PG8_MMA(ai, bj, At, Bt) do { __builtin_amdgcn_s_setprio(1); _Pragma("unroll") for (int m = 0; m < 4; ++m) _Pragma("unroll") for (int n = 0; n < 2; ++n) _Pragma("unroll") for (int k = 0; k < 2; ++k) \
;         acc[ai][bj][m][n] = __builtin_amdgcn_mfma_f32_16x16x32_bf16(Bt[n][k], At[m][k], acc[ai][bj][m][n], 0, 0, 0); __builtin_amdgcn_s_setprio(0); } while (0)
; #define PG8_WAIT_V(n) asm volatile("s_waitcnt vmcnt(" #n ")" ::: "memory")
; #define PG8_WAIT_L(n) asm volatile("s_waitcnt lgkmcnt(" #n ")" ::: "memory")
; #define PG8_BAR __builtin_amdgcn_s_barrier()
; #define PG8_SCHED __builtin_amdgcn_sched_barrier(0)
; template <class Epi, class Sched, bool ALIGN_EPI = false, bool SP2 = false>
; __device__ __forceinline__ void gemm_phase(PG8_LAS unsigned char* lds, const Gemm g, const Sched& S, const Epi& E) {
;     ...
;             PG8_LDB(B0, 0, 0); PG8_LDB(B1, 0, 1); PG8_SCHED; PG8_LDA(At, 0, 0); PG8_STAGE(PG8_SA(1, 1), a1 + hstep, voffA);
;             PG8_WAIT_V(8); PG8_WAIT_L(0); PG8_BAR; PG8_MMA(0, 0, At, B0); PG8_MMA(0, 1, At, B1); PG8_BAR; PG8_SCHED;
;             PG8_LDA(At, 0, 1); PG8_STAGE(PG8_SB(0, 0), b2, voffB); PG8_STAGE(PG8_SB(0, 1), b2 + hstep, voffB); PG8_STAGE(PG8_SA(0, 0), a2, voffA);
;             PG8_WAIT_V(8); PG8_WAIT_L(0); PG8_BAR; PG8_MMA(1, 0, At, B0); PG8_MMA(1, 1, At, B1); PG8_BAR; PG8_SCHED;
.LBB0_671:
	ds_read_b128 v[128:131], v161
	ds_read_b128 v[132:135], v162
	ds_read_b128 v[152:155], v163
	ds_read_b128 v[180:183], v164
	ds_read_b128 v[186:189], v165
	ds_read_b128 v[190:193], v166
	ds_read_b128 v[194:197], v167
	ds_read_b128 v[198:201], v168
	s_add_u32 s12, s10, 0xfffc0080
	s_addc_u32 s13, s11, -1
	s_cmp_eq_u32 s75, 12
	s_cselect_b32 s49, s9, s13
	s_cselect_b32 s48, s43, s12
	s_cselect_b32 s13, s37, s74
	s_cselect_b32 s12, s72, s73
	s_mov_b32 m0, s68
	ds_read_b128 v[202:205], v159
	ds_read_b128 v[206:209], v159 offset:1024
	ds_read_b128 v[210:213], v159 offset:2048
	ds_read_b128 v[214:217], v159 offset:3072
	ds_read_b128 v[218:221], v159 offset:4096
	ds_read_b128 v[222:225], v159 offset:5120
	ds_read_b128 v[226:229], v159 offset:6144
	ds_read_b128 v[230:233], v159 offset:7168
	global_load_lds_dwordx4 v146, s[10:11]
	s_mov_b32 m0, s69
	s_nop 0
	global_load_lds_dwordx4 v144, s[10:11]
	s_waitcnt vmcnt(8)
	s_waitcnt lgkmcnt(0)
	s_barrier
	s_setprio 1
	s_waitcnt lgkmcnt(0)
	v_mfma_f32_16x16x32_bf16 v[124:127], v[128:131], v[202:205], v[124:127]
	v_mfma_f32_16x16x32_bf16 v[120:123], v[152:155], v[202:205], v[120:123]
	v_mfma_f32_16x16x32_bf16 v[108:111], v[128:131], v[210:213], v[108:111]
	v_mfma_f32_16x16x32_bf16 v[104:107], v[152:155], v[210:213], v[104:107]
	v_mfma_f32_16x16x32_bf16 v[92:95], v[128:131], v[218:221], v[92:95]
	v_mfma_f32_16x16x32_bf16 v[88:91], v[152:155], v[218:221], v[88:91]
	v_mfma_f32_16x16x32_bf16 v[76:79], v[128:131], v[226:229], v[76:79]
	v_mfma_f32_16x16x32_bf16 v[72:75], v[152:155], v[226:229], v[72:75]
	v_mfma_f32_16x16x32_bf16 v[124:127], v[132:135], v[206:209], v[124:127]
	v_mfma_f32_16x16x32_bf16 v[120:123], v[180:183], v[206:209], v[120:123]
	v_mfma_f32_16x16x32_bf16 v[108:111], v[132:135], v[214:217], v[108:111]
	v_mfma_f32_16x16x32_bf16 v[104:107], v[180:183], v[214:217], v[104:107]
	v_mfma_f32_16x16x32_bf16 v[92:95], v[132:135], v[222:225], v[92:95]
	v_mfma_f32_16x16x32_bf16 v[88:91], v[180:183], v[222:225], v[88:91]
	v_mfma_f32_16x16x32_bf16 v[76:79], v[132:135], v[230:233], v[76:79]
	v_mfma_f32_16x16x32_bf16 v[72:75], v[180:183], v[230:233], v[72:75]
	s_setprio 0
	s_setprio 1
	v_mfma_f32_16x16x32_bf16 v[116:119], v[186:189], v[202:205], v[116:119]
	v_mfma_f32_16x16x32_bf16 v[112:115], v[194:197], v[202:205], v[112:115]
	v_mfma_f32_16x16x32_bf16 v[100:103], v[186:189], v[210:213], v[100:103]
	v_mfma_f32_16x16x32_bf16 v[96:99], v[194:197], v[210:213], v[96:99]
	v_mfma_f32_16x16x32_bf16 v[84:87], v[186:189], v[218:221], v[84:87]
	v_mfma_f32_16x16x32_bf16 v[80:83], v[194:197], v[218:221], v[80:83]
	v_mfma_f32_16x16x32_bf16 v[68:71], v[186:189], v[226:229], v[68:71]
	v_mfma_f32_16x16x32_bf16 v[64:67], v[194:197], v[226:229], v[64:67]
	v_mfma_f32_16x16x32_bf16 v[116:119], v[190:193], v[206:209], v[116:119]
	v_mfma_f32_16x16x32_bf16 v[112:115], v[198:201], v[206:209], v[112:115]
	v_mfma_f32_16x16x32_bf16 v[100:103], v[190:193], v[214:217], v[100:103]
	v_mfma_f32_16x16x32_bf16 v[96:99], v[198:201], v[214:217], v[96:99]
	v_mfma_f32_16x16x32_bf16 v[84:87], v[190:193], v[222:225], v[84:87]
	v_mfma_f32_16x16x32_bf16 v[80:83], v[198:201], v[222:225], v[80:83]
	v_mfma_f32_16x16x32_bf16 v[68:71], v[190:193], v[230:233], v[68:71]
	v_mfma_f32_16x16x32_bf16 v[64:67], v[198:201], v[230:233], v[64:67]
	s_setprio 0
	s_barrier
	s_add_u32 s88, s12, 0x80
	s_addc_u32 s89, s13, 0
	s_add_u32 s90, s48, 0x80
	s_addc_u32 s91, s49, 0
	s_mov_b32 m0, s52
	s_add_u32 s76, s12, 0x40000
	ds_read_b128 v[202:205], v159 offset:16384
	ds_read_b128 v[206:209], v159 offset:17408
	ds_read_b128 v[210:213], v159 offset:18432
	ds_read_b128 v[214:217], v159 offset:19456
	ds_read_b128 v[218:221], v159 offset:20480
	ds_read_b128 v[222:225], v159 offset:21504
	ds_read_b128 v[226:229], v159 offset:22528
	ds_read_b128 v[230:233], v159 offset:23552
	global_load_lds_dwordx4 v138, s[12:13]
	s_mov_b32 m0, s53
	s_addc_u32 s77, s13, 0
	global_load_lds_dwordx4 v142, s[12:13]
	s_mov_b32 m0, s54
	s_nop 0
	global_load_lds_dwordx4 v138, s[76:77]
	s_mov_b32 m0, s55
	s_nop 0
	global_load_lds_dwordx4 v142, s[76:77]
	s_mov_b32 m0, s51
	s_nop 0
	global_load_lds_dwordx4 v136, s[48:49]
	s_mov_b32 m0, s56
	s_nop 0
	global_load_lds_dwordx4 v140, s[48:49]
	s_waitcnt vmcnt(8)
	s_waitcnt lgkmcnt(0)
	s_barrier
	s_setprio 1
	s_waitcnt lgkmcnt(0)
	v_mfma_f32_16x16x32_bf16 v[60:63], v[128:131], v[202:205], v[60:63]
	v_mfma_f32_16x16x32_bf16 v[56:59], v[152:155], v[202:205], v[56:59]
	v_mfma_f32_16x16x32_bf16 v[44:47], v[128:131], v[210:213], v[44:47]
	v_mfma_f32_16x16x32_bf16 v[40:43], v[152:155], v[210:213], v[40:43]
	v_mfma_f32_16x16x32_bf16 v[28:31], v[128:131], v[218:221], v[28:31]
	v_mfma_f32_16x16x32_bf16 v[24:27], v[152:155], v[218:221], v[24:27]
	v_mfma_f32_16x16x32_bf16 v[12:15], v[128:131], v[226:229], v[12:15]
	v_mfma_f32_16x16x32_bf16 v[8:11], v[152:155], v[226:229], v[8:11]
	v_mfma_f32_16x16x32_bf16 v[60:63], v[132:135], v[206:209], v[60:63]
	v_mfma_f32_16x16x32_bf16 v[56:59], v[180:183], v[206:209], v[56:59]
	v_mfma_f32_16x16x32_bf16 v[44:47], v[132:135], v[214:217], v[44:47]
	v_mfma_f32_16x16x32_bf16 v[40:43], v[180:183], v[214:217], v[40:43]
	v_mfma_f32_16x16x32_bf16 v[28:31], v[132:135], v[222:225], v[28:31]
	v_mfma_f32_16x16x32_bf16 v[24:27], v[180:183], v[222:225], v[24:27]
	v_mfma_f32_16x16x32_bf16 v[12:15], v[132:135], v[230:233], v[12:15]
	v_mfma_f32_16x16x32_bf16 v[8:11], v[180:183], v[230:233], v[8:11]
	s_setprio 0
	s_setprio 1
	v_mfma_f32_16x16x32_bf16 v[52:55], v[186:189], v[202:205], v[52:55]
	v_mfma_f32_16x16x32_bf16 v[48:51], v[194:197], v[202:205], v[48:51]
	v_mfma_f32_16x16x32_bf16 v[36:39], v[186:189], v[210:213], v[36:39]
	v_mfma_f32_16x16x32_bf16 v[32:35], v[194:197], v[210:213], v[32:35]
	v_mfma_f32_16x16x32_bf16 v[20:23], v[186:189], v[218:221], v[20:23]
	v_mfma_f32_16x16x32_bf16 v[16:19], v[194:197], v[218:221], v[16:19]
	v_mfma_f32_16x16x32_bf16 v[4:7], v[186:189], v[226:229], v[4:7]
	v_mfma_f32_16x16x32_bf16 v[0:3], v[194:197], v[226:229], v[0:3]
	v_mfma_f32_16x16x32_bf16 v[52:55], v[190:193], v[206:209], v[52:55]
	v_mfma_f32_16x16x32_bf16 v[48:51], v[198:201], v[206:209], v[48:51]
	v_mfma_f32_16x16x32_bf16 v[36:39], v[190:193], v[214:217], v[36:39]
	v_mfma_f32_16x16x32_bf16 v[32:35], v[198:201], v[214:217], v[32:35]
	v_mfma_f32_16x16x32_bf16 v[20:23], v[190:193], v[222:225], v[20:23]
	v_mfma_f32_16x16x32_bf16 v[16:19], v[198:201], v[222:225], v[16:19]
	v_mfma_f32_16x16x32_bf16 v[4:7], v[190:193], v[230:233], v[4:7]
	v_mfma_f32_16x16x32_bf16 v[0:3], v[198:201], v[230:233], v[0:3]
	s_setprio 0
	s_barrier
; #define PG8_STAGE(bufoff, gbase, voff) do { _Pragma("unroll") for (int _i = 0; _i < 2; ++_i) \
;         __builtin_amdgcn_global_load_lds((const unsigned*)((const char*)(gbase) + (voff)[_i]), (PG8_LAS unsigned*)(lds + (bufoff) + ldsw + _i * 8192), 16, 0, 0); } while (0)
; #define PG8_LDA(dst, b, h) do { _Pragma("unroll") for (int m = 0; m < 4; ++m) _Pragma("unroll") for (int k = 0; k < 2; ++k) dst[m][k] = *(const PG8_LAS bf16x8*)(lds + PG8_SA(b, h) + aoff + m * 2048 + k * 1024); } while (0)
; #define PG8_LDB(dst, b, h) do { _Pragma("unroll") for (int n = 0; n < 2; ++n) _Pragma("unroll") for (int k = 0; k < 2; ++k) dst[n][k] = *(const PG8_LAS bf16x8*)(lds + PG8_SB(b, h) + boff + n * 2048 + k * 1024); } while (0)
; #define PG8_MMA(ai, bj, At, Bt) do { __builtin_amdgcn_s_setprio(1); _Pragma("unroll") for (int m = 0; m < 4; ++m) _Pragma("unroll") for (int n = 0; n < 2; ++n) _Pragma("unroll") for (int k = 0; k < 2; ++k) \
;         acc[ai][bj][m][n] = __builtin_amdgcn_mfma_f32_16x16x32_bf16(Bt[n][k], At[m][k], acc[ai][bj][m][n], 0, 0, 0); __builtin_amdgcn_s_setprio(0); } while (0)
; #define PG8_WAIT_V(n) asm volatile("s_waitcnt vmcnt(" #n ")" ::: "memory")
; #define PG8_WAIT_L(n) asm volatile("s_waitcnt lgkmcnt(" #n ")" ::: "memory")
; #define PG8_BAR __builtin_amdgcn_s_barrier()
; #define PG8_SCHED __builtin_amdgcn_sched_barrier(0)
; template <class Epi, class Sched, bool ALIGN_EPI = false, bool SP2 = false>
; __device__ __forceinline__ void gemm_phase(PG8_LAS unsigned char* lds, const Gemm g, const Sched& S, const Epi& E) {
;     ...
;         for (int t = 0; t < nt; t += 2) {
;     ...
;             PG8_LDB(B0, 1, 0); PG8_LDB(B1, 1, 1); PG8_SCHED; PG8_LDA(At, 1, 0); PG8_STAGE(PG8_SA(0, 1), a2 + hstep, voffA);
;             PG8_WAIT_V(8); PG8_WAIT_L(0); PG8_BAR; PG8_MMA(0, 0, At, B0); PG8_MMA(0, 1, At, B1); PG8_BAR; PG8_SCHED;
;             PG8_LDA(At, 1, 1); PG8_STAGE(PG8_SB(1, 0), b3, voffB); PG8_STAGE(PG8_SB(1, 1), b3 + hstep, voffB); PG8_STAGE(PG8_SA(1, 0), a3, voffA);
;             PG8_WAIT_V(8); PG8_WAIT_L(0); PG8_BAR; PG8_MMA(1, 0, At, B0); PG8_MMA(1, 1, At, B1); PG8_BAR; PG8_SCHED;
	ds_read_b128 v[128:131], v169
	ds_read_b128 v[132:135], v170
	ds_read_b128 v[152:155], v171
	ds_read_b128 v[180:183], v172
	ds_read_b128 v[186:189], v173
	ds_read_b128 v[190:193], v174
	ds_read_b128 v[194:197], v175
	ds_read_b128 v[198:201], v176
	s_add_u32 s48, s48, 0x40000
	s_addc_u32 s49, s49, 0
	s_mov_b32 m0, s57
	ds_read_b128 v[202:205], v159 offset:32768
	ds_read_b128 v[206:209], v159 offset:33792
	ds_read_b128 v[210:213], v159 offset:34816
	ds_read_b128 v[214:217], v159 offset:35840
	ds_read_b128 v[218:221], v159 offset:36864
	ds_read_b128 v[222:225], v159 offset:37888
	ds_read_b128 v[226:229], v159 offset:38912
	ds_read_b128 v[230:233], v159 offset:39936
	global_load_lds_dwordx4 v136, s[48:49]
	s_mov_b32 m0, s58
	s_nop 0
	global_load_lds_dwordx4 v140, s[48:49]
	s_waitcnt vmcnt(8)
	s_waitcnt lgkmcnt(0)
	s_barrier
	s_setprio 1
	s_waitcnt lgkmcnt(0)
	v_mfma_f32_16x16x32_bf16 v[124:127], v[128:131], v[202:205], v[124:127]
	v_mfma_f32_16x16x32_bf16 v[120:123], v[152:155], v[202:205], v[120:123]
	v_mfma_f32_16x16x32_bf16 v[108:111], v[128:131], v[210:213], v[108:111]
	v_mfma_f32_16x16x32_bf16 v[104:107], v[152:155], v[210:213], v[104:107]
	v_mfma_f32_16x16x32_bf16 v[92:95], v[128:131], v[218:221], v[92:95]
	v_mfma_f32_16x16x32_bf16 v[88:91], v[152:155], v[218:221], v[88:91]
	v_mfma_f32_16x16x32_bf16 v[76:79], v[128:131], v[226:229], v[76:79]
	v_mfma_f32_16x16x32_bf16 v[72:75], v[152:155], v[226:229], v[72:75]
	v_mfma_f32_16x16x32_bf16 v[124:127], v[132:135], v[206:209], v[124:127]
	v_mfma_f32_16x16x32_bf16 v[120:123], v[180:183], v[206:209], v[120:123]
	v_mfma_f32_16x16x32_bf16 v[108:111], v[132:135], v[214:217], v[108:111]
	v_mfma_f32_16x16x32_bf16 v[104:107], v[180:183], v[214:217], v[104:107]
	v_mfma_f32_16x16x32_bf16 v[92:95], v[132:135], v[222:225], v[92:95]
	v_mfma_f32_16x16x32_bf16 v[88:91], v[180:183], v[222:225], v[88:91]
	v_mfma_f32_16x16x32_bf16 v[76:79], v[132:135], v[230:233], v[76:79]
	v_mfma_f32_16x16x32_bf16 v[72:75], v[180:183], v[230:233], v[72:75]
	s_setprio 0
	s_setprio 1
	v_mfma_f32_16x16x32_bf16 v[116:119], v[186:189], v[202:205], v[116:119]
	v_mfma_f32_16x16x32_bf16 v[112:115], v[194:197], v[202:205], v[112:115]
	v_mfma_f32_16x16x32_bf16 v[100:103], v[186:189], v[210:213], v[100:103]
	v_mfma_f32_16x16x32_bf16 v[96:99], v[194:197], v[210:213], v[96:99]
	v_mfma_f32_16x16x32_bf16 v[84:87], v[186:189], v[218:221], v[84:87]
	v_mfma_f32_16x16x32_bf16 v[80:83], v[194:197], v[218:221], v[80:83]
	v_mfma_f32_16x16x32_bf16 v[68:71], v[186:189], v[226:229], v[68:71]
	v_mfma_f32_16x16x32_bf16 v[64:67], v[194:197], v[226:229], v[64:67]
	v_mfma_f32_16x16x32_bf16 v[116:119], v[190:193], v[206:209], v[116:119]
	v_mfma_f32_16x16x32_bf16 v[112:115], v[198:201], v[206:209], v[112:115]
	v_mfma_f32_16x16x32_bf16 v[100:103], v[190:193], v[214:217], v[100:103]
	v_mfma_f32_16x16x32_bf16 v[96:99], v[198:201], v[214:217], v[96:99]
	v_mfma_f32_16x16x32_bf16 v[84:87], v[190:193], v[222:225], v[84:87]
	v_mfma_f32_16x16x32_bf16 v[80:83], v[198:201], v[222:225], v[80:83]
	v_mfma_f32_16x16x32_bf16 v[68:71], v[190:193], v[230:233], v[68:71]
	v_mfma_f32_16x16x32_bf16 v[64:67], v[198:201], v[230:233], v[64:67]
	s_setprio 0
	s_barrier
	s_mov_b32 m0, s60
	s_add_u32 s12, s12, 0x40080
	ds_read_b128 v[202:205], v159 offset:49152
	ds_read_b128 v[206:209], v159 offset:50176
	ds_read_b128 v[210:213], v159 offset:51200
	ds_read_b128 v[214:217], v159 offset:52224
	ds_read_b128 v[218:221], v159 offset:53248
	ds_read_b128 v[222:225], v159 offset:54272
	ds_read_b128 v[226:229], v159 offset:55296
	ds_read_b128 v[230:233], v159 offset:56320
	global_load_lds_dwordx4 v138, s[88:89]
	s_mov_b32 m0, s61
	s_addc_u32 s13, s13, 0
	global_load_lds_dwordx4 v142, s[88:89]
	s_mov_b32 m0, s64
	s_nop 0
	global_load_lds_dwordx4 v138, s[12:13]
	s_mov_b32 m0, s65
	s_nop 0
	global_load_lds_dwordx4 v142, s[12:13]
	s_mov_b32 m0, s62
	s_nop 0
	global_load_lds_dwordx4 v136, s[90:91]
	s_mov_b32 m0, s63
	s_nop 0
	global_load_lds_dwordx4 v140, s[90:91]
	s_waitcnt vmcnt(8)
	s_waitcnt lgkmcnt(0)
	s_barrier
	s_setprio 1
	s_waitcnt lgkmcnt(0)
	v_mfma_f32_16x16x32_bf16 v[60:63], v[128:131], v[202:205], v[60:63]
	v_mfma_f32_16x16x32_bf16 v[56:59], v[152:155], v[202:205], v[56:59]
	v_mfma_f32_16x16x32_bf16 v[44:47], v[128:131], v[210:213], v[44:47]
	v_mfma_f32_16x16x32_bf16 v[40:43], v[152:155], v[210:213], v[40:43]
	v_mfma_f32_16x16x32_bf16 v[28:31], v[128:131], v[218:221], v[28:31]
	v_mfma_f32_16x16x32_bf16 v[24:27], v[152:155], v[218:221], v[24:27]
	v_mfma_f32_16x16x32_bf16 v[12:15], v[128:131], v[226:229], v[12:15]
	v_mfma_f32_16x16x32_bf16 v[8:11], v[152:155], v[226:229], v[8:11]
	v_mfma_f32_16x16x32_bf16 v[60:63], v[132:135], v[206:209], v[60:63]
	v_mfma_f32_16x16x32_bf16 v[56:59], v[180:183], v[206:209], v[56:59]
	v_mfma_f32_16x16x32_bf16 v[44:47], v[132:135], v[214:217], v[44:47]
	v_mfma_f32_16x16x32_bf16 v[40:43], v[180:183], v[214:217], v[40:43]
	v_mfma_f32_16x16x32_bf16 v[28:31], v[132:135], v[222:225], v[28:31]
	v_mfma_f32_16x16x32_bf16 v[24:27], v[180:183], v[222:225], v[24:27]
	v_mfma_f32_16x16x32_bf16 v[12:15], v[132:135], v[230:233], v[12:15]
	v_mfma_f32_16x16x32_bf16 v[8:11], v[180:183], v[230:233], v[8:11]
	s_setprio 0
	s_setprio 1
	v_mfma_f32_16x16x32_bf16 v[52:55], v[186:189], v[202:205], v[52:55]
	v_mfma_f32_16x16x32_bf16 v[48:51], v[194:197], v[202:205], v[48:51]
	v_mfma_f32_16x16x32_bf16 v[36:39], v[186:189], v[210:213], v[36:39]
	v_mfma_f32_16x16x32_bf16 v[32:35], v[194:197], v[210:213], v[32:35]
	v_mfma_f32_16x16x32_bf16 v[20:23], v[186:189], v[218:221], v[20:23]
	v_mfma_f32_16x16x32_bf16 v[16:19], v[194:197], v[218:221], v[16:19]
	v_mfma_f32_16x16x32_bf16 v[4:7], v[186:189], v[226:229], v[4:7]
	v_mfma_f32_16x16x32_bf16 v[0:3], v[194:197], v[226:229], v[0:3]
	v_mfma_f32_16x16x32_bf16 v[52:55], v[190:193], v[206:209], v[52:55]
	v_mfma_f32_16x16x32_bf16 v[48:51], v[198:201], v[206:209], v[48:51]
	v_mfma_f32_16x16x32_bf16 v[36:39], v[190:193], v[214:217], v[36:39]
	v_mfma_f32_16x16x32_bf16 v[32:35], v[198:201], v[214:217], v[32:35]
	v_mfma_f32_16x16x32_bf16 v[20:23], v[190:193], v[222:225], v[20:23]
	v_mfma_f32_16x16x32_bf16 v[16:19], v[198:201], v[222:225], v[16:19]
	v_mfma_f32_16x16x32_bf16 v[4:7], v[190:193], v[230:233], v[4:7]
	v_mfma_f32_16x16x32_bf16 v[0:3], v[198:201], v[230:233], v[0:3]
	s_setprio 0
	s_barrier
	s_add_i32 s75, s75, 2
	s_add_u32 s73, s73, 0x100
	s_addc_u32 s74, s74, 0
	s_add_u32 s10, s10, 0x100
	s_addc_u32 s11, s11, 0
	s_cmp_gt_u32 s75, 13
	s_cbranch_scc0 .LBB0_671
	s_and_b64 vcc, exec, s[30:31]
	s_cbranch_vccz .LBB0_674
	s_barrier

; #define PG8_STAGE(bufoff, gbase, voff) do { _Pragma("unroll") for (int _i = 0; _i < 2; ++_i) \
;         __builtin_amdgcn_global_load_lds((const unsigned*)((const char*)(gbase) + (voff)[_i]), (PG8_LAS unsigned*)(lds + (bufoff) + ldsw + _i * 8192), 16, 0, 0); } while (0)
; #define PG8_LDA(dst, b, h) do { _Pragma("unroll") for (int m = 0; m < 4; ++m) _Pragma("unroll") for (int k = 0; k < 2; ++k) dst[m][k] = *(const PG8_LAS bf16x8*)(lds + PG8_SA(b, h) + aoff + m * 2048 + k * 1024); } while (0)
; #define PG8_LDB(dst, b, h) do { _Pragma("unroll") for (int n = 0; n < 2; ++n) _Pragma("unroll") for (int k = 0; k < 2; ++k) dst[n][k] = *(const PG8_LAS bf16x8*)(lds + PG8_SB(b, h) + boff + n * 2048 + k * 1024); } while (0)
; #define PG8_MMA(ai, bj, At, Bt) do { __builtin_amdgcn_s_setprio(1); _Pragma("unroll") for (int m = 0; m < 4; ++m) _Pragma("unroll") for (int n = 0; n < 2; ++n) _Pragma("unroll") for (int k = 0; k < 2; ++k) \
;         acc[ai][bj][m][n] = __builtin_amdgcn_mfma_f32_16x16x32_bf16(Bt[n][k], At[m][k], acc[ai][bj][m][n], 0, 0, 0); __builtin_amdgcn_s_setprio(0); } while (0)
; #define PG8_WAIT_V(n) asm volatile("s_waitcnt vmcnt(" #n ")" ::: "memory")
; #define PG8_WAIT_L(n) asm volatile("s_waitcnt lgkmcnt(" #n ")" ::: "memory")
; template <class Epi, class Sched, bool ALIGN_EPI = false, bool SP2 = false>
; __device__ __forceinline__ void gemm_phase(PG8_LAS unsigned char* lds, const Gemm g, const Sched& S, const Epi& E) {
;     ...
;             const bool last = (t == nt - 2);
;             const char* a1 = cA + (size_t)(t + 1) * kstep;
;             const char* a2 = last ? nA : cA + (size_t)(t + 2) * kstep; const char* b2 = last ? nB : cB + (size_t)(t + 2) * kstep;
;             const char* a3 = a2 + kstep; const char* b3 = b2 + kstep;
;             if (last && has_next) S.a_ready(nxt);
;             if constexpr (SP2) {
;             PG8_LDB(B0, 0, 0); PG8_LDB(B1, 0, 1); PG8_SCHED; PG8_LDA(At, 0, 0); PG8_STAGE(PG8_SA(1, 1), a1 + hstep, voffA);
;             PG8_WAIT_V(8); PG8_WAIT_L(0); PG8_BAR; PG8_MMA(0, 0, At, B0); PG8_MMA(0, 1, At, B1); PG8_BAR; PG8_SCHED;
;             PG8_LDA(At, 0, 1); PG8_STAGE(PG8_SB(0, 0), b2, voffB); PG8_STAGE(PG8_SB(0, 1), b2 + hstep, voffB); PG8_STAGE(PG8_SA(0, 0), a2, voffA);
;             PG8_WAIT_V(8); PG8_WAIT_L(0); PG8_BAR; PG8_MMA(1, 0, At, B0); PG8_MMA(1, 1, At, B1); PG8_BAR; PG8_SCHED;
.LBB0_760:
	ds_read_b128 v[128:131], v188
	ds_read_b128 v[132:135], v189
	ds_read_b128 v[136:139], v190
	ds_read_b128 v[140:143], v191
	ds_read_b128 v[144:147], v192
	ds_read_b128 v[148:151], v193
	ds_read_b128 v[172:175], v194
	ds_read_b128 v[176:179], v195
	s_add_u32 s46, s44, 0xfffc0080
	s_addc_u32 s47, s45, -1
	s_cmp_eq_u32 s74, 12
	s_cselect_b32 s49, s9, s47
	s_cselect_b32 s48, s11, s46
	s_cselect_b32 s47, s31, s73
	s_cselect_b32 s46, s35, s72
	s_mov_b32 m0, s68
	ds_read_b128 v[180:183], v186
	ds_read_b128 v[208:211], v186 offset:1024
	ds_read_b128 v[212:215], v186 offset:2048
	ds_read_b128 v[216:219], v186 offset:3072
	ds_read_b128 v[220:223], v186 offset:4096
	ds_read_b128 v[224:227], v186 offset:5120
	ds_read_b128 v[228:231], v186 offset:6144
	ds_read_b128 v[232:235], v186 offset:7168
	global_load_lds_dwordx4 v166, s[44:45]
	s_mov_b32 m0, s69
	s_nop 0
	global_load_lds_dwordx4 v164, s[44:45]
	s_waitcnt vmcnt(8)
	s_waitcnt lgkmcnt(0)
	s_barrier
	s_setprio 1
	s_waitcnt lgkmcnt(0)
	v_mfma_f32_16x16x32_bf16 v[124:127], v[128:131], v[180:183], v[124:127]
	v_mfma_f32_16x16x32_bf16 v[120:123], v[136:139], v[180:183], v[120:123]
	v_mfma_f32_16x16x32_bf16 v[108:111], v[128:131], v[212:215], v[108:111]
	v_mfma_f32_16x16x32_bf16 v[104:107], v[136:139], v[212:215], v[104:107]
	v_mfma_f32_16x16x32_bf16 v[92:95], v[128:131], v[220:223], v[92:95]
	v_mfma_f32_16x16x32_bf16 v[88:91], v[136:139], v[220:223], v[88:91]
	v_mfma_f32_16x16x32_bf16 v[76:79], v[128:131], v[228:231], v[76:79]
	v_mfma_f32_16x16x32_bf16 v[72:75], v[136:139], v[228:231], v[72:75]
	v_mfma_f32_16x16x32_bf16 v[124:127], v[132:135], v[208:211], v[124:127]
	v_mfma_f32_16x16x32_bf16 v[120:123], v[140:143], v[208:211], v[120:123]
	v_mfma_f32_16x16x32_bf16 v[108:111], v[132:135], v[216:219], v[108:111]
	v_mfma_f32_16x16x32_bf16 v[104:107], v[140:143], v[216:219], v[104:107]
	v_mfma_f32_16x16x32_bf16 v[92:95], v[132:135], v[224:227], v[92:95]
	v_mfma_f32_16x16x32_bf16 v[88:91], v[140:143], v[224:227], v[88:91]
	v_mfma_f32_16x16x32_bf16 v[76:79], v[132:135], v[232:235], v[76:79]
	v_mfma_f32_16x16x32_bf16 v[72:75], v[140:143], v[232:235], v[72:75]
	s_setprio 0
	s_setprio 1
	v_mfma_f32_16x16x32_bf16 v[116:119], v[144:147], v[180:183], v[116:119]
	v_mfma_f32_16x16x32_bf16 v[112:115], v[172:175], v[180:183], v[112:115]
	v_mfma_f32_16x16x32_bf16 v[100:103], v[144:147], v[212:215], v[100:103]
	v_mfma_f32_16x16x32_bf16 v[96:99], v[172:175], v[212:215], v[96:99]
	v_mfma_f32_16x16x32_bf16 v[84:87], v[144:147], v[220:223], v[84:87]
	v_mfma_f32_16x16x32_bf16 v[80:83], v[172:175], v[220:223], v[80:83]
	v_mfma_f32_16x16x32_bf16 v[68:71], v[144:147], v[228:231], v[68:71]
	v_mfma_f32_16x16x32_bf16 v[64:67], v[172:175], v[228:231], v[64:67]
	v_mfma_f32_16x16x32_bf16 v[116:119], v[148:151], v[208:211], v[116:119]
	v_mfma_f32_16x16x32_bf16 v[112:115], v[176:179], v[208:211], v[112:115]
	v_mfma_f32_16x16x32_bf16 v[100:103], v[148:151], v[216:219], v[100:103]
	v_mfma_f32_16x16x32_bf16 v[96:99], v[176:179], v[216:219], v[96:99]
	v_mfma_f32_16x16x32_bf16 v[84:87], v[148:151], v[224:227], v[84:87]
	v_mfma_f32_16x16x32_bf16 v[80:83], v[176:179], v[224:227], v[80:83]
	v_mfma_f32_16x16x32_bf16 v[68:71], v[148:151], v[232:235], v[68:71]
	v_mfma_f32_16x16x32_bf16 v[64:67], v[176:179], v[232:235], v[64:67]
	s_setprio 0
	s_barrier
	s_add_u32 s88, s46, 0x80
	s_addc_u32 s89, s47, 0
	s_add_u32 s90, s48, 0x80
	s_addc_u32 s91, s49, 0
	s_mov_b32 m0, s51
	s_add_u32 s76, s46, 0x40000
	ds_read_b128 v[180:183], v186 offset:16384
	ds_read_b128 v[208:211], v186 offset:17408
	ds_read_b128 v[212:215], v186 offset:18432
	ds_read_b128 v[216:219], v186 offset:19456
	ds_read_b128 v[220:223], v186 offset:20480
	ds_read_b128 v[224:227], v186 offset:21504
	ds_read_b128 v[228:231], v186 offset:22528
	ds_read_b128 v[232:235], v186 offset:23552
	global_load_lds_dwordx4 v154, s[46:47]
	s_mov_b32 m0, s52
	s_addc_u32 s77, s47, 0
	global_load_lds_dwordx4 v158, s[46:47]
	s_mov_b32 m0, s53
	s_nop 0
	global_load_lds_dwordx4 v154, s[76:77]
	s_mov_b32 m0, s54
	s_nop 0
	global_load_lds_dwordx4 v158, s[76:77]
	s_mov_b32 m0, s50
	s_nop 0
	global_load_lds_dwordx4 v152, s[48:49]
	s_mov_b32 m0, s55
	s_nop 0
	global_load_lds_dwordx4 v156, s[48:49]
	s_waitcnt vmcnt(8)
	s_waitcnt lgkmcnt(0)
	s_barrier
	s_setprio 1
	s_waitcnt lgkmcnt(0)
	v_mfma_f32_16x16x32_bf16 v[60:63], v[128:131], v[180:183], v[60:63]
	v_mfma_f32_16x16x32_bf16 v[56:59], v[136:139], v[180:183], v[56:59]
	v_mfma_f32_16x16x32_bf16 v[44:47], v[128:131], v[212:215], v[44:47]
	v_mfma_f32_16x16x32_bf16 v[40:43], v[136:139], v[212:215], v[40:43]
	v_mfma_f32_16x16x32_bf16 v[28:31], v[128:131], v[220:223], v[28:31]
	v_mfma_f32_16x16x32_bf16 v[24:27], v[136:139], v[220:223], v[24:27]
	v_mfma_f32_16x16x32_bf16 v[12:15], v[128:131], v[228:231], v[12:15]
	v_mfma_f32_16x16x32_bf16 v[8:11], v[136:139], v[228:231], v[8:11]
	v_mfma_f32_16x16x32_bf16 v[60:63], v[132:135], v[208:211], v[60:63]
	v_mfma_f32_16x16x32_bf16 v[56:59], v[140:143], v[208:211], v[56:59]
	v_mfma_f32_16x16x32_bf16 v[44:47], v[132:135], v[216:219], v[44:47]
	v_mfma_f32_16x16x32_bf16 v[40:43], v[140:143], v[216:219], v[40:43]
	v_mfma_f32_16x16x32_bf16 v[28:31], v[132:135], v[224:227], v[28:31]
	v_mfma_f32_16x16x32_bf16 v[24:27], v[140:143], v[224:227], v[24:27]
	v_mfma_f32_16x16x32_bf16 v[12:15], v[132:135], v[232:235], v[12:15]
	v_mfma_f32_16x16x32_bf16 v[8:11], v[140:143], v[232:235], v[8:11]
	s_setprio 0
	s_setprio 1
	v_mfma_f32_16x16x32_bf16 v[52:55], v[144:147], v[180:183], v[52:55]
	v_mfma_f32_16x16x32_bf16 v[48:51], v[172:175], v[180:183], v[48:51]
	v_mfma_f32_16x16x32_bf16 v[36:39], v[144:147], v[212:215], v[36:39]
	v_mfma_f32_16x16x32_bf16 v[32:35], v[172:175], v[212:215], v[32:35]
	v_mfma_f32_16x16x32_bf16 v[20:23], v[144:147], v[220:223], v[20:23]
	v_mfma_f32_16x16x32_bf16 v[16:19], v[172:175], v[220:223], v[16:19]
	v_mfma_f32_16x16x32_bf16 v[4:7], v[144:147], v[228:231], v[4:7]
	v_mfma_f32_16x16x32_bf16 v[0:3], v[172:175], v[228:231], v[0:3]
	v_mfma_f32_16x16x32_bf16 v[52:55], v[148:151], v[208:211], v[52:55]
	v_mfma_f32_16x16x32_bf16 v[48:51], v[176:179], v[208:211], v[48:51]
	v_mfma_f32_16x16x32_bf16 v[36:39], v[148:151], v[216:219], v[36:39]
	v_mfma_f32_16x16x32_bf16 v[32:35], v[176:179], v[216:219], v[32:35]
	v_mfma_f32_16x16x32_bf16 v[20:23], v[148:151], v[224:227], v[20:23]
	v_mfma_f32_16x16x32_bf16 v[16:19], v[176:179], v[224:227], v[16:19]
	v_mfma_f32_16x16x32_bf16 v[4:7], v[148:151], v[232:235], v[4:7]
	v_mfma_f32_16x16x32_bf16 v[0:3], v[176:179], v[232:235], v[0:3]
	s_setprio 0
	s_barrier
; #define PG8_STAGE(bufoff, gbase, voff) do { _Pragma("unroll") for (int _i = 0; _i < 2; ++_i) \
;         __builtin_amdgcn_global_load_lds((const unsigned*)((const char*)(gbase) + (voff)[_i]), (PG8_LAS unsigned*)(lds + (bufoff) + ldsw + _i * 8192), 16, 0, 0); } while (0)
; #define PG8_LDA(dst, b, h) do { _Pragma("unroll") for (int m = 0; m < 4; ++m) _Pragma("unroll") for (int k = 0; k < 2; ++k) dst[m][k] = *(const PG8_LAS bf16x8*)(lds + PG8_SA(b, h) + aoff + m * 2048 + k * 1024); } while (0)
; #define PG8_LDB(dst, b, h) do { _Pragma("unroll") for (int n = 0; n < 2; ++n) _Pragma("unroll") for (int k = 0; k < 2; ++k) dst[n][k] = *(const PG8_LAS bf16x8*)(lds + PG8_SB(b, h) + boff + n * 2048 + k * 1024); } while (0)
; #define PG8_MMA(ai, bj, At, Bt) do { __builtin_amdgcn_s_setprio(1); _Pragma("unroll") for (int m = 0; m < 4; ++m) _Pragma("unroll") for (int n = 0; n < 2; ++n) _Pragma("unroll") for (int k = 0; k < 2; ++k) \
;         acc[ai][bj][m][n] = __builtin_amdgcn_mfma_f32_16x16x32_bf16(Bt[n][k], At[m][k], acc[ai][bj][m][n], 0, 0, 0); __builtin_amdgcn_s_setprio(0); } while (0)
; #define PG8_WAIT_V(n) asm volatile("s_waitcnt vmcnt(" #n ")" ::: "memory")
; #define PG8_WAIT_L(n) asm volatile("s_waitcnt lgkmcnt(" #n ")" ::: "memory")
; #define PG8_BAR __builtin_amdgcn_s_barrier()
; #define PG8_SCHED __builtin_amdgcn_sched_barrier(0)
; template <class Epi, class Sched, bool ALIGN_EPI = false, bool SP2 = false>
; __device__ __forceinline__ void gemm_phase(PG8_LAS unsigned char* lds, const Gemm g, const Sched& S, const Epi& E) {
;     ...
;         for (int t = 0; t < nt; t += 2) {
;     ...
;             PG8_LDB(B0, 1, 0); PG8_LDB(B1, 1, 1); PG8_SCHED; PG8_LDA(At, 1, 0); PG8_STAGE(PG8_SA(0, 1), a2 + hstep, voffA);
;             PG8_WAIT_V(8); PG8_WAIT_L(0); PG8_BAR; PG8_MMA(0, 0, At, B0); PG8_MMA(0, 1, At, B1); PG8_BAR; PG8_SCHED;
;             PG8_LDA(At, 1, 1); PG8_STAGE(PG8_SB(1, 0), b3, voffB); PG8_STAGE(PG8_SB(1, 1), b3 + hstep, voffB); PG8_STAGE(PG8_SA(1, 0), a3, voffA);
;             PG8_WAIT_V(8); PG8_WAIT_L(0); PG8_BAR; PG8_MMA(1, 0, At, B0); PG8_MMA(1, 1, At, B1); PG8_BAR; PG8_SCHED;
	ds_read_b128 v[128:131], v196
	ds_read_b128 v[132:135], v197
	ds_read_b128 v[136:139], v198
	ds_read_b128 v[140:143], v199
	ds_read_b128 v[144:147], v200
	ds_read_b128 v[148:151], v201
	ds_read_b128 v[172:175], v202
	ds_read_b128 v[176:179], v203
	s_add_u32 s48, s48, 0x40000
	s_addc_u32 s49, s49, 0
	s_mov_b32 m0, s56
	ds_read_b128 v[180:183], v186 offset:32768
	ds_read_b128 v[208:211], v186 offset:33792
	ds_read_b128 v[212:215], v186 offset:34816
	ds_read_b128 v[216:219], v186 offset:35840
	ds_read_b128 v[220:223], v186 offset:36864
	ds_read_b128 v[224:227], v186 offset:37888
	ds_read_b128 v[228:231], v186 offset:38912
	ds_read_b128 v[232:235], v186 offset:39936
	global_load_lds_dwordx4 v152, s[48:49]
	s_mov_b32 m0, s57
	s_nop 0
	global_load_lds_dwordx4 v156, s[48:49]
	s_waitcnt vmcnt(8)
	s_waitcnt lgkmcnt(0)
	s_barrier
	s_setprio 1
	s_waitcnt lgkmcnt(0)
	v_mfma_f32_16x16x32_bf16 v[124:127], v[128:131], v[180:183], v[124:127]
	v_mfma_f32_16x16x32_bf16 v[120:123], v[136:139], v[180:183], v[120:123]
	v_mfma_f32_16x16x32_bf16 v[108:111], v[128:131], v[212:215], v[108:111]
	v_mfma_f32_16x16x32_bf16 v[104:107], v[136:139], v[212:215], v[104:107]
	v_mfma_f32_16x16x32_bf16 v[92:95], v[128:131], v[220:223], v[92:95]
	v_mfma_f32_16x16x32_bf16 v[88:91], v[136:139], v[220:223], v[88:91]
	v_mfma_f32_16x16x32_bf16 v[76:79], v[128:131], v[228:231], v[76:79]
	v_mfma_f32_16x16x32_bf16 v[72:75], v[136:139], v[228:231], v[72:75]
	v_mfma_f32_16x16x32_bf16 v[124:127], v[132:135], v[208:211], v[124:127]
	v_mfma_f32_16x16x32_bf16 v[120:123], v[140:143], v[208:211], v[120:123]
	v_mfma_f32_16x16x32_bf16 v[108:111], v[132:135], v[216:219], v[108:111]
	v_mfma_f32_16x16x32_bf16 v[104:107], v[140:143], v[216:219], v[104:107]
	v_mfma_f32_16x16x32_bf16 v[92:95], v[132:135], v[224:227], v[92:95]
	v_mfma_f32_16x16x32_bf16 v[88:91], v[140:143], v[224:227], v[88:91]
	v_mfma_f32_16x16x32_bf16 v[76:79], v[132:135], v[232:235], v[76:79]
	v_mfma_f32_16x16x32_bf16 v[72:75], v[140:143], v[232:235], v[72:75]
	s_setprio 0
	s_setprio 1
	v_mfma_f32_16x16x32_bf16 v[116:119], v[144:147], v[180:183], v[116:119]
	v_mfma_f32_16x16x32_bf16 v[112:115], v[172:175], v[180:183], v[112:115]
	v_mfma_f32_16x16x32_bf16 v[100:103], v[144:147], v[212:215], v[100:103]
	v_mfma_f32_16x16x32_bf16 v[96:99], v[172:175], v[212:215], v[96:99]
	v_mfma_f32_16x16x32_bf16 v[84:87], v[144:147], v[220:223], v[84:87]
	v_mfma_f32_16x16x32_bf16 v[80:83], v[172:175], v[220:223], v[80:83]
	v_mfma_f32_16x16x32_bf16 v[68:71], v[144:147], v[228:231], v[68:71]
	v_mfma_f32_16x16x32_bf16 v[64:67], v[172:175], v[228:231], v[64:67]
	v_mfma_f32_16x16x32_bf16 v[116:119], v[148:151], v[208:211], v[116:119]
	v_mfma_f32_16x16x32_bf16 v[112:115], v[176:179], v[208:211], v[112:115]
	v_mfma_f32_16x16x32_bf16 v[100:103], v[148:151], v[216:219], v[100:103]
	v_mfma_f32_16x16x32_bf16 v[96:99], v[176:179], v[216:219], v[96:99]
	v_mfma_f32_16x16x32_bf16 v[84:87], v[148:151], v[224:227], v[84:87]
	v_mfma_f32_16x16x32_bf16 v[80:83], v[176:179], v[224:227], v[80:83]
	v_mfma_f32_16x16x32_bf16 v[68:71], v[148:151], v[232:235], v[68:71]
	v_mfma_f32_16x16x32_bf16 v[64:67], v[176:179], v[232:235], v[64:67]
	s_setprio 0
	s_barrier
	s_mov_b32 m0, s59
	s_add_u32 s46, s46, 0x40080
	ds_read_b128 v[180:183], v186 offset:49152
	ds_read_b128 v[208:211], v186 offset:50176
	ds_read_b128 v[212:215], v186 offset:51200
	ds_read_b128 v[216:219], v186 offset:52224
	ds_read_b128 v[220:223], v186 offset:53248
	ds_read_b128 v[224:227], v186 offset:54272
	ds_read_b128 v[228:231], v186 offset:55296
	ds_read_b128 v[232:235], v186 offset:56320
	global_load_lds_dwordx4 v154, s[88:89]
	s_mov_b32 m0, s60
	s_addc_u32 s47, s47, 0
	global_load_lds_dwordx4 v158, s[88:89]
	s_mov_b32 m0, s63
	s_nop 0
	global_load_lds_dwordx4 v154, s[46:47]
	s_mov_b32 m0, s64
	s_nop 0
	global_load_lds_dwordx4 v158, s[46:47]
	s_mov_b32 m0, s61
	s_nop 0
	global_load_lds_dwordx4 v152, s[90:91]
	s_mov_b32 m0, s62
	s_nop 0
	global_load_lds_dwordx4 v156, s[90:91]
	s_waitcnt vmcnt(8)
	s_waitcnt lgkmcnt(0)
	s_barrier
	s_setprio 1
	s_waitcnt lgkmcnt(0)
	v_mfma_f32_16x16x32_bf16 v[60:63], v[128:131], v[180:183], v[60:63]
	v_mfma_f32_16x16x32_bf16 v[56:59], v[136:139], v[180:183], v[56:59]
	v_mfma_f32_16x16x32_bf16 v[44:47], v[128:131], v[212:215], v[44:47]
	v_mfma_f32_16x16x32_bf16 v[40:43], v[136:139], v[212:215], v[40:43]
	v_mfma_f32_16x16x32_bf16 v[28:31], v[128:131], v[220:223], v[28:31]
	v_mfma_f32_16x16x32_bf16 v[24:27], v[136:139], v[220:223], v[24:27]
	v_mfma_f32_16x16x32_bf16 v[12:15], v[128:131], v[228:231], v[12:15]
	v_mfma_f32_16x16x32_bf16 v[8:11], v[136:139], v[228:231], v[8:11]
	v_mfma_f32_16x16x32_bf16 v[60:63], v[132:135], v[208:211], v[60:63]
	v_mfma_f32_16x16x32_bf16 v[56:59], v[140:143], v[208:211], v[56:59]
	v_mfma_f32_16x16x32_bf16 v[44:47], v[132:135], v[216:219], v[44:47]
	v_mfma_f32_16x16x32_bf16 v[40:43], v[140:143], v[216:219], v[40:43]
	v_mfma_f32_16x16x32_bf16 v[28:31], v[132:135], v[224:227], v[28:31]
	v_mfma_f32_16x16x32_bf16 v[24:27], v[140:143], v[224:227], v[24:27]
	v_mfma_f32_16x16x32_bf16 v[12:15], v[132:135], v[232:235], v[12:15]
	v_mfma_f32_16x16x32_bf16 v[8:11], v[140:143], v[232:235], v[8:11]
	s_setprio 0
	s_setprio 1
	v_mfma_f32_16x16x32_bf16 v[52:55], v[144:147], v[180:183], v[52:55]
	v_mfma_f32_16x16x32_bf16 v[48:51], v[172:175], v[180:183], v[48:51]
	v_mfma_f32_16x16x32_bf16 v[36:39], v[144:147], v[212:215], v[36:39]
	v_mfma_f32_16x16x32_bf16 v[32:35], v[172:175], v[212:215], v[32:35]
	v_mfma_f32_16x16x32_bf16 v[20:23], v[144:147], v[220:223], v[20:23]
	v_mfma_f32_16x16x32_bf16 v[16:19], v[172:175], v[220:223], v[16:19]
	v_mfma_f32_16x16x32_bf16 v[4:7], v[144:147], v[228:231], v[4:7]
	v_mfma_f32_16x16x32_bf16 v[0:3], v[172:175], v[228:231], v[0:3]
	v_mfma_f32_16x16x32_bf16 v[52:55], v[148:151], v[208:211], v[52:55]
	v_mfma_f32_16x16x32_bf16 v[48:51], v[176:179], v[208:211], v[48:51]
	v_mfma_f32_16x16x32_bf16 v[36:39], v[148:151], v[216:219], v[36:39]
	v_mfma_f32_16x16x32_bf16 v[32:35], v[176:179], v[216:219], v[32:35]
	v_mfma_f32_16x16x32_bf16 v[20:23], v[148:151], v[224:227], v[20:23]
	v_mfma_f32_16x16x32_bf16 v[16:19], v[176:179], v[224:227], v[16:19]
	v_mfma_f32_16x16x32_bf16 v[4:7], v[148:151], v[232:235], v[4:7]
	v_mfma_f32_16x16x32_bf16 v[0:3], v[176:179], v[232:235], v[0:3]
	s_setprio 0
	s_barrier
	s_add_i32 s74, s74, 2
	s_add_u32 s72, s72, 0x100
	s_addc_u32 s73, s73, 0
	s_add_u32 s44, s44, 0x100
	s_addc_u32 s45, s45, 0
	s_cmp_gt_u32 s74, 13
	s_cbranch_scc0 .LBB0_760
	s_and_b64 vcc, exec, s[26:27]
	s_cbranch_vccz .LBB0_763
	s_barrier

; #define PG8_STAGE(bufoff, gbase, voff) do { _Pragma("unroll") for (int _i = 0; _i < 2; ++_i) \
;         __builtin_amdgcn_global_load_lds((const unsigned*)((const char*)(gbase) + (voff)[_i]), (PG8_LAS unsigned*)(lds + (bufoff) + ldsw + _i * 8192), 16, 0, 0); } while (0)
; #define PG8_LDA(dst, b, h) do { _Pragma("unroll") for (int m = 0; m < 4; ++m) _Pragma("unroll") for (int k = 0; k < 2; ++k) dst[m][k] = *(const PG8_LAS bf16x8*)(lds + PG8_SA(b, h) + aoff + m * 2048 + k * 1024); } while (0)
; #define PG8_LDB(dst, b, h) do { _Pragma("unroll") for (int n = 0; n < 2; ++n) _Pragma("unroll") for (int k = 0; k < 2; ++k) dst[n][k] = *(const PG8_LAS bf16x8*)(lds + PG8_SB(b, h) + boff + n * 2048 + k * 1024); } while (0)
; #define PG8_MMA(ai, bj, At, Bt) do { __builtin_amdgcn_s_setprio(1); _Pragma("unroll") for (int m = 0; m < 4; ++m) _Pragma("unroll") for (int n = 0; n < 2; ++n) _Pragma("unroll") for (int k = 0; k < 2; ++k) \
;         acc[ai][bj][m][n] = __builtin_amdgcn_mfma_f32_16x16x32_bf16(Bt[n][k], At[m][k], acc[ai][bj][m][n], 0, 0, 0); __builtin_amdgcn_s_setprio(0); } while (0)
; #define PG8_WAIT_V(n) asm volatile("s_waitcnt vmcnt(" #n ")" ::: "memory")
; #define PG8_WAIT_L(n) asm volatile("s_waitcnt lgkmcnt(" #n ")" ::: "memory")
; template <class Epi, class Sched, bool ALIGN_EPI = false, bool SP2 = false>
; __device__ __forceinline__ void gemm_phase(PG8_LAS unsigned char* lds, const Gemm g, const Sched& S, const Epi& E) {
;     ...
;             const bool last = (t == nt - 2);
;             const char* a1 = cA + (size_t)(t + 1) * kstep;
;             const char* a2 = last ? nA : cA + (size_t)(t + 2) * kstep; const char* b2 = last ? nB : cB + (size_t)(t + 2) * kstep;
;             const char* a3 = a2 + kstep; const char* b3 = b2 + kstep;
;             if (last && has_next) S.a_ready(nxt);
;             if constexpr (SP2) {
;             PG8_LDB(B0, 0, 0); PG8_LDB(B1, 0, 1); PG8_SCHED; PG8_LDA(At, 0, 0); PG8_STAGE(PG8_SA(1, 1), a1 + hstep, voffA);
;             PG8_WAIT_V(8); PG8_WAIT_L(0); PG8_BAR; PG8_MMA(0, 0, At, B0); PG8_MMA(0, 1, At, B1); PG8_BAR; PG8_SCHED;
;             PG8_LDA(At, 0, 1); PG8_STAGE(PG8_SB(0, 0), b2, voffB); PG8_STAGE(PG8_SB(0, 1), b2 + hstep, voffB); PG8_STAGE(PG8_SA(0, 0), a2, voffA);
;             PG8_WAIT_V(8); PG8_WAIT_L(0); PG8_BAR; PG8_MMA(1, 0, At, B0); PG8_MMA(1, 1, At, B1); PG8_BAR; PG8_SCHED;
.LBB0_1463:
	ds_read_b128 v[144:147], v151
	ds_read_b128 v[168:171], v152
	ds_read_b128 v[172:175], v153
	ds_read_b128 v[176:179], v154
	ds_read_b128 v[180:183], v155
	ds_read_b128 v[186:189], v156
	ds_read_b128 v[190:193], v157
	ds_read_b128 v[194:197], v158
	s_add_u32 s42, s36, 0xfffc0080
	s_addc_u32 s43, s37, -1
	s_cmp_eq_u32 s72, 12
	s_cselect_b32 s45, s27, s43
	s_cselect_b32 s44, s35, s42
	s_cselect_b32 s43, s25, s71
	s_cselect_b32 s42, s69, s70
	s_mov_b32 m0, s66
	ds_read_b128 v[198:201], v149
	ds_read_b128 v[202:205], v149 offset:1024
	ds_read_b128 v[206:209], v149 offset:2048
	ds_read_b128 v[210:213], v149 offset:3072
	ds_read_b128 v[214:217], v149 offset:4096
	ds_read_b128 v[218:221], v149 offset:5120
	ds_read_b128 v[222:225], v149 offset:6144
	ds_read_b128 v[226:229], v149 offset:7168
	global_load_lds_dwordx4 v138, s[36:37]
	s_mov_b32 m0, s67
	s_nop 0
	global_load_lds_dwordx4 v136, s[36:37]
	s_waitcnt vmcnt(8)
	s_waitcnt lgkmcnt(0)
	s_barrier
	s_setprio 1
	s_waitcnt lgkmcnt(0)
	v_mfma_f32_16x16x32_bf16 v[124:127], v[144:147], v[198:201], v[124:127]
	v_mfma_f32_16x16x32_bf16 v[120:123], v[172:175], v[198:201], v[120:123]
	v_mfma_f32_16x16x32_bf16 v[108:111], v[144:147], v[206:209], v[108:111]
	v_mfma_f32_16x16x32_bf16 v[104:107], v[172:175], v[206:209], v[104:107]
	v_mfma_f32_16x16x32_bf16 v[92:95], v[144:147], v[214:217], v[92:95]
	v_mfma_f32_16x16x32_bf16 v[88:91], v[172:175], v[214:217], v[88:91]
	v_mfma_f32_16x16x32_bf16 v[76:79], v[144:147], v[222:225], v[76:79]
	v_mfma_f32_16x16x32_bf16 v[72:75], v[172:175], v[222:225], v[72:75]
	v_mfma_f32_16x16x32_bf16 v[124:127], v[168:171], v[202:205], v[124:127]
	v_mfma_f32_16x16x32_bf16 v[120:123], v[176:179], v[202:205], v[120:123]
	v_mfma_f32_16x16x32_bf16 v[108:111], v[168:171], v[210:213], v[108:111]
	v_mfma_f32_16x16x32_bf16 v[104:107], v[176:179], v[210:213], v[104:107]
	v_mfma_f32_16x16x32_bf16 v[92:95], v[168:171], v[218:221], v[92:95]
	v_mfma_f32_16x16x32_bf16 v[88:91], v[176:179], v[218:221], v[88:91]
	v_mfma_f32_16x16x32_bf16 v[76:79], v[168:171], v[226:229], v[76:79]
	v_mfma_f32_16x16x32_bf16 v[72:75], v[176:179], v[226:229], v[72:75]
	s_setprio 0
	s_setprio 1
	v_mfma_f32_16x16x32_bf16 v[116:119], v[180:183], v[198:201], v[116:119]
	v_mfma_f32_16x16x32_bf16 v[112:115], v[190:193], v[198:201], v[112:115]
	v_mfma_f32_16x16x32_bf16 v[100:103], v[180:183], v[206:209], v[100:103]
	v_mfma_f32_16x16x32_bf16 v[96:99], v[190:193], v[206:209], v[96:99]
	v_mfma_f32_16x16x32_bf16 v[84:87], v[180:183], v[214:217], v[84:87]
	v_mfma_f32_16x16x32_bf16 v[80:83], v[190:193], v[214:217], v[80:83]
	v_mfma_f32_16x16x32_bf16 v[68:71], v[180:183], v[222:225], v[68:71]
	v_mfma_f32_16x16x32_bf16 v[64:67], v[190:193], v[222:225], v[64:67]
	v_mfma_f32_16x16x32_bf16 v[116:119], v[186:189], v[202:205], v[116:119]
	v_mfma_f32_16x16x32_bf16 v[112:115], v[194:197], v[202:205], v[112:115]
	v_mfma_f32_16x16x32_bf16 v[100:103], v[186:189], v[210:213], v[100:103]
	v_mfma_f32_16x16x32_bf16 v[96:99], v[194:197], v[210:213], v[96:99]
	v_mfma_f32_16x16x32_bf16 v[84:87], v[186:189], v[218:221], v[84:87]
	v_mfma_f32_16x16x32_bf16 v[80:83], v[194:197], v[218:221], v[80:83]
	v_mfma_f32_16x16x32_bf16 v[68:71], v[186:189], v[226:229], v[68:71]
	v_mfma_f32_16x16x32_bf16 v[64:67], v[194:197], v[226:229], v[64:67]
	s_setprio 0
	s_barrier
	s_add_u32 s88, s42, 0x80
	s_addc_u32 s89, s43, 0
	s_add_u32 s90, s44, 0x80
	s_addc_u32 s91, s45, 0
	s_mov_b32 m0, s50
	s_add_u32 s74, s42, 0x40000
	ds_read_b128 v[198:201], v149 offset:16384
	ds_read_b128 v[202:205], v149 offset:17408
	ds_read_b128 v[206:209], v149 offset:18432
	ds_read_b128 v[210:213], v149 offset:19456
	ds_read_b128 v[214:217], v149 offset:20480
	ds_read_b128 v[218:221], v149 offset:21504
	ds_read_b128 v[222:225], v149 offset:22528
	ds_read_b128 v[226:229], v149 offset:23552
	global_load_lds_dwordx4 v130, s[42:43]
	s_mov_b32 m0, s51
	s_addc_u32 s75, s43, 0
	global_load_lds_dwordx4 v134, s[42:43]
	s_mov_b32 m0, s52
	s_nop 0
	global_load_lds_dwordx4 v130, s[74:75]
	s_mov_b32 m0, s53
	s_nop 0
	global_load_lds_dwordx4 v134, s[74:75]
	s_mov_b32 m0, s49
	s_nop 0
	global_load_lds_dwordx4 v128, s[44:45]
	s_mov_b32 m0, s54
	s_nop 0
	global_load_lds_dwordx4 v132, s[44:45]
	s_waitcnt vmcnt(8)
	s_waitcnt lgkmcnt(0)
	s_barrier
	s_setprio 1
	s_waitcnt lgkmcnt(0)
	v_mfma_f32_16x16x32_bf16 v[60:63], v[144:147], v[198:201], v[60:63]
	v_mfma_f32_16x16x32_bf16 v[56:59], v[172:175], v[198:201], v[56:59]
	v_mfma_f32_16x16x32_bf16 v[44:47], v[144:147], v[206:209], v[44:47]
	v_mfma_f32_16x16x32_bf16 v[40:43], v[172:175], v[206:209], v[40:43]
	v_mfma_f32_16x16x32_bf16 v[28:31], v[144:147], v[214:217], v[28:31]
	v_mfma_f32_16x16x32_bf16 v[24:27], v[172:175], v[214:217], v[24:27]
	v_mfma_f32_16x16x32_bf16 v[12:15], v[144:147], v[222:225], v[12:15]
	v_mfma_f32_16x16x32_bf16 v[8:11], v[172:175], v[222:225], v[8:11]
	v_mfma_f32_16x16x32_bf16 v[60:63], v[168:171], v[202:205], v[60:63]
	v_mfma_f32_16x16x32_bf16 v[56:59], v[176:179], v[202:205], v[56:59]
	v_mfma_f32_16x16x32_bf16 v[44:47], v[168:171], v[210:213], v[44:47]
	v_mfma_f32_16x16x32_bf16 v[40:43], v[176:179], v[210:213], v[40:43]
	v_mfma_f32_16x16x32_bf16 v[28:31], v[168:171], v[218:221], v[28:31]
	v_mfma_f32_16x16x32_bf16 v[24:27], v[176:179], v[218:221], v[24:27]
	v_mfma_f32_16x16x32_bf16 v[12:15], v[168:171], v[226:229], v[12:15]
	v_mfma_f32_16x16x32_bf16 v[8:11], v[176:179], v[226:229], v[8:11]
	s_setprio 0
	s_setprio 1
	v_mfma_f32_16x16x32_bf16 v[52:55], v[180:183], v[198:201], v[52:55]
	v_mfma_f32_16x16x32_bf16 v[48:51], v[190:193], v[198:201], v[48:51]
	v_mfma_f32_16x16x32_bf16 v[36:39], v[180:183], v[206:209], v[36:39]
	v_mfma_f32_16x16x32_bf16 v[32:35], v[190:193], v[206:209], v[32:35]
	v_mfma_f32_16x16x32_bf16 v[20:23], v[180:183], v[214:217], v[20:23]
	v_mfma_f32_16x16x32_bf16 v[16:19], v[190:193], v[214:217], v[16:19]
	v_mfma_f32_16x16x32_bf16 v[4:7], v[180:183], v[222:225], v[4:7]
	v_mfma_f32_16x16x32_bf16 v[0:3], v[190:193], v[222:225], v[0:3]
	v_mfma_f32_16x16x32_bf16 v[52:55], v[186:189], v[202:205], v[52:55]
	v_mfma_f32_16x16x32_bf16 v[48:51], v[194:197], v[202:205], v[48:51]
	v_mfma_f32_16x16x32_bf16 v[36:39], v[186:189], v[210:213], v[36:39]
	v_mfma_f32_16x16x32_bf16 v[32:35], v[194:197], v[210:213], v[32:35]
	v_mfma_f32_16x16x32_bf16 v[20:23], v[186:189], v[218:221], v[20:23]
	v_mfma_f32_16x16x32_bf16 v[16:19], v[194:197], v[218:221], v[16:19]
	v_mfma_f32_16x16x32_bf16 v[4:7], v[186:189], v[226:229], v[4:7]
	v_mfma_f32_16x16x32_bf16 v[0:3], v[194:197], v[226:229], v[0:3]
	s_setprio 0
	s_barrier
; #define PG8_STAGE(bufoff, gbase, voff) do { _Pragma("unroll") for (int _i = 0; _i < 2; ++_i) \
;         __builtin_amdgcn_global_load_lds((const unsigned*)((const char*)(gbase) + (voff)[_i]), (PG8_LAS unsigned*)(lds + (bufoff) + ldsw + _i * 8192), 16, 0, 0); } while (0)
; #define PG8_LDA(dst, b, h) do { _Pragma("unroll") for (int m = 0; m < 4; ++m) _Pragma("unroll") for (int k = 0; k < 2; ++k) dst[m][k] = *(const PG8_LAS bf16x8*)(lds + PG8_SA(b, h) + aoff + m * 2048 + k * 1024); } while (0)
; #define PG8_LDB(dst, b, h) do { _Pragma("unroll") for (int n = 0; n < 2; ++n) _Pragma("unroll") for (int k = 0; k < 2; ++k) dst[n][k] = *(const PG8_LAS bf16x8*)(lds + PG8_SB(b, h) + boff + n * 2048 + k * 1024); } while (0)
; #define PG8_MMA(ai, bj, At, Bt) do { __builtin_amdgcn_s_setprio(1); _Pragma("unroll") for (int m = 0; m < 4; ++m) _Pragma("unroll") for (int n = 0; n < 2; ++n) _Pragma("unroll") for (int k = 0; k < 2; ++k) \
;         acc[ai][bj][m][n] = __builtin_amdgcn_mfma_f32_16x16x32_bf16(Bt[n][k], At[m][k], acc[ai][bj][m][n], 0, 0, 0); __builtin_amdgcn_s_setprio(0); } while (0)
; #define PG8_WAIT_V(n) asm volatile("s_waitcnt vmcnt(" #n ")" ::: "memory")
; #define PG8_WAIT_L(n) asm volatile("s_waitcnt lgkmcnt(" #n ")" ::: "memory")
; #define PG8_BAR __builtin_amdgcn_s_barrier()
; #define PG8_SCHED __builtin_amdgcn_sched_barrier(0)
; template <class Epi, class Sched, bool ALIGN_EPI = false, bool SP2 = false>
; __device__ __forceinline__ void gemm_phase(PG8_LAS unsigned char* lds, const Gemm g, const Sched& S, const Epi& E) {
;     ...
;         for (int t = 0; t < nt; t += 2) {
;     ...
;             PG8_LDB(B0, 1, 0); PG8_LDB(B1, 1, 1); PG8_SCHED; PG8_LDA(At, 1, 0); PG8_STAGE(PG8_SA(0, 1), a2 + hstep, voffA);
;             PG8_WAIT_V(8); PG8_WAIT_L(0); PG8_BAR; PG8_MMA(0, 0, At, B0); PG8_MMA(0, 1, At, B1); PG8_BAR; PG8_SCHED;
;             PG8_LDA(At, 1, 1); PG8_STAGE(PG8_SB(1, 0), b3, voffB); PG8_STAGE(PG8_SB(1, 1), b3 + hstep, voffB); PG8_STAGE(PG8_SA(1, 0), a3, voffA);
;             PG8_WAIT_V(8); PG8_WAIT_L(0); PG8_BAR; PG8_MMA(1, 0, At, B0); PG8_MMA(1, 1, At, B1); PG8_BAR; PG8_SCHED;
	ds_read_b128 v[144:147], v159
	ds_read_b128 v[168:171], v160
	ds_read_b128 v[172:175], v161
	ds_read_b128 v[176:179], v162
	ds_read_b128 v[180:183], v163
	ds_read_b128 v[186:189], v164
	ds_read_b128 v[190:193], v165
	ds_read_b128 v[194:197], v166
	s_add_u32 s44, s44, 0x40000
	s_addc_u32 s45, s45, 0
	s_mov_b32 m0, s55
	ds_read_b128 v[198:201], v149 offset:32768
	ds_read_b128 v[202:205], v149 offset:33792
	ds_read_b128 v[206:209], v149 offset:34816
	ds_read_b128 v[210:213], v149 offset:35840
	ds_read_b128 v[214:217], v149 offset:36864
	ds_read_b128 v[218:221], v149 offset:37888
	ds_read_b128 v[222:225], v149 offset:38912
	ds_read_b128 v[226:229], v149 offset:39936
	global_load_lds_dwordx4 v128, s[44:45]
	s_mov_b32 m0, s56
	s_nop 0
	global_load_lds_dwordx4 v132, s[44:45]
	s_waitcnt vmcnt(8)
	s_waitcnt lgkmcnt(0)
	s_barrier
	s_setprio 1
	s_waitcnt lgkmcnt(0)
	v_mfma_f32_16x16x32_bf16 v[124:127], v[144:147], v[198:201], v[124:127]
	v_mfma_f32_16x16x32_bf16 v[120:123], v[172:175], v[198:201], v[120:123]
	v_mfma_f32_16x16x32_bf16 v[108:111], v[144:147], v[206:209], v[108:111]
	v_mfma_f32_16x16x32_bf16 v[104:107], v[172:175], v[206:209], v[104:107]
	v_mfma_f32_16x16x32_bf16 v[92:95], v[144:147], v[214:217], v[92:95]
	v_mfma_f32_16x16x32_bf16 v[88:91], v[172:175], v[214:217], v[88:91]
	v_mfma_f32_16x16x32_bf16 v[76:79], v[144:147], v[222:225], v[76:79]
	v_mfma_f32_16x16x32_bf16 v[72:75], v[172:175], v[222:225], v[72:75]
	v_mfma_f32_16x16x32_bf16 v[124:127], v[168:171], v[202:205], v[124:127]
	v_mfma_f32_16x16x32_bf16 v[120:123], v[176:179], v[202:205], v[120:123]
	v_mfma_f32_16x16x32_bf16 v[108:111], v[168:171], v[210:213], v[108:111]
	v_mfma_f32_16x16x32_bf16 v[104:107], v[176:179], v[210:213], v[104:107]
	v_mfma_f32_16x16x32_bf16 v[92:95], v[168:171], v[218:221], v[92:95]
	v_mfma_f32_16x16x32_bf16 v[88:91], v[176:179], v[218:221], v[88:91]
	v_mfma_f32_16x16x32_bf16 v[76:79], v[168:171], v[226:229], v[76:79]
	v_mfma_f32_16x16x32_bf16 v[72:75], v[176:179], v[226:229], v[72:75]
	s_setprio 0
	s_setprio 1
	v_mfma_f32_16x16x32_bf16 v[116:119], v[180:183], v[198:201], v[116:119]
	v_mfma_f32_16x16x32_bf16 v[112:115], v[190:193], v[198:201], v[112:115]
	v_mfma_f32_16x16x32_bf16 v[100:103], v[180:183], v[206:209], v[100:103]
	v_mfma_f32_16x16x32_bf16 v[96:99], v[190:193], v[206:209], v[96:99]
	v_mfma_f32_16x16x32_bf16 v[84:87], v[180:183], v[214:217], v[84:87]
	v_mfma_f32_16x16x32_bf16 v[80:83], v[190:193], v[214:217], v[80:83]
	v_mfma_f32_16x16x32_bf16 v[68:71], v[180:183], v[222:225], v[68:71]
	v_mfma_f32_16x16x32_bf16 v[64:67], v[190:193], v[222:225], v[64:67]
	v_mfma_f32_16x16x32_bf16 v[116:119], v[186:189], v[202:205], v[116:119]
	v_mfma_f32_16x16x32_bf16 v[112:115], v[194:197], v[202:205], v[112:115]
	v_mfma_f32_16x16x32_bf16 v[100:103], v[186:189], v[210:213], v[100:103]
	v_mfma_f32_16x16x32_bf16 v[96:99], v[194:197], v[210:213], v[96:99]
	v_mfma_f32_16x16x32_bf16 v[84:87], v[186:189], v[218:221], v[84:87]
	v_mfma_f32_16x16x32_bf16 v[80:83], v[194:197], v[218:221], v[80:83]
	v_mfma_f32_16x16x32_bf16 v[68:71], v[186:189], v[226:229], v[68:71]
	v_mfma_f32_16x16x32_bf16 v[64:67], v[194:197], v[226:229], v[64:67]
	s_setprio 0
	s_barrier
	s_mov_b32 m0, s58
	s_add_u32 s42, s42, 0x40080
	ds_read_b128 v[198:201], v149 offset:49152
	ds_read_b128 v[202:205], v149 offset:50176
	ds_read_b128 v[206:209], v149 offset:51200
	ds_read_b128 v[210:213], v149 offset:52224
	ds_read_b128 v[214:217], v149 offset:53248
	ds_read_b128 v[218:221], v149 offset:54272
	ds_read_b128 v[222:225], v149 offset:55296
	ds_read_b128 v[226:229], v149 offset:56320
	global_load_lds_dwordx4 v130, s[88:89]
	s_mov_b32 m0, s59
	s_addc_u32 s43, s43, 0
	global_load_lds_dwordx4 v134, s[88:89]
	s_mov_b32 m0, s62
	s_nop 0
	global_load_lds_dwordx4 v130, s[42:43]
	s_mov_b32 m0, s63
	s_nop 0
	global_load_lds_dwordx4 v134, s[42:43]
	s_mov_b32 m0, s60
	s_nop 0
	global_load_lds_dwordx4 v128, s[90:91]
	s_mov_b32 m0, s61
	s_nop 0
	global_load_lds_dwordx4 v132, s[90:91]
	s_waitcnt vmcnt(8)
	s_waitcnt lgkmcnt(0)
	s_barrier
	s_setprio 1
	s_waitcnt lgkmcnt(0)
	v_mfma_f32_16x16x32_bf16 v[60:63], v[144:147], v[198:201], v[60:63]
	v_mfma_f32_16x16x32_bf16 v[56:59], v[172:175], v[198:201], v[56:59]
	v_mfma_f32_16x16x32_bf16 v[44:47], v[144:147], v[206:209], v[44:47]
	v_mfma_f32_16x16x32_bf16 v[40:43], v[172:175], v[206:209], v[40:43]
	v_mfma_f32_16x16x32_bf16 v[28:31], v[144:147], v[214:217], v[28:31]
	v_mfma_f32_16x16x32_bf16 v[24:27], v[172:175], v[214:217], v[24:27]
	v_mfma_f32_16x16x32_bf16 v[12:15], v[144:147], v[222:225], v[12:15]
	v_mfma_f32_16x16x32_bf16 v[8:11], v[172:175], v[222:225], v[8:11]
	v_mfma_f32_16x16x32_bf16 v[60:63], v[168:171], v[202:205], v[60:63]
	v_mfma_f32_16x16x32_bf16 v[56:59], v[176:179], v[202:205], v[56:59]
	v_mfma_f32_16x16x32_bf16 v[44:47], v[168:171], v[210:213], v[44:47]
	v_mfma_f32_16x16x32_bf16 v[40:43], v[176:179], v[210:213], v[40:43]
	v_mfma_f32_16x16x32_bf16 v[28:31], v[168:171], v[218:221], v[28:31]
	v_mfma_f32_16x16x32_bf16 v[24:27], v[176:179], v[218:221], v[24:27]
	v_mfma_f32_16x16x32_bf16 v[12:15], v[168:171], v[226:229], v[12:15]
	v_mfma_f32_16x16x32_bf16 v[8:11], v[176:179], v[226:229], v[8:11]
	s_setprio 0
	s_setprio 1
	v_mfma_f32_16x16x32_bf16 v[52:55], v[180:183], v[198:201], v[52:55]
	v_mfma_f32_16x16x32_bf16 v[48:51], v[190:193], v[198:201], v[48:51]
	v_mfma_f32_16x16x32_bf16 v[36:39], v[180:183], v[206:209], v[36:39]
	v_mfma_f32_16x16x32_bf16 v[32:35], v[190:193], v[206:209], v[32:35]
	v_mfma_f32_16x16x32_bf16 v[20:23], v[180:183], v[214:217], v[20:23]
	v_mfma_f32_16x16x32_bf16 v[16:19], v[190:193], v[214:217], v[16:19]
	v_mfma_f32_16x16x32_bf16 v[4:7], v[180:183], v[222:225], v[4:7]
	v_mfma_f32_16x16x32_bf16 v[0:3], v[190:193], v[222:225], v[0:3]
	v_mfma_f32_16x16x32_bf16 v[52:55], v[186:189], v[202:205], v[52:55]
	v_mfma_f32_16x16x32_bf16 v[48:51], v[194:197], v[202:205], v[48:51]
	v_mfma_f32_16x16x32_bf16 v[36:39], v[186:189], v[210:213], v[36:39]
	v_mfma_f32_16x16x32_bf16 v[32:35], v[194:197], v[210:213], v[32:35]
	v_mfma_f32_16x16x32_bf16 v[20:23], v[186:189], v[218:221], v[20:23]
	v_mfma_f32_16x16x32_bf16 v[16:19], v[194:197], v[218:221], v[16:19]
	v_mfma_f32_16x16x32_bf16 v[4:7], v[186:189], v[226:229], v[4:7]
	v_mfma_f32_16x16x32_bf16 v[0:3], v[194:197], v[226:229], v[0:3]
	s_setprio 0
	s_barrier
	s_add_i32 s72, s72, 2
	s_add_u32 s70, s70, 0x100
	s_addc_u32 s71, s71, 0
	s_add_u32 s36, s36, 0x100
	s_addc_u32 s37, s37, 0
	s_cmp_gt_u32 s72, 13
	s_cbranch_scc0 .LBB0_1463
	s_and_b64 vcc, exec, s[20:21]
	s_cbranch_vccz .LBB0_1466
	s_barrier

; #define PG8_STAGE(bufoff, gbase, voff) do { _Pragma("unroll") for (int _i = 0; _i < 2; ++_i) \
;         __builtin_amdgcn_global_load_lds((const unsigned*)((const char*)(gbase) + (voff)[_i]), (PG8_LAS unsigned*)(lds + (bufoff) + ldsw + _i * 8192), 16, 0, 0); } while (0)
; #define PG8_LDA(dst, b, h) do { _Pragma("unroll") for (int m = 0; m < 4; ++m) _Pragma("unroll") for (int k = 0; k < 2; ++k) dst[m][k] = *(const PG8_LAS bf16x8*)(lds + PG8_SA(b, h) + aoff + m * 2048 + k * 1024); } while (0)
; #define PG8_LDB(dst, b, h) do { _Pragma("unroll") for (int n = 0; n < 2; ++n) _Pragma("unroll") for (int k = 0; k < 2; ++k) dst[n][k] = *(const PG8_LAS bf16x8*)(lds + PG8_SB(b, h) + boff + n * 2048 + k * 1024); } while (0)
; #define PG8_MMA(ai, bj, At, Bt) do { __builtin_amdgcn_s_setprio(1); _Pragma("unroll") for (int m = 0; m < 4; ++m) _Pragma("unroll") for (int n = 0; n < 2; ++n) _Pragma("unroll") for (int k = 0; k < 2; ++k) \
;         acc[ai][bj][m][n] = __builtin_amdgcn_mfma_f32_16x16x32_bf16(Bt[n][k], At[m][k], acc[ai][bj][m][n], 0, 0, 0); __builtin_amdgcn_s_setprio(0); } while (0)
; #define PG8_WAIT_V(n) asm volatile("s_waitcnt vmcnt(" #n ")" ::: "memory")
; #define PG8_WAIT_L(n) asm volatile("s_waitcnt lgkmcnt(" #n ")" ::: "memory")
; template <class Epi, class Sched, bool ALIGN_EPI = false, bool SP2 = false>
; __device__ __forceinline__ void gemm_phase(PG8_LAS unsigned char* lds, const Gemm g, const Sched& S, const Epi& E) {
;     ...
;             const bool last = (t == nt - 2);
;             const char* a1 = cA + (size_t)(t + 1) * kstep;
;             const char* a2 = last ? nA : cA + (size_t)(t + 2) * kstep; const char* b2 = last ? nB : cB + (size_t)(t + 2) * kstep;
;             const char* a3 = a2 + kstep; const char* b3 = b2 + kstep;
;             if (last && has_next) S.a_ready(nxt);
;             if constexpr (SP2) {
;             PG8_LDB(B0, 0, 0); PG8_LDB(B1, 0, 1); PG8_SCHED; PG8_LDA(At, 0, 0); PG8_STAGE(PG8_SA(1, 1), a1 + hstep, voffA);
;             PG8_WAIT_V(8); PG8_WAIT_L(0); PG8_BAR; PG8_MMA(0, 0, At, B0); PG8_MMA(0, 1, At, B1); PG8_BAR; PG8_SCHED;
;             PG8_LDA(At, 0, 1); PG8_STAGE(PG8_SB(0, 0), b2, voffB); PG8_STAGE(PG8_SB(0, 1), b2 + hstep, voffB); PG8_STAGE(PG8_SA(0, 0), a2, voffA);
;             PG8_WAIT_V(8); PG8_WAIT_L(0); PG8_BAR; PG8_MMA(1, 0, At, B0); PG8_MMA(1, 1, At, B1); PG8_BAR; PG8_SCHED;
.LBB0_1744:
	ds_read_b128 v[128:131], v161
	ds_read_b128 v[132:135], v162
	ds_read_b128 v[152:155], v163
	ds_read_b128 v[180:183], v164
	ds_read_b128 v[186:189], v165
	ds_read_b128 v[190:193], v166
	ds_read_b128 v[194:197], v167
	ds_read_b128 v[198:201], v168
	s_add_u32 s48, s12, 0xfffc0080
	s_addc_u32 s49, s13, -1
	s_cmp_eq_u32 s75, 12
	s_cselect_b32 s51, s9, s49
	s_cselect_b32 s50, s11, s48
	s_cselect_b32 s49, s34, s74
	s_cselect_b32 s48, s37, s43
	s_mov_b32 m0, s70
	ds_read_b128 v[202:205], v159
	ds_read_b128 v[206:209], v159 offset:1024
	ds_read_b128 v[210:213], v159 offset:2048
	ds_read_b128 v[214:217], v159 offset:3072
	ds_read_b128 v[218:221], v159 offset:4096
	ds_read_b128 v[222:225], v159 offset:5120
	ds_read_b128 v[226:229], v159 offset:6144
	ds_read_b128 v[230:233], v159 offset:7168
	global_load_lds_dwordx4 v146, s[12:13]
	s_mov_b32 m0, s71
	s_nop 0
	global_load_lds_dwordx4 v144, s[12:13]
	s_waitcnt vmcnt(8)
	s_waitcnt lgkmcnt(0)
	s_barrier
	s_setprio 1
	s_waitcnt lgkmcnt(0)
	v_mfma_f32_16x16x32_bf16 v[124:127], v[128:131], v[202:205], v[124:127]
	v_mfma_f32_16x16x32_bf16 v[120:123], v[152:155], v[202:205], v[120:123]
	v_mfma_f32_16x16x32_bf16 v[108:111], v[128:131], v[210:213], v[108:111]
	v_mfma_f32_16x16x32_bf16 v[104:107], v[152:155], v[210:213], v[104:107]
	v_mfma_f32_16x16x32_bf16 v[92:95], v[128:131], v[218:221], v[92:95]
	v_mfma_f32_16x16x32_bf16 v[88:91], v[152:155], v[218:221], v[88:91]
	v_mfma_f32_16x16x32_bf16 v[76:79], v[128:131], v[226:229], v[76:79]
	v_mfma_f32_16x16x32_bf16 v[72:75], v[152:155], v[226:229], v[72:75]
	v_mfma_f32_16x16x32_bf16 v[124:127], v[132:135], v[206:209], v[124:127]
	v_mfma_f32_16x16x32_bf16 v[120:123], v[180:183], v[206:209], v[120:123]
	v_mfma_f32_16x16x32_bf16 v[108:111], v[132:135], v[214:217], v[108:111]
	v_mfma_f32_16x16x32_bf16 v[104:107], v[180:183], v[214:217], v[104:107]
	v_mfma_f32_16x16x32_bf16 v[92:95], v[132:135], v[222:225], v[92:95]
	v_mfma_f32_16x16x32_bf16 v[88:91], v[180:183], v[222:225], v[88:91]
	v_mfma_f32_16x16x32_bf16 v[76:79], v[132:135], v[230:233], v[76:79]
	v_mfma_f32_16x16x32_bf16 v[72:75], v[180:183], v[230:233], v[72:75]
	s_setprio 0
	s_setprio 1
	v_mfma_f32_16x16x32_bf16 v[116:119], v[186:189], v[202:205], v[116:119]
	v_mfma_f32_16x16x32_bf16 v[112:115], v[194:197], v[202:205], v[112:115]
	v_mfma_f32_16x16x32_bf16 v[100:103], v[186:189], v[210:213], v[100:103]
	v_mfma_f32_16x16x32_bf16 v[96:99], v[194:197], v[210:213], v[96:99]
	v_mfma_f32_16x16x32_bf16 v[84:87], v[186:189], v[218:221], v[84:87]
	v_mfma_f32_16x16x32_bf16 v[80:83], v[194:197], v[218:221], v[80:83]
	v_mfma_f32_16x16x32_bf16 v[68:71], v[186:189], v[226:229], v[68:71]
	v_mfma_f32_16x16x32_bf16 v[64:67], v[194:197], v[226:229], v[64:67]
	v_mfma_f32_16x16x32_bf16 v[116:119], v[190:193], v[206:209], v[116:119]
	v_mfma_f32_16x16x32_bf16 v[112:115], v[198:201], v[206:209], v[112:115]
	v_mfma_f32_16x16x32_bf16 v[100:103], v[190:193], v[214:217], v[100:103]
	v_mfma_f32_16x16x32_bf16 v[96:99], v[198:201], v[214:217], v[96:99]
	v_mfma_f32_16x16x32_bf16 v[84:87], v[190:193], v[222:225], v[84:87]
	v_mfma_f32_16x16x32_bf16 v[80:83], v[198:201], v[222:225], v[80:83]
	v_mfma_f32_16x16x32_bf16 v[68:71], v[190:193], v[230:233], v[68:71]
	v_mfma_f32_16x16x32_bf16 v[64:67], v[198:201], v[230:233], v[64:67]
	s_setprio 0
	s_barrier
	s_add_u32 s88, s48, 0x80
	s_addc_u32 s89, s49, 0
	s_add_u32 s90, s50, 0x80
	s_addc_u32 s91, s51, 0
	s_mov_b32 m0, s54
	s_add_u32 s76, s48, 0x40000
	ds_read_b128 v[202:205], v159 offset:16384
	ds_read_b128 v[206:209], v159 offset:17408
	ds_read_b128 v[210:213], v159 offset:18432
	ds_read_b128 v[214:217], v159 offset:19456
	ds_read_b128 v[218:221], v159 offset:20480
	ds_read_b128 v[222:225], v159 offset:21504
	ds_read_b128 v[226:229], v159 offset:22528
	ds_read_b128 v[230:233], v159 offset:23552
	global_load_lds_dwordx4 v138, s[48:49]
	s_mov_b32 m0, s55
	s_addc_u32 s77, s49, 0
	global_load_lds_dwordx4 v142, s[48:49]
	s_mov_b32 m0, s56
	s_nop 0
	global_load_lds_dwordx4 v138, s[76:77]
	s_mov_b32 m0, s57
	s_nop 0
	global_load_lds_dwordx4 v142, s[76:77]
	s_mov_b32 m0, s53
	s_nop 0
	global_load_lds_dwordx4 v136, s[50:51]
	s_mov_b32 m0, s58
	s_nop 0
	global_load_lds_dwordx4 v140, s[50:51]
	s_waitcnt vmcnt(8)
	s_waitcnt lgkmcnt(0)
	s_barrier
	s_setprio 1
	s_waitcnt lgkmcnt(0)
	v_mfma_f32_16x16x32_bf16 v[60:63], v[128:131], v[202:205], v[60:63]
	v_mfma_f32_16x16x32_bf16 v[56:59], v[152:155], v[202:205], v[56:59]
	v_mfma_f32_16x16x32_bf16 v[44:47], v[128:131], v[210:213], v[44:47]
	v_mfma_f32_16x16x32_bf16 v[40:43], v[152:155], v[210:213], v[40:43]
	v_mfma_f32_16x16x32_bf16 v[28:31], v[128:131], v[218:221], v[28:31]
	v_mfma_f32_16x16x32_bf16 v[24:27], v[152:155], v[218:221], v[24:27]
	v_mfma_f32_16x16x32_bf16 v[12:15], v[128:131], v[226:229], v[12:15]
	v_mfma_f32_16x16x32_bf16 v[8:11], v[152:155], v[226:229], v[8:11]
	v_mfma_f32_16x16x32_bf16 v[60:63], v[132:135], v[206:209], v[60:63]
	v_mfma_f32_16x16x32_bf16 v[56:59], v[180:183], v[206:209], v[56:59]
	v_mfma_f32_16x16x32_bf16 v[44:47], v[132:135], v[214:217], v[44:47]
	v_mfma_f32_16x16x32_bf16 v[40:43], v[180:183], v[214:217], v[40:43]
	v_mfma_f32_16x16x32_bf16 v[28:31], v[132:135], v[222:225], v[28:31]
	v_mfma_f32_16x16x32_bf16 v[24:27], v[180:183], v[222:225], v[24:27]
	v_mfma_f32_16x16x32_bf16 v[12:15], v[132:135], v[230:233], v[12:15]
	v_mfma_f32_16x16x32_bf16 v[8:11], v[180:183], v[230:233], v[8:11]
	s_setprio 0
	s_setprio 1
	v_mfma_f32_16x16x32_bf16 v[52:55], v[186:189], v[202:205], v[52:55]
	v_mfma_f32_16x16x32_bf16 v[48:51], v[194:197], v[202:205], v[48:51]
	v_mfma_f32_16x16x32_bf16 v[36:39], v[186:189], v[210:213], v[36:39]
	v_mfma_f32_16x16x32_bf16 v[32:35], v[194:197], v[210:213], v[32:35]
	v_mfma_f32_16x16x32_bf16 v[20:23], v[186:189], v[218:221], v[20:23]
	v_mfma_f32_16x16x32_bf16 v[16:19], v[194:197], v[218:221], v[16:19]
	v_mfma_f32_16x16x32_bf16 v[4:7], v[186:189], v[226:229], v[4:7]
	v_mfma_f32_16x16x32_bf16 v[0:3], v[194:197], v[226:229], v[0:3]
	v_mfma_f32_16x16x32_bf16 v[52:55], v[190:193], v[206:209], v[52:55]
	v_mfma_f32_16x16x32_bf16 v[48:51], v[198:201], v[206:209], v[48:51]
	v_mfma_f32_16x16x32_bf16 v[36:39], v[190:193], v[214:217], v[36:39]
	v_mfma_f32_16x16x32_bf16 v[32:35], v[198:201], v[214:217], v[32:35]
	v_mfma_f32_16x16x32_bf16 v[20:23], v[190:193], v[222:225], v[20:23]
	v_mfma_f32_16x16x32_bf16 v[16:19], v[198:201], v[222:225], v[16:19]
	v_mfma_f32_16x16x32_bf16 v[4:7], v[190:193], v[230:233], v[4:7]
	v_mfma_f32_16x16x32_bf16 v[0:3], v[198:201], v[230:233], v[0:3]
	s_setprio 0
	s_barrier
; #define PG8_STAGE(bufoff, gbase, voff) do { _Pragma("unroll") for (int _i = 0; _i < 2; ++_i) \
;         __builtin_amdgcn_global_load_lds((const unsigned*)((const char*)(gbase) + (voff)[_i]), (PG8_LAS unsigned*)(lds + (bufoff) + ldsw + _i * 8192), 16, 0, 0); } while (0)
; #define PG8_LDA(dst, b, h) do { _Pragma("unroll") for (int m = 0; m < 4; ++m) _Pragma("unroll") for (int k = 0; k < 2; ++k) dst[m][k] = *(const PG8_LAS bf16x8*)(lds + PG8_SA(b, h) + aoff + m * 2048 + k * 1024); } while (0)
; #define PG8_LDB(dst, b, h) do { _Pragma("unroll") for (int n = 0; n < 2; ++n) _Pragma("unroll") for (int k = 0; k < 2; ++k) dst[n][k] = *(const PG8_LAS bf16x8*)(lds + PG8_SB(b, h) + boff + n * 2048 + k * 1024); } while (0)
; #define PG8_MMA(ai, bj, At, Bt) do { __builtin_amdgcn_s_setprio(1); _Pragma("unroll") for (int m = 0; m < 4; ++m) _Pragma("unroll") for (int n = 0; n < 2; ++n) _Pragma("unroll") for (int k = 0; k < 2; ++k) \
;         acc[ai][bj][m][n] = __builtin_amdgcn_mfma_f32_16x16x32_bf16(Bt[n][k], At[m][k], acc[ai][bj][m][n], 0, 0, 0); __builtin_amdgcn_s_setprio(0); } while (0)
; #define PG8_WAIT_V(n) asm volatile("s_waitcnt vmcnt(" #n ")" ::: "memory")
; #define PG8_WAIT_L(n) asm volatile("s_waitcnt lgkmcnt(" #n ")" ::: "memory")
; #define PG8_BAR __builtin_amdgcn_s_barrier()
; #define PG8_SCHED __builtin_amdgcn_sched_barrier(0)
; template <class Epi, class Sched, bool ALIGN_EPI = false, bool SP2 = false>
; __device__ __forceinline__ void gemm_phase(PG8_LAS unsigned char* lds, const Gemm g, const Sched& S, const Epi& E) {
;     ...
;         for (int t = 0; t < nt; t += 2) {
;     ...
;             PG8_LDB(B0, 1, 0); PG8_LDB(B1, 1, 1); PG8_SCHED; PG8_LDA(At, 1, 0); PG8_STAGE(PG8_SA(0, 1), a2 + hstep, voffA);
;             PG8_WAIT_V(8); PG8_WAIT_L(0); PG8_BAR; PG8_MMA(0, 0, At, B0); PG8_MMA(0, 1, At, B1); PG8_BAR; PG8_SCHED;
;             PG8_LDA(At, 1, 1); PG8_STAGE(PG8_SB(1, 0), b3, voffB); PG8_STAGE(PG8_SB(1, 1), b3 + hstep, voffB); PG8_STAGE(PG8_SA(1, 0), a3, voffA);
;             PG8_WAIT_V(8); PG8_WAIT_L(0); PG8_BAR; PG8_MMA(1, 0, At, B0); PG8_MMA(1, 1, At, B1); PG8_BAR; PG8_SCHED;
	ds_read_b128 v[128:131], v169
	ds_read_b128 v[132:135], v170
	ds_read_b128 v[152:155], v171
	ds_read_b128 v[180:183], v172
	ds_read_b128 v[186:189], v173
	ds_read_b128 v[190:193], v174
	ds_read_b128 v[194:197], v175
	ds_read_b128 v[198:201], v176
	s_add_u32 s50, s50, 0x40000
	s_addc_u32 s51, s51, 0
	s_mov_b32 m0, s59
	ds_read_b128 v[202:205], v159 offset:32768
	ds_read_b128 v[206:209], v159 offset:33792
	ds_read_b128 v[210:213], v159 offset:34816
	ds_read_b128 v[214:217], v159 offset:35840
	ds_read_b128 v[218:221], v159 offset:36864
	ds_read_b128 v[222:225], v159 offset:37888
	ds_read_b128 v[226:229], v159 offset:38912
	ds_read_b128 v[230:233], v159 offset:39936
	global_load_lds_dwordx4 v136, s[50:51]
	s_mov_b32 m0, s60
	s_nop 0
	global_load_lds_dwordx4 v140, s[50:51]
	s_waitcnt vmcnt(8)
	s_waitcnt lgkmcnt(0)
	s_barrier
	s_setprio 1
	s_waitcnt lgkmcnt(0)
	v_mfma_f32_16x16x32_bf16 v[124:127], v[128:131], v[202:205], v[124:127]
	v_mfma_f32_16x16x32_bf16 v[120:123], v[152:155], v[202:205], v[120:123]
	v_mfma_f32_16x16x32_bf16 v[108:111], v[128:131], v[210:213], v[108:111]
	v_mfma_f32_16x16x32_bf16 v[104:107], v[152:155], v[210:213], v[104:107]
	v_mfma_f32_16x16x32_bf16 v[92:95], v[128:131], v[218:221], v[92:95]
	v_mfma_f32_16x16x32_bf16 v[88:91], v[152:155], v[218:221], v[88:91]
	v_mfma_f32_16x16x32_bf16 v[76:79], v[128:131], v[226:229], v[76:79]
	v_mfma_f32_16x16x32_bf16 v[72:75], v[152:155], v[226:229], v[72:75]
	v_mfma_f32_16x16x32_bf16 v[124:127], v[132:135], v[206:209], v[124:127]
	v_mfma_f32_16x16x32_bf16 v[120:123], v[180:183], v[206:209], v[120:123]
	v_mfma_f32_16x16x32_bf16 v[108:111], v[132:135], v[214:217], v[108:111]
	v_mfma_f32_16x16x32_bf16 v[104:107], v[180:183], v[214:217], v[104:107]
	v_mfma_f32_16x16x32_bf16 v[92:95], v[132:135], v[222:225], v[92:95]
	v_mfma_f32_16x16x32_bf16 v[88:91], v[180:183], v[222:225], v[88:91]
	v_mfma_f32_16x16x32_bf16 v[76:79], v[132:135], v[230:233], v[76:79]
	v_mfma_f32_16x16x32_bf16 v[72:75], v[180:183], v[230:233], v[72:75]
	s_setprio 0
	s_setprio 1
	v_mfma_f32_16x16x32_bf16 v[116:119], v[186:189], v[202:205], v[116:119]
	v_mfma_f32_16x16x32_bf16 v[112:115], v[194:197], v[202:205], v[112:115]
	v_mfma_f32_16x16x32_bf16 v[100:103], v[186:189], v[210:213], v[100:103]
	v_mfma_f32_16x16x32_bf16 v[96:99], v[194:197], v[210:213], v[96:99]
	v_mfma_f32_16x16x32_bf16 v[84:87], v[186:189], v[218:221], v[84:87]
	v_mfma_f32_16x16x32_bf16 v[80:83], v[194:197], v[218:221], v[80:83]
	v_mfma_f32_16x16x32_bf16 v[68:71], v[186:189], v[226:229], v[68:71]
	v_mfma_f32_16x16x32_bf16 v[64:67], v[194:197], v[226:229], v[64:67]
	v_mfma_f32_16x16x32_bf16 v[116:119], v[190:193], v[206:209], v[116:119]
	v_mfma_f32_16x16x32_bf16 v[112:115], v[198:201], v[206:209], v[112:115]
	v_mfma_f32_16x16x32_bf16 v[100:103], v[190:193], v[214:217], v[100:103]
	v_mfma_f32_16x16x32_bf16 v[96:99], v[198:201], v[214:217], v[96:99]
	v_mfma_f32_16x16x32_bf16 v[84:87], v[190:193], v[222:225], v[84:87]
	v_mfma_f32_16x16x32_bf16 v[80:83], v[198:201], v[222:225], v[80:83]
	v_mfma_f32_16x16x32_bf16 v[68:71], v[190:193], v[230:233], v[68:71]
	v_mfma_f32_16x16x32_bf16 v[64:67], v[198:201], v[230:233], v[64:67]
	s_setprio 0
	s_barrier
	s_mov_b32 m0, s62
	s_add_u32 s48, s48, 0x40080
	ds_read_b128 v[202:205], v159 offset:49152
	ds_read_b128 v[206:209], v159 offset:50176
	ds_read_b128 v[210:213], v159 offset:51200
	ds_read_b128 v[214:217], v159 offset:52224
	ds_read_b128 v[218:221], v159 offset:53248
	ds_read_b128 v[222:225], v159 offset:54272
	ds_read_b128 v[226:229], v159 offset:55296
	ds_read_b128 v[230:233], v159 offset:56320
	global_load_lds_dwordx4 v138, s[88:89]
	s_mov_b32 m0, s63
	s_addc_u32 s49, s49, 0
	global_load_lds_dwordx4 v142, s[88:89]
	s_mov_b32 m0, s66
	s_nop 0
	global_load_lds_dwordx4 v138, s[48:49]
	s_mov_b32 m0, s67
	s_nop 0
	global_load_lds_dwordx4 v142, s[48:49]
	s_mov_b32 m0, s64
	s_nop 0
	global_load_lds_dwordx4 v136, s[90:91]
	s_mov_b32 m0, s65
	s_nop 0
	global_load_lds_dwordx4 v140, s[90:91]
	s_waitcnt vmcnt(8)
	s_waitcnt lgkmcnt(0)
	s_barrier
	s_setprio 1
	s_waitcnt lgkmcnt(0)
	v_mfma_f32_16x16x32_bf16 v[60:63], v[128:131], v[202:205], v[60:63]
	v_mfma_f32_16x16x32_bf16 v[56:59], v[152:155], v[202:205], v[56:59]
	v_mfma_f32_16x16x32_bf16 v[44:47], v[128:131], v[210:213], v[44:47]
	v_mfma_f32_16x16x32_bf16 v[40:43], v[152:155], v[210:213], v[40:43]
	v_mfma_f32_16x16x32_bf16 v[28:31], v[128:131], v[218:221], v[28:31]
	v_mfma_f32_16x16x32_bf16 v[24:27], v[152:155], v[218:221], v[24:27]
	v_mfma_f32_16x16x32_bf16 v[12:15], v[128:131], v[226:229], v[12:15]
	v_mfma_f32_16x16x32_bf16 v[8:11], v[152:155], v[226:229], v[8:11]
	v_mfma_f32_16x16x32_bf16 v[60:63], v[132:135], v[206:209], v[60:63]
	v_mfma_f32_16x16x32_bf16 v[56:59], v[180:183], v[206:209], v[56:59]
	v_mfma_f32_16x16x32_bf16 v[44:47], v[132:135], v[214:217], v[44:47]
	v_mfma_f32_16x16x32_bf16 v[40:43], v[180:183], v[214:217], v[40:43]
	v_mfma_f32_16x16x32_bf16 v[28:31], v[132:135], v[222:225], v[28:31]
	v_mfma_f32_16x16x32_bf16 v[24:27], v[180:183], v[222:225], v[24:27]
	v_mfma_f32_16x16x32_bf16 v[12:15], v[132:135], v[230:233], v[12:15]
	v_mfma_f32_16x16x32_bf16 v[8:11], v[180:183], v[230:233], v[8:11]
	s_setprio 0
	s_setprio 1
	v_mfma_f32_16x16x32_bf16 v[52:55], v[186:189], v[202:205], v[52:55]
	v_mfma_f32_16x16x32_bf16 v[48:51], v[194:197], v[202:205], v[48:51]
	v_mfma_f32_16x16x32_bf16 v[36:39], v[186:189], v[210:213], v[36:39]
	v_mfma_f32_16x16x32_bf16 v[32:35], v[194:197], v[210:213], v[32:35]
	v_mfma_f32_16x16x32_bf16 v[20:23], v[186:189], v[218:221], v[20:23]
	v_mfma_f32_16x16x32_bf16 v[16:19], v[194:197], v[218:221], v[16:19]
	v_mfma_f32_16x16x32_bf16 v[4:7], v[186:189], v[226:229], v[4:7]
	v_mfma_f32_16x16x32_bf16 v[0:3], v[194:197], v[226:229], v[0:3]
	v_mfma_f32_16x16x32_bf16 v[52:55], v[190:193], v[206:209], v[52:55]
	v_mfma_f32_16x16x32_bf16 v[48:51], v[198:201], v[206:209], v[48:51]
	v_mfma_f32_16x16x32_bf16 v[36:39], v[190:193], v[214:217], v[36:39]
	v_mfma_f32_16x16x32_bf16 v[32:35], v[198:201], v[214:217], v[32:35]
	v_mfma_f32_16x16x32_bf16 v[20:23], v[190:193], v[222:225], v[20:23]
	v_mfma_f32_16x16x32_bf16 v[16:19], v[198:201], v[222:225], v[16:19]
	v_mfma_f32_16x16x32_bf16 v[4:7], v[190:193], v[230:233], v[4:7]
	v_mfma_f32_16x16x32_bf16 v[0:3], v[198:201], v[230:233], v[0:3]
	s_setprio 0
	s_barrier
	s_add_i32 s75, s75, 2
	s_add_u32 s43, s43, 0x100
	s_addc_u32 s74, s74, 0
	s_add_u32 s12, s12, 0x100
	s_addc_u32 s13, s13, 0
	s_cmp_gt_u32 s75, 13
	s_cbranch_scc0 .LBB0_1744
	s_and_b64 vcc, exec, s[30:31]
	s_cbranch_vccz .LBB0_1747
	s_barrier
